# GEMM K-loops: first iteration peeled with zero MFMA source, accumulator zero-fill removed (7 instances)
# speedup vs baseline: 1.0634x; 1.0079x over previous
.LBB0_252:
	s_add_u32 s0, s0, 0x80
	s_addc_u32 s1, s1, 0
	s_add_u32 s47, s4, 0x100
	s_addc_u32 s48, s5, 0
	s_mov_b32 s4, 0
	s_waitcnt lgkmcnt(0)
	s_waitcnt vmcnt(0)
	s_add_i32 s49, s4, 2
	s_add_u32 s16, s0, 0x80
	s_addc_u32 s5, s1, 0
	s_add_i32 s65, 0, 0x10000
	v_add_u32_e32 v142, s65, v145
	ds_read_b128 v[148:151], v142
	ds_read_b128 v[152:155], v142 offset:1024
	ds_read_b128 v[156:159], v142 offset:2048
	ds_read_b128 v[160:163], v142 offset:3072
	s_cmp_eq_u32 s41, s4
	s_cselect_b32 s4, s10, s16
	s_cselect_b32 s5, s11, s5
	s_cselect_b32 s17, s13, s48
	s_cselect_b32 s16, s12, s47
	v_lshl_add_u64 v[142:143], s[0:1], 0, v[138:139]
	s_add_i32 m0, s26, 0xc000
	ds_read_b128 v[164:167], v146
	ds_read_b128 v[168:171], v146 offset:1024
	ds_read_b128 v[172:175], v146 offset:2048
	ds_read_b128 v[176:179], v146 offset:3072
	ds_read_b128 v[180:183], v146 offset:4096
	ds_read_b128 v[204:207], v146 offset:5120
	ds_read_b128 v[208:211], v146 offset:6144
	ds_read_b128 v[212:215], v146 offset:7168
	global_load_lds_dwordx4 v[142:143], off
	v_lshl_add_u64 v[142:143], s[0:1], 0, v[140:141]
	s_add_i32 m0, s26, 0xe000
	s_nop 0
	global_load_lds_dwordx4 v[142:143], off
	s_waitcnt lgkmcnt(8)
	s_barrier
	s_waitcnt lgkmcnt(0)
	s_setprio 1
	s_waitcnt lgkmcnt(0)
	v_mfma_f32_16x16x32_bf16 v[126:129], v[148:151], v[164:167], 0
	v_mfma_f32_16x16x32_bf16 v[122:125], v[156:159], v[164:167], 0
	v_mfma_f32_16x16x32_bf16 v[110:113], v[148:151], v[172:175], 0
	v_mfma_f32_16x16x32_bf16 v[106:109], v[156:159], v[172:175], 0
	v_mfma_f32_16x16x32_bf16 v[94:97], v[148:151], v[180:183], 0
	v_mfma_f32_16x16x32_bf16 v[90:93], v[156:159], v[180:183], 0
	v_mfma_f32_16x16x32_bf16 v[78:81], v[148:151], v[208:211], 0
	v_mfma_f32_16x16x32_bf16 v[74:77], v[156:159], v[208:211], 0
	v_mfma_f32_16x16x32_bf16 v[126:129], v[152:155], v[168:171], v[126:129]
	v_mfma_f32_16x16x32_bf16 v[122:125], v[160:163], v[168:171], v[122:125]
	v_mfma_f32_16x16x32_bf16 v[110:113], v[152:155], v[176:179], v[110:113]
	v_mfma_f32_16x16x32_bf16 v[106:109], v[160:163], v[176:179], v[106:109]
	v_mfma_f32_16x16x32_bf16 v[94:97], v[152:155], v[204:207], v[94:97]
	v_mfma_f32_16x16x32_bf16 v[90:93], v[160:163], v[204:207], v[90:93]
	v_mfma_f32_16x16x32_bf16 v[78:81], v[152:155], v[212:215], v[78:81]
	v_mfma_f32_16x16x32_bf16 v[74:77], v[160:163], v[212:215], v[74:77]
	s_setprio 0
	s_barrier
	s_add_i32 s66, 0, 0x14000
	v_add_u32_e32 v142, s66, v145
	s_add_i32 s65, s65, s24
	ds_read_b128 v[216:219], v142
	ds_read_b128 v[220:223], v142 offset:1024
	ds_read_b128 v[224:227], v142 offset:2048
	ds_read_b128 v[228:231], v142 offset:3072
	v_lshl_add_u64 v[142:143], s[16:17], 0, v[132:133]
	s_mov_b32 m0, s65
	v_lshl_add_u64 v[184:185], s[16:17], 0, v[136:137]
	global_load_lds_dwordx4 v[142:143], off
	s_add_i32 m0, s65, 0x2000
	s_nop 0
	global_load_lds_dwordx4 v[184:185], off
	s_barrier
	s_waitcnt lgkmcnt(0)
	s_setprio 1
	s_waitcnt lgkmcnt(0)
	v_mfma_f32_16x16x32_bf16 v[114:117], v[216:219], v[164:167], 0
	v_mfma_f32_16x16x32_bf16 v[118:121], v[224:227], v[164:167], 0
	v_mfma_f32_16x16x32_bf16 v[98:101], v[216:219], v[172:175], 0
	v_mfma_f32_16x16x32_bf16 v[102:105], v[224:227], v[172:175], 0
	v_mfma_f32_16x16x32_bf16 v[82:85], v[216:219], v[180:183], 0
	v_mfma_f32_16x16x32_bf16 v[86:89], v[224:227], v[180:183], 0
	v_mfma_f32_16x16x32_bf16 v[66:69], v[216:219], v[208:211], 0
	v_mfma_f32_16x16x32_bf16 v[70:73], v[224:227], v[208:211], 0
	v_mfma_f32_16x16x32_bf16 v[114:117], v[220:223], v[168:171], v[114:117]
	v_mfma_f32_16x16x32_bf16 v[118:121], v[228:231], v[168:171], v[118:121]
	v_mfma_f32_16x16x32_bf16 v[98:101], v[220:223], v[176:179], v[98:101]
	v_mfma_f32_16x16x32_bf16 v[102:105], v[228:231], v[176:179], v[102:105]
	v_mfma_f32_16x16x32_bf16 v[82:85], v[220:223], v[204:207], v[82:85]
	v_mfma_f32_16x16x32_bf16 v[86:89], v[228:231], v[204:207], v[86:89]
	v_mfma_f32_16x16x32_bf16 v[66:69], v[220:223], v[212:215], v[66:69]
	v_mfma_f32_16x16x32_bf16 v[70:73], v[228:231], v[212:215], v[70:73]
	s_setprio 0
	s_mov_b32 m0, s26
	v_lshl_add_u64 v[232:233], s[4:5], 0, v[130:131]
	s_barrier
	ds_read_b128 v[164:167], v146 offset:16384
	ds_read_b128 v[168:171], v146 offset:17408
	ds_read_b128 v[172:175], v146 offset:18432
	ds_read_b128 v[176:179], v146 offset:19456
	ds_read_b128 v[180:183], v146 offset:20480
	ds_read_b128 v[204:207], v146 offset:21504
	ds_read_b128 v[208:211], v146 offset:22528
	ds_read_b128 v[212:215], v146 offset:23552
	global_load_lds_dwordx4 v[232:233], off
	v_lshl_add_u64 v[234:235], s[4:5], 0, v[134:135]
	s_mov_b32 m0, s27
	s_nop 0
	global_load_lds_dwordx4 v[234:235], off
	s_barrier
	s_waitcnt lgkmcnt(0)
	s_setprio 1
	s_waitcnt lgkmcnt(0)
	v_mfma_f32_16x16x32_bf16 v[62:65], v[148:151], v[164:167], 0
	v_mfma_f32_16x16x32_bf16 v[58:61], v[156:159], v[164:167], 0
	v_mfma_f32_16x16x32_bf16 v[46:49], v[148:151], v[172:175], 0
	v_mfma_f32_16x16x32_bf16 v[42:45], v[156:159], v[172:175], 0
	v_mfma_f32_16x16x32_bf16 v[30:33], v[148:151], v[180:183], 0
	v_mfma_f32_16x16x32_bf16 v[26:29], v[156:159], v[180:183], 0
	v_mfma_f32_16x16x32_bf16 v[14:17], v[148:151], v[208:211], 0
	v_mfma_f32_16x16x32_bf16 v[10:13], v[156:159], v[208:211], 0
	v_mfma_f32_16x16x32_bf16 v[62:65], v[152:155], v[168:171], v[62:65]
	v_mfma_f32_16x16x32_bf16 v[58:61], v[160:163], v[168:171], v[58:61]
	v_mfma_f32_16x16x32_bf16 v[46:49], v[152:155], v[176:179], v[46:49]
	v_mfma_f32_16x16x32_bf16 v[42:45], v[160:163], v[176:179], v[42:45]
	v_mfma_f32_16x16x32_bf16 v[30:33], v[152:155], v[204:207], v[30:33]
	v_mfma_f32_16x16x32_bf16 v[26:29], v[160:163], v[204:207], v[26:29]
	v_mfma_f32_16x16x32_bf16 v[14:17], v[152:155], v[212:215], v[14:17]
	v_mfma_f32_16x16x32_bf16 v[10:13], v[160:163], v[212:215], v[10:13]
	s_setprio 0
	s_barrier
	s_add_u32 s16, s16, s92
	s_addc_u32 s17, s17, 0
	s_add_i32 s65, s66, s24
	v_lshl_add_u64 v[236:237], s[16:17], 0, v[132:133]
	s_mov_b32 m0, s65
	v_lshl_add_u64 v[238:239], s[16:17], 0, v[136:137]
	global_load_lds_dwordx4 v[236:237], off
	s_add_i32 m0, s65, 0x2000
	s_nop 0
	global_load_lds_dwordx4 v[238:239], off
	s_waitcnt vmcnt(6)
	s_barrier
	s_setprio 1
	v_mfma_f32_16x16x32_bf16 v[50:53], v[216:219], v[164:167], 0
	v_mfma_f32_16x16x32_bf16 v[54:57], v[224:227], v[164:167], 0
	v_mfma_f32_16x16x32_bf16 v[34:37], v[216:219], v[172:175], 0
	v_mfma_f32_16x16x32_bf16 v[38:41], v[224:227], v[172:175], 0
	v_mfma_f32_16x16x32_bf16 v[18:21], v[216:219], v[180:183], 0
	v_mfma_f32_16x16x32_bf16 v[22:25], v[224:227], v[180:183], 0
	v_mfma_f32_16x16x32_bf16 v[6:9], v[216:219], v[208:211], 0
	v_mfma_f32_16x16x32_bf16 v[2:5], v[224:227], v[208:211], 0
	v_mfma_f32_16x16x32_bf16 v[50:53], v[220:223], v[168:171], v[50:53]
	v_mfma_f32_16x16x32_bf16 v[54:57], v[228:231], v[168:171], v[54:57]
	v_mfma_f32_16x16x32_bf16 v[34:37], v[220:223], v[176:179], v[34:37]
	v_mfma_f32_16x16x32_bf16 v[38:41], v[228:231], v[176:179], v[38:41]
	v_mfma_f32_16x16x32_bf16 v[18:21], v[220:223], v[204:207], v[18:21]
	v_mfma_f32_16x16x32_bf16 v[22:25], v[228:231], v[204:207], v[22:25]
	v_mfma_f32_16x16x32_bf16 v[6:9], v[220:223], v[212:215], v[6:9]
	v_mfma_f32_16x16x32_bf16 v[2:5], v[228:231], v[212:215], v[2:5]
	s_setprio 0
	s_add_i32 s16, 0, 0x18000
	v_add_u32_e32 v147, s16, v145
	s_barrier
	ds_read_b128 v[148:151], v147
	ds_read_b128 v[152:155], v147 offset:1024
	ds_read_b128 v[156:159], v147 offset:2048
	ds_read_b128 v[160:163], v147 offset:3072
	s_add_u32 s4, s4, s92
	s_addc_u32 s5, s5, 0
	s_mov_b32 m0, s28
	v_lshl_add_u64 v[216:217], s[4:5], 0, v[130:131]
	ds_read_b128 v[164:167], v146 offset:32768
	ds_read_b128 v[168:171], v146 offset:33792
	ds_read_b128 v[172:175], v146 offset:34816
	ds_read_b128 v[176:179], v146 offset:35840
	ds_read_b128 v[180:183], v146 offset:36864
	ds_read_b128 v[204:207], v146 offset:37888
	ds_read_b128 v[208:211], v146 offset:38912
	ds_read_b128 v[212:215], v146 offset:39936
	global_load_lds_dwordx4 v[216:217], off
	v_lshl_add_u64 v[216:217], s[4:5], 0, v[134:135]
	s_mov_b32 m0, s29
	s_nop 0
	global_load_lds_dwordx4 v[216:217], off
	s_waitcnt lgkmcnt(8)
	s_barrier
	s_waitcnt lgkmcnt(0)
	s_setprio 1
	s_waitcnt lgkmcnt(0)
	v_mfma_f32_16x16x32_bf16 v[126:129], v[148:151], v[164:167], v[126:129]
	v_mfma_f32_16x16x32_bf16 v[122:125], v[156:159], v[164:167], v[122:125]
	v_mfma_f32_16x16x32_bf16 v[110:113], v[148:151], v[172:175], v[110:113]
	v_mfma_f32_16x16x32_bf16 v[106:109], v[156:159], v[172:175], v[106:109]
	v_mfma_f32_16x16x32_bf16 v[94:97], v[148:151], v[180:183], v[94:97]
	v_mfma_f32_16x16x32_bf16 v[90:93], v[156:159], v[180:183], v[90:93]
	v_mfma_f32_16x16x32_bf16 v[78:81], v[148:151], v[208:211], v[78:81]
	v_mfma_f32_16x16x32_bf16 v[74:77], v[156:159], v[208:211], v[74:77]
	v_mfma_f32_16x16x32_bf16 v[126:129], v[152:155], v[168:171], v[126:129]
	v_mfma_f32_16x16x32_bf16 v[122:125], v[160:163], v[168:171], v[122:125]
	v_mfma_f32_16x16x32_bf16 v[110:113], v[152:155], v[176:179], v[110:113]
	v_mfma_f32_16x16x32_bf16 v[106:109], v[160:163], v[176:179], v[106:109]
	v_mfma_f32_16x16x32_bf16 v[94:97], v[152:155], v[204:207], v[94:97]
	v_mfma_f32_16x16x32_bf16 v[90:93], v[160:163], v[204:207], v[90:93]
	v_mfma_f32_16x16x32_bf16 v[78:81], v[152:155], v[212:215], v[78:81]
	v_mfma_f32_16x16x32_bf16 v[74:77], v[160:163], v[212:215], v[74:77]
	s_setprio 0
	s_barrier
	s_add_i32 s4, 0, 0x1c000
	s_add_i32 s5, s16, s24
	v_add_u32_e32 v147, s4, v145
	v_lshl_add_u64 v[142:143], v[142:143], 0, s[6:7]
	s_mov_b32 m0, s5
	ds_read_b128 v[216:219], v147
	ds_read_b128 v[220:223], v147 offset:1024
	ds_read_b128 v[224:227], v147 offset:2048
	ds_read_b128 v[228:231], v147 offset:3072
	global_load_lds_dwordx4 v[142:143], off
	v_lshl_add_u64 v[142:143], v[184:185], 0, s[6:7]
	s_add_i32 m0, s5, 0x2000
	s_nop 0
	global_load_lds_dwordx4 v[142:143], off
	s_barrier
	s_waitcnt lgkmcnt(0)
	s_setprio 1
	s_waitcnt lgkmcnt(0)
	v_mfma_f32_16x16x32_bf16 v[114:117], v[216:219], v[164:167], v[114:117]
	v_mfma_f32_16x16x32_bf16 v[118:121], v[224:227], v[164:167], v[118:121]
	v_mfma_f32_16x16x32_bf16 v[98:101], v[216:219], v[172:175], v[98:101]
	v_mfma_f32_16x16x32_bf16 v[102:105], v[224:227], v[172:175], v[102:105]
	v_mfma_f32_16x16x32_bf16 v[82:85], v[216:219], v[180:183], v[82:85]
	v_mfma_f32_16x16x32_bf16 v[86:89], v[224:227], v[180:183], v[86:89]
	v_mfma_f32_16x16x32_bf16 v[66:69], v[216:219], v[208:211], v[66:69]
	v_mfma_f32_16x16x32_bf16 v[70:73], v[224:227], v[208:211], v[70:73]
	v_mfma_f32_16x16x32_bf16 v[114:117], v[220:223], v[168:171], v[114:117]
	v_mfma_f32_16x16x32_bf16 v[118:121], v[228:231], v[168:171], v[118:121]
	v_mfma_f32_16x16x32_bf16 v[98:101], v[220:223], v[176:179], v[98:101]
	v_mfma_f32_16x16x32_bf16 v[102:105], v[228:231], v[176:179], v[102:105]
	v_mfma_f32_16x16x32_bf16 v[82:85], v[220:223], v[204:207], v[82:85]
	v_mfma_f32_16x16x32_bf16 v[86:89], v[228:231], v[204:207], v[86:89]
	v_mfma_f32_16x16x32_bf16 v[66:69], v[220:223], v[212:215], v[66:69]
	v_mfma_f32_16x16x32_bf16 v[70:73], v[228:231], v[212:215], v[70:73]
	s_setprio 0
	s_mov_b32 m0, s35
	v_lshl_add_u64 v[142:143], v[232:233], 0, s[6:7]
	s_barrier
	ds_read_b128 v[164:167], v146 offset:49152
	ds_read_b128 v[168:171], v146 offset:50176
	ds_read_b128 v[172:175], v146 offset:51200
	ds_read_b128 v[176:179], v146 offset:52224
	ds_read_b128 v[180:183], v146 offset:53248
	ds_read_b128 v[204:207], v146 offset:54272
	ds_read_b128 v[208:211], v146 offset:55296
	ds_read_b128 v[212:215], v146 offset:56320
	global_load_lds_dwordx4 v[142:143], off
	v_lshl_add_u64 v[142:143], v[234:235], 0, s[6:7]
	s_mov_b32 m0, s40
	s_nop 0
	global_load_lds_dwordx4 v[142:143], off
	s_barrier
	s_waitcnt lgkmcnt(0)
	s_setprio 1
	s_waitcnt lgkmcnt(0)
	v_mfma_f32_16x16x32_bf16 v[62:65], v[148:151], v[164:167], v[62:65]
	v_mfma_f32_16x16x32_bf16 v[58:61], v[156:159], v[164:167], v[58:61]
	v_mfma_f32_16x16x32_bf16 v[46:49], v[148:151], v[172:175], v[46:49]
	v_mfma_f32_16x16x32_bf16 v[42:45], v[156:159], v[172:175], v[42:45]
	v_mfma_f32_16x16x32_bf16 v[30:33], v[148:151], v[180:183], v[30:33]
	v_mfma_f32_16x16x32_bf16 v[26:29], v[156:159], v[180:183], v[26:29]
	v_mfma_f32_16x16x32_bf16 v[14:17], v[148:151], v[208:211], v[14:17]
	v_mfma_f32_16x16x32_bf16 v[10:13], v[156:159], v[208:211], v[10:13]
	v_mfma_f32_16x16x32_bf16 v[62:65], v[152:155], v[168:171], v[62:65]
	v_mfma_f32_16x16x32_bf16 v[58:61], v[160:163], v[168:171], v[58:61]
	v_mfma_f32_16x16x32_bf16 v[46:49], v[152:155], v[176:179], v[46:49]
	v_mfma_f32_16x16x32_bf16 v[42:45], v[160:163], v[176:179], v[42:45]
	v_mfma_f32_16x16x32_bf16 v[30:33], v[152:155], v[204:207], v[30:33]
	v_mfma_f32_16x16x32_bf16 v[26:29], v[160:163], v[204:207], v[26:29]
	v_mfma_f32_16x16x32_bf16 v[14:17], v[152:155], v[212:215], v[14:17]
	v_mfma_f32_16x16x32_bf16 v[10:13], v[160:163], v[212:215], v[10:13]
	s_setprio 0
	s_barrier
	s_add_i32 s4, s4, s24
	v_lshl_add_u64 v[142:143], v[236:237], 0, s[6:7]
	s_mov_b32 m0, s4
	s_nop 0
	global_load_lds_dwordx4 v[142:143], off
	v_lshl_add_u64 v[142:143], v[238:239], 0, s[6:7]
	s_add_i32 m0, s4, 0x2000
	s_nop 0
	global_load_lds_dwordx4 v[142:143], off
	s_waitcnt vmcnt(6)
	s_barrier
	s_setprio 1
	v_mfma_f32_16x16x32_bf16 v[50:53], v[216:219], v[164:167], v[50:53]
	v_mfma_f32_16x16x32_bf16 v[54:57], v[224:227], v[164:167], v[54:57]
	v_mfma_f32_16x16x32_bf16 v[34:37], v[216:219], v[172:175], v[34:37]
	v_mfma_f32_16x16x32_bf16 v[38:41], v[224:227], v[172:175], v[38:41]
	v_mfma_f32_16x16x32_bf16 v[18:21], v[216:219], v[180:183], v[18:21]
	v_mfma_f32_16x16x32_bf16 v[22:25], v[224:227], v[180:183], v[22:25]
	v_mfma_f32_16x16x32_bf16 v[6:9], v[216:219], v[208:211], v[6:9]
	v_mfma_f32_16x16x32_bf16 v[2:5], v[224:227], v[208:211], v[2:5]
	v_mfma_f32_16x16x32_bf16 v[50:53], v[220:223], v[168:171], v[50:53]
	v_mfma_f32_16x16x32_bf16 v[54:57], v[228:231], v[168:171], v[54:57]
	v_mfma_f32_16x16x32_bf16 v[34:37], v[220:223], v[176:179], v[34:37]
	v_mfma_f32_16x16x32_bf16 v[38:41], v[228:231], v[176:179], v[38:41]
	v_mfma_f32_16x16x32_bf16 v[18:21], v[220:223], v[204:207], v[18:21]
	v_mfma_f32_16x16x32_bf16 v[22:25], v[228:231], v[204:207], v[22:25]
	v_mfma_f32_16x16x32_bf16 v[6:9], v[220:223], v[212:215], v[6:9]
	v_mfma_f32_16x16x32_bf16 v[2:5], v[228:231], v[212:215], v[2:5]
	s_setprio 0
	s_add_u32 s0, s0, 0x100
	s_addc_u32 s1, s1, 0
	s_add_u32 s47, s47, 0x100
	s_addc_u32 s48, s48, 0
	s_cmp_ge_u32 s49, s30
	s_mov_b32 s4, s49
	s_barrier
	s_cbranch_scc1 .Lkexit_253

.Lkexit_253:
	s_lshl_b32 s0, s45, 8
	v_mov_b32_e32 v142, v144
	v_mov_b32_e32 v143, v1
	s_add_i32 s0, s0, s31
	v_readlane_b32 s4, v242, 7
	v_add_u32_e32 v147, s0, v142
	s_lshl_b32 s0, s46, 8
	s_or_b32 s0, s0, s34
	v_add_u32_e32 v154, s50, v147
	v_lshl_add_u32 v152, v143, 3, s0
	v_ashrrev_i32_e32 v155, 31, v154
	v_add_u32_e32 v142, 0xffff0000, v154
	v_mov_b32_e32 v143, v0
	v_readlane_b32 s0, v243, 48
	v_ashrrev_i32_e32 v153, 31, v152
	v_lshlrev_b64 v[156:157], 12, v[142:143]
	v_lshlrev_b64 v[142:143], 11, v[154:155]
	v_readlane_b32 s1, v243, 49
	s_mov_b32 s16, 0x10000
	v_readlane_b32 s5, v242, 8
	v_lshl_add_u64 v[148:149], s[0:1], 0, v[142:143]
	v_lshlrev_b64 v[142:143], 1, v[152:153]
	v_lshl_add_u64 v[158:159], v[148:149], 0, v[142:143]
	v_lshlrev_b32_e32 v160, 11, v144
	v_lshl_add_u32 v160, v152, 1, v160
	s_lshl_b32 s65, s45, 8
	s_add_i32 s65, s65, s31
	s_add_i32 s48, s65, s50
	s_lshl_b32 s48, s48, 11
	s_add_u32 s48, s0, s48
	s_addc_u32 s49, s1, 0
	global_load_dwordx4 v[148:151], v160, s[48:49]
	global_load_dwordx4 v[162:165], v160, s[48:49] offset:256
	s_add_i32 s48, s65, s83
	s_lshl_b32 s48, s48, 11
	s_add_u32 s48, s0, s48
	s_addc_u32 s49, s1, 0
	global_load_dwordx4 v[166:169], v160, s[48:49]
	global_load_dwordx4 v[170:173], v160, s[48:49] offset:256
	s_add_i32 s48, s65, s91
	s_lshl_b32 s48, s48, 11
	s_add_u32 s48, s0, s48
	s_addc_u32 s49, s1, 0
	global_load_dwordx4 v[174:177], v160, s[48:49]
	global_load_dwordx4 v[178:181], v160, s[48:49] offset:256
	s_add_i32 s48, s65, s51
	s_lshl_b32 s48, s48, 11
	s_add_u32 s48, s0, s48
	s_addc_u32 s49, s1, 0
	global_load_dwordx4 v[182:185], v160, s[48:49]
	global_load_dwordx4 v[204:207], v160, s[48:49] offset:256
	s_add_i32 s48, s65, s88
	s_lshl_b32 s48, s48, 11
	s_add_u32 s48, s0, s48
	s_addc_u32 s49, s1, 0
	global_load_dwordx4 v[208:211], v160, s[48:49]
	global_load_dwordx4 v[212:215], v160, s[48:49] offset:256
	s_add_i32 s48, s65, s60
	s_lshl_b32 s48, s48, 11
	s_add_u32 s48, s0, s48
	s_addc_u32 s49, s1, 0
	global_load_dwordx4 v[216:219], v160, s[48:49]
	global_load_dwordx4 v[220:223], v160, s[48:49] offset:256
	s_add_i32 s48, s65, s61
	s_lshl_b32 s48, s48, 11
	s_add_u32 s48, s0, s48
	s_addc_u32 s49, s1, 0
	global_load_dwordx4 v[224:227], v160, s[48:49]
	global_load_dwordx4 v[228:231], v160, s[48:49] offset:256
	s_add_i32 s48, s65, s62
	s_lshl_b32 s48, s48, 11
	s_add_u32 s48, s0, s48
	s_addc_u32 s49, s1, 0
	global_load_dwordx4 v[232:235], v160, s[48:49]
	global_load_dwordx4 v[236:239], v160, s[48:49] offset:256
	v_cmp_gt_i32_e32 vcc, s16, v154
	s_mov_b32 s45, s44
	s_mov_b32 s46, s43
	s_waitcnt vmcnt(15)
	v_lshlrev_b32_e32 v160, 16, v148
	v_and_b32_e32 v161, 0xffff0000, v148
	v_lshlrev_b32_e32 v148, 16, v149
	v_and_b32_e32 v149, 0xffff0000, v149
	v_pk_add_f32 v[128:129], v[128:129], v[148:149]
	v_lshlrev_b32_e32 v148, 16, v150
	v_and_b32_e32 v149, 0xffff0000, v150
	v_pk_add_f32 v[148:149], v[122:123], v[148:149]
	v_lshlrev_b32_e32 v122, 16, v151
	v_and_b32_e32 v123, 0xffff0000, v151
	v_pk_add_f32 v[150:151], v[124:125], v[122:123]
	v_lshlrev_b64 v[122:123], 12, v[154:155]
	v_lshl_add_u64 v[122:123], s[74:75], 0, v[122:123]
	v_lshl_add_u64 v[124:125], s[4:5], 0, v[156:157]
	v_cndmask_b32_e32 v125, v125, v123, vcc
	v_cndmask_b32_e32 v124, v124, v122, vcc
	v_lshlrev_b64 v[122:123], 2, v[152:153]
	v_pk_add_f32 v[126:127], v[126:127], v[160:161]
	v_lshl_add_u64 v[152:153], v[124:125], 0, v[122:123]
	global_store_dwordx4 v[152:153], v[126:129], off nt
	global_store_dwordx4 v[152:153], v[148:151], off offset:16 nt
	s_waitcnt vmcnt(16)
	v_lshlrev_b32_e32 v128, 16, v165
	v_and_b32_e32 v129, 0xffff0000, v165
	v_pk_add_f32 v[120:121], v[120:121], v[128:129]
	v_lshlrev_b32_e32 v128, 16, v164
	v_and_b32_e32 v129, 0xffff0000, v164
	v_lshlrev_b32_e32 v126, 16, v163
	v_and_b32_e32 v127, 0xffff0000, v163
	v_pk_add_f32 v[116:117], v[116:117], v[126:127]
	v_lshlrev_b32_e32 v126, 16, v162
	v_and_b32_e32 v127, 0xffff0000, v162
	v_pk_add_f32 v[118:119], v[118:119], v[128:129]
	v_pk_add_f32 v[114:115], v[114:115], v[126:127]
	global_store_dwordx4 v[152:153], v[114:117], off offset:512 nt
	global_store_dwordx4 v[152:153], v[118:121], off offset:528 nt
	s_nop 0
	v_mov_b32_e32 v115, v0
	v_add_u32_e32 v118, s83, v147
	v_ashrrev_i32_e32 v119, 31, v118
	v_add_u32_e32 v114, 0xffff0000, v118
	v_lshlrev_b64 v[120:121], 12, v[114:115]
	v_lshlrev_b64 v[114:115], 11, v[118:119]
	v_lshl_add_u64 v[114:115], s[0:1], 0, v[114:115]
	v_lshl_add_u64 v[124:125], v[114:115], 0, v[142:143]
	v_cmp_gt_i32_e32 vcc, s16, v118
	s_waitcnt vmcnt(17)
	v_lshlrev_b32_e32 v126, 16, v166
	v_and_b32_e32 v127, 0xffff0000, v166
	v_lshlrev_b32_e32 v114, 16, v167
	v_and_b32_e32 v115, 0xffff0000, v167
	v_pk_add_f32 v[112:113], v[112:113], v[114:115]
	v_lshlrev_b32_e32 v114, 16, v168
	v_and_b32_e32 v115, 0xffff0000, v168
	v_pk_add_f32 v[106:107], v[106:107], v[114:115]
	v_lshlrev_b32_e32 v114, 16, v169
	v_and_b32_e32 v115, 0xffff0000, v169
	v_pk_add_f32 v[108:109], v[108:109], v[114:115]
	v_lshlrev_b64 v[114:115], 12, v[118:119]
	v_lshl_add_u64 v[114:115], s[74:75], 0, v[114:115]
	v_lshl_add_u64 v[116:117], s[4:5], 0, v[120:121]
	v_cndmask_b32_e32 v115, v117, v115, vcc
	v_cndmask_b32_e32 v114, v116, v114, vcc
	v_pk_add_f32 v[110:111], v[110:111], v[126:127]
	v_lshl_add_u64 v[114:115], v[114:115], 0, v[122:123]
	global_store_dwordx4 v[114:115], v[110:113], off nt
	global_store_dwordx4 v[114:115], v[106:109], off offset:16 nt
	s_waitcnt vmcnt(18)
	v_lshlrev_b32_e32 v110, 16, v173
	v_and_b32_e32 v111, 0xffff0000, v173
	v_pk_add_f32 v[104:105], v[104:105], v[110:111]
	v_lshlrev_b32_e32 v110, 16, v172
	v_and_b32_e32 v111, 0xffff0000, v172
	v_lshlrev_b32_e32 v108, 16, v171
	v_and_b32_e32 v109, 0xffff0000, v171
	v_pk_add_f32 v[100:101], v[100:101], v[108:109]
	v_lshlrev_b32_e32 v108, 16, v170
	v_and_b32_e32 v109, 0xffff0000, v170
	v_pk_add_f32 v[102:103], v[102:103], v[110:111]
	v_pk_add_f32 v[98:99], v[98:99], v[108:109]
	global_store_dwordx4 v[114:115], v[98:101], off offset:512 nt
	global_store_dwordx4 v[114:115], v[102:105], off offset:528 nt
	s_nop 0
	v_mov_b32_e32 v99, v0
	v_add_u32_e32 v102, s91, v147
	v_ashrrev_i32_e32 v103, 31, v102
	v_add_u32_e32 v98, 0xffff0000, v102
	v_lshlrev_b64 v[104:105], 12, v[98:99]
	v_lshlrev_b64 v[98:99], 11, v[102:103]
	v_lshl_add_u64 v[98:99], s[0:1], 0, v[98:99]
	v_lshl_add_u64 v[106:107], v[98:99], 0, v[142:143]
	v_cmp_gt_i32_e32 vcc, s16, v102
	s_waitcnt vmcnt(19)
	v_lshlrev_b32_e32 v108, 16, v174
	v_and_b32_e32 v109, 0xffff0000, v174
	v_lshlrev_b32_e32 v98, 16, v175
	v_and_b32_e32 v99, 0xffff0000, v175
	v_pk_add_f32 v[96:97], v[96:97], v[98:99]
	v_lshlrev_b32_e32 v98, 16, v176
	v_and_b32_e32 v99, 0xffff0000, v176
	v_pk_add_f32 v[90:91], v[90:91], v[98:99]
	v_lshlrev_b32_e32 v98, 16, v177
	v_and_b32_e32 v99, 0xffff0000, v177
	v_pk_add_f32 v[92:93], v[92:93], v[98:99]
	v_lshlrev_b64 v[98:99], 12, v[102:103]
	v_lshl_add_u64 v[98:99], s[74:75], 0, v[98:99]
	v_lshl_add_u64 v[100:101], s[4:5], 0, v[104:105]
	v_cndmask_b32_e32 v99, v101, v99, vcc
	v_cndmask_b32_e32 v98, v100, v98, vcc
	v_pk_add_f32 v[94:95], v[94:95], v[108:109]
	v_lshl_add_u64 v[98:99], v[98:99], 0, v[122:123]
	global_store_dwordx4 v[98:99], v[94:97], off nt
	global_store_dwordx4 v[98:99], v[90:93], off offset:16 nt
	s_waitcnt vmcnt(20)
	v_lshlrev_b32_e32 v94, 16, v181
	v_and_b32_e32 v95, 0xffff0000, v181
	v_pk_add_f32 v[88:89], v[88:89], v[94:95]
	v_lshlrev_b32_e32 v94, 16, v180
	v_and_b32_e32 v95, 0xffff0000, v180
	v_lshlrev_b32_e32 v92, 16, v179
	v_and_b32_e32 v93, 0xffff0000, v179
	v_pk_add_f32 v[84:85], v[84:85], v[92:93]
	v_lshlrev_b32_e32 v92, 16, v178
	v_and_b32_e32 v93, 0xffff0000, v178
	v_pk_add_f32 v[86:87], v[86:87], v[94:95]
	v_pk_add_f32 v[82:83], v[82:83], v[92:93]
	global_store_dwordx4 v[98:99], v[82:85], off offset:512 nt
	global_store_dwordx4 v[98:99], v[86:89], off offset:528 nt
	s_nop 0
	v_mov_b32_e32 v83, v0
	v_add_u32_e32 v86, s51, v147
	v_ashrrev_i32_e32 v87, 31, v86
	v_add_u32_e32 v82, 0xffff0000, v86
	v_lshlrev_b64 v[88:89], 12, v[82:83]
	v_lshlrev_b64 v[82:83], 11, v[86:87]
	v_lshl_add_u64 v[82:83], s[0:1], 0, v[82:83]
	v_lshl_add_u64 v[90:91], v[82:83], 0, v[142:143]
	v_cmp_gt_i32_e32 vcc, s16, v86
	s_waitcnt vmcnt(21)
	v_lshlrev_b32_e32 v92, 16, v182
	v_and_b32_e32 v93, 0xffff0000, v182
	v_lshlrev_b32_e32 v82, 16, v183
	v_and_b32_e32 v83, 0xffff0000, v183
	v_pk_add_f32 v[80:81], v[80:81], v[82:83]
	v_lshlrev_b32_e32 v82, 16, v184
	v_and_b32_e32 v83, 0xffff0000, v184
	v_pk_add_f32 v[74:75], v[74:75], v[82:83]
	v_lshlrev_b32_e32 v82, 16, v185
	v_and_b32_e32 v83, 0xffff0000, v185
	v_pk_add_f32 v[76:77], v[76:77], v[82:83]
	v_lshlrev_b64 v[82:83], 12, v[86:87]
	v_lshl_add_u64 v[82:83], s[74:75], 0, v[82:83]
	v_lshl_add_u64 v[84:85], s[4:5], 0, v[88:89]
	v_cndmask_b32_e32 v83, v85, v83, vcc
	v_cndmask_b32_e32 v82, v84, v82, vcc
	v_pk_add_f32 v[78:79], v[78:79], v[92:93]
	v_lshl_add_u64 v[82:83], v[82:83], 0, v[122:123]
	global_store_dwordx4 v[82:83], v[78:81], off nt
	global_store_dwordx4 v[82:83], v[74:77], off offset:16 nt
	s_waitcnt vmcnt(22)
	v_lshlrev_b32_e32 v78, 16, v207
	v_and_b32_e32 v79, 0xffff0000, v207
	v_pk_add_f32 v[72:73], v[72:73], v[78:79]
	v_lshlrev_b32_e32 v78, 16, v206
	v_and_b32_e32 v79, 0xffff0000, v206
	v_lshlrev_b32_e32 v76, 16, v205
	v_and_b32_e32 v77, 0xffff0000, v205
	v_pk_add_f32 v[68:69], v[68:69], v[76:77]
	v_lshlrev_b32_e32 v76, 16, v204
	v_and_b32_e32 v77, 0xffff0000, v204
	v_pk_add_f32 v[70:71], v[70:71], v[78:79]
	v_pk_add_f32 v[66:67], v[66:67], v[76:77]
	global_store_dwordx4 v[82:83], v[66:69], off offset:512 nt
	global_store_dwordx4 v[82:83], v[70:73], off offset:528 nt
	s_nop 0
	v_mov_b32_e32 v67, v0
	v_add_u32_e32 v70, s88, v147
	v_ashrrev_i32_e32 v71, 31, v70
	v_add_u32_e32 v66, 0xffff0000, v70
	v_lshlrev_b64 v[72:73], 12, v[66:67]
	v_lshlrev_b64 v[66:67], 11, v[70:71]
	v_lshl_add_u64 v[66:67], s[0:1], 0, v[66:67]
	v_lshl_add_u64 v[74:75], v[66:67], 0, v[142:143]
	v_cmp_gt_i32_e32 vcc, s16, v70
	s_waitcnt vmcnt(23)
	v_lshlrev_b32_e32 v76, 16, v208
	v_and_b32_e32 v77, 0xffff0000, v208
	v_lshlrev_b32_e32 v66, 16, v209
	v_and_b32_e32 v67, 0xffff0000, v209
	v_pk_add_f32 v[64:65], v[64:65], v[66:67]
	v_lshlrev_b32_e32 v66, 16, v210
	v_and_b32_e32 v67, 0xffff0000, v210
	v_pk_add_f32 v[58:59], v[58:59], v[66:67]
	v_lshlrev_b32_e32 v66, 16, v211
	v_and_b32_e32 v67, 0xffff0000, v211
	v_pk_add_f32 v[60:61], v[60:61], v[66:67]
	v_lshlrev_b64 v[66:67], 12, v[70:71]
	v_lshl_add_u64 v[66:67], s[74:75], 0, v[66:67]
	v_lshl_add_u64 v[68:69], s[4:5], 0, v[72:73]
	v_cndmask_b32_e32 v67, v69, v67, vcc
	v_cndmask_b32_e32 v66, v68, v66, vcc
	v_pk_add_f32 v[62:63], v[62:63], v[76:77]
	v_lshl_add_u64 v[66:67], v[66:67], 0, v[122:123]
	global_store_dwordx4 v[66:67], v[62:65], off nt
	global_store_dwordx4 v[66:67], v[58:61], off offset:16 nt
	s_waitcnt vmcnt(24)
	v_lshlrev_b32_e32 v62, 16, v215
	v_and_b32_e32 v63, 0xffff0000, v215
	v_pk_add_f32 v[56:57], v[56:57], v[62:63]
	v_lshlrev_b32_e32 v62, 16, v214
	v_and_b32_e32 v63, 0xffff0000, v214
	v_lshlrev_b32_e32 v60, 16, v213
	v_and_b32_e32 v61, 0xffff0000, v213
	v_pk_add_f32 v[52:53], v[52:53], v[60:61]
	v_lshlrev_b32_e32 v60, 16, v212
	v_and_b32_e32 v61, 0xffff0000, v212
	v_pk_add_f32 v[54:55], v[54:55], v[62:63]
	v_pk_add_f32 v[50:51], v[50:51], v[60:61]
	global_store_dwordx4 v[66:67], v[50:53], off offset:512 nt
	global_store_dwordx4 v[66:67], v[54:57], off offset:528 nt
	s_nop 0
	v_mov_b32_e32 v51, v0
	v_add_u32_e32 v54, s60, v147
	v_ashrrev_i32_e32 v55, 31, v54
	v_add_u32_e32 v50, 0xffff0000, v54
	v_lshlrev_b64 v[56:57], 12, v[50:51]
	v_lshlrev_b64 v[50:51], 11, v[54:55]
	v_lshl_add_u64 v[50:51], s[0:1], 0, v[50:51]
	v_lshl_add_u64 v[58:59], v[50:51], 0, v[142:143]
	v_cmp_gt_i32_e32 vcc, s16, v54
	s_waitcnt vmcnt(25)
	v_lshlrev_b32_e32 v60, 16, v216
	v_and_b32_e32 v61, 0xffff0000, v216
	v_lshlrev_b32_e32 v50, 16, v217
	v_and_b32_e32 v51, 0xffff0000, v217
	v_pk_add_f32 v[48:49], v[48:49], v[50:51]
	v_lshlrev_b32_e32 v50, 16, v218
	v_and_b32_e32 v51, 0xffff0000, v218
	v_pk_add_f32 v[42:43], v[42:43], v[50:51]
	v_lshlrev_b32_e32 v50, 16, v219
	v_and_b32_e32 v51, 0xffff0000, v219
	v_pk_add_f32 v[44:45], v[44:45], v[50:51]
	v_lshlrev_b64 v[50:51], 12, v[54:55]
	v_lshl_add_u64 v[50:51], s[74:75], 0, v[50:51]
	v_lshl_add_u64 v[52:53], s[4:5], 0, v[56:57]
	v_cndmask_b32_e32 v51, v53, v51, vcc
	v_cndmask_b32_e32 v50, v52, v50, vcc
	v_pk_add_f32 v[46:47], v[46:47], v[60:61]
	v_lshl_add_u64 v[50:51], v[50:51], 0, v[122:123]
	global_store_dwordx4 v[50:51], v[46:49], off nt
	global_store_dwordx4 v[50:51], v[42:45], off offset:16 nt
	s_waitcnt vmcnt(26)
	v_lshlrev_b32_e32 v46, 16, v223
	v_and_b32_e32 v47, 0xffff0000, v223
	v_pk_add_f32 v[40:41], v[40:41], v[46:47]
	v_lshlrev_b32_e32 v46, 16, v222
	v_and_b32_e32 v47, 0xffff0000, v222
	v_lshlrev_b32_e32 v44, 16, v221
	v_and_b32_e32 v45, 0xffff0000, v221
	v_pk_add_f32 v[36:37], v[36:37], v[44:45]
	v_lshlrev_b32_e32 v44, 16, v220
	v_and_b32_e32 v45, 0xffff0000, v220
	v_pk_add_f32 v[38:39], v[38:39], v[46:47]
	v_pk_add_f32 v[34:35], v[34:35], v[44:45]
	global_store_dwordx4 v[50:51], v[34:37], off offset:512 nt
	global_store_dwordx4 v[50:51], v[38:41], off offset:528 nt
	s_nop 0
	v_mov_b32_e32 v35, v0
	v_add_u32_e32 v38, s61, v147
	v_ashrrev_i32_e32 v39, 31, v38
	v_add_u32_e32 v34, 0xffff0000, v38
	v_lshlrev_b64 v[40:41], 12, v[34:35]
	v_lshlrev_b64 v[34:35], 11, v[38:39]
	v_lshl_add_u64 v[34:35], s[0:1], 0, v[34:35]
	v_lshl_add_u64 v[42:43], v[34:35], 0, v[142:143]
	v_cmp_gt_i32_e32 vcc, s16, v38
	s_waitcnt vmcnt(27)
	v_lshlrev_b32_e32 v44, 16, v224
	v_and_b32_e32 v45, 0xffff0000, v224
	v_lshlrev_b32_e32 v34, 16, v225
	v_and_b32_e32 v35, 0xffff0000, v225
	v_pk_add_f32 v[32:33], v[32:33], v[34:35]
	v_lshlrev_b32_e32 v34, 16, v226
	v_and_b32_e32 v35, 0xffff0000, v226
	v_pk_add_f32 v[26:27], v[26:27], v[34:35]
	v_lshlrev_b32_e32 v34, 16, v227
	v_and_b32_e32 v35, 0xffff0000, v227
	v_pk_add_f32 v[28:29], v[28:29], v[34:35]
	v_lshlrev_b64 v[34:35], 12, v[38:39]
	v_lshl_add_u64 v[34:35], s[74:75], 0, v[34:35]
	v_lshl_add_u64 v[36:37], s[4:5], 0, v[40:41]
	v_cndmask_b32_e32 v35, v37, v35, vcc
	v_cndmask_b32_e32 v34, v36, v34, vcc
	v_pk_add_f32 v[30:31], v[30:31], v[44:45]
	v_lshl_add_u64 v[34:35], v[34:35], 0, v[122:123]
	global_store_dwordx4 v[34:35], v[30:33], off nt
	global_store_dwordx4 v[34:35], v[26:29], off offset:16 nt
	s_waitcnt vmcnt(28)
	v_lshlrev_b32_e32 v30, 16, v231
	v_and_b32_e32 v31, 0xffff0000, v231
	v_pk_add_f32 v[24:25], v[24:25], v[30:31]
	v_lshlrev_b32_e32 v30, 16, v230
	v_and_b32_e32 v31, 0xffff0000, v230
	v_lshlrev_b32_e32 v28, 16, v229
	v_and_b32_e32 v29, 0xffff0000, v229
	v_pk_add_f32 v[20:21], v[20:21], v[28:29]
	v_lshlrev_b32_e32 v28, 16, v228
	v_and_b32_e32 v29, 0xffff0000, v228
	v_pk_add_f32 v[22:23], v[22:23], v[30:31]
	v_pk_add_f32 v[18:19], v[18:19], v[28:29]
	global_store_dwordx4 v[34:35], v[18:21], off offset:512 nt
	global_store_dwordx4 v[34:35], v[22:25], off offset:528 nt
	s_nop 0
	v_mov_b32_e32 v19, v0
	v_add_u32_e32 v22, s62, v147
	v_ashrrev_i32_e32 v23, 31, v22
	v_add_u32_e32 v18, 0xffff0000, v22
	v_lshlrev_b64 v[24:25], 12, v[18:19]
	v_lshlrev_b64 v[18:19], 11, v[22:23]
	v_lshl_add_u64 v[18:19], s[0:1], 0, v[18:19]
	v_lshl_add_u64 v[26:27], v[18:19], 0, v[142:143]
	v_cmp_gt_i32_e32 vcc, s16, v22
	s_mov_b64 s[0:1], s[10:11]
	s_waitcnt vmcnt(29)
	v_lshlrev_b32_e32 v28, 16, v232
	v_and_b32_e32 v29, 0xffff0000, v232
	v_lshlrev_b32_e32 v18, 16, v233
	v_and_b32_e32 v19, 0xffff0000, v233
	v_pk_add_f32 v[16:17], v[16:17], v[18:19]
	v_lshlrev_b32_e32 v18, 16, v234
	v_and_b32_e32 v19, 0xffff0000, v234
	v_pk_add_f32 v[10:11], v[10:11], v[18:19]
	v_lshlrev_b32_e32 v18, 16, v235
	v_and_b32_e32 v19, 0xffff0000, v235
	v_pk_add_f32 v[12:13], v[12:13], v[18:19]
	v_lshlrev_b64 v[18:19], 12, v[22:23]
	v_lshl_add_u64 v[18:19], s[74:75], 0, v[18:19]
	v_lshl_add_u64 v[20:21], s[4:5], 0, v[24:25]
	v_cndmask_b32_e32 v19, v21, v19, vcc
	v_cndmask_b32_e32 v18, v20, v18, vcc
	v_pk_add_f32 v[14:15], v[14:15], v[28:29]
	v_lshl_add_u64 v[18:19], v[18:19], 0, v[122:123]
	global_store_dwordx4 v[18:19], v[14:17], off nt
	global_store_dwordx4 v[18:19], v[10:13], off offset:16 nt
	s_and_b64 vcc, exec, s[8:9]
	s_mov_b64 s[4:5], s[12:13]
	s_waitcnt vmcnt(30)
	v_lshlrev_b32_e32 v14, 16, v239
	v_and_b32_e32 v15, 0xffff0000, v239
	v_pk_add_f32 v[4:5], v[4:5], v[14:15]
	v_lshlrev_b32_e32 v14, 16, v238
	v_and_b32_e32 v15, 0xffff0000, v238
	v_lshlrev_b32_e32 v12, 16, v237
	v_and_b32_e32 v13, 0xffff0000, v237
	v_pk_add_f32 v[8:9], v[8:9], v[12:13]
	v_lshlrev_b32_e32 v12, 16, v236
	v_and_b32_e32 v13, 0xffff0000, v236
	v_pk_add_f32 v[6:7], v[6:7], v[12:13]
	v_pk_add_f32 v[2:3], v[2:3], v[14:15]
	global_store_dwordx4 v[18:19], v[6:9], off offset:512 nt
	global_store_dwordx4 v[18:19], v[2:5], off offset:528 nt
	s_cbranch_vccz .LBB0_242
	s_waitcnt vmcnt(0)
	s_cmpk_gt_u32 s18, 0xff
	s_cbranch_scc1 .LBB0_257
	s_barrier

.LBB0_281:
	s_add_u32 s0, s0, 0x80
	s_addc_u32 s1, s1, 0
	s_add_u32 s20, s4, 0x100
	s_addc_u32 s21, s5, 0
	s_mov_b32 s4, 0
	s_waitcnt lgkmcnt(0)
	s_add_i32 s22, s4, 2
	s_add_u32 s10, s0, 0x80
	s_addc_u32 s5, s1, 0
	s_add_i32 s23, 0, 0x10000
	v_add_u32_e32 v154, s23, v165
	ds_read_b128 v[142:145], v154
	ds_read_b128 v[146:149], v154 offset:1024
	ds_read_b128 v[150:153], v154 offset:2048
	ds_read_b128 v[154:157], v154 offset:3072
	s_cmp_eq_u32 s44, s4
	s_cselect_b32 s4, s16, s10
	s_cselect_b32 s5, s17, s5
	s_cselect_b32 s11, s13, s21
	s_cselect_b32 s10, s12, s20
	v_lshl_add_u64 v[162:163], s[0:1], 0, v[138:139]
	s_add_i32 m0, s29, 0xc000
	ds_read_b128 v[158:161], v166
	ds_read_b128 v[168:171], v166 offset:1024
	ds_read_b128 v[172:175], v166 offset:2048
	ds_read_b128 v[176:179], v166 offset:3072
	ds_read_b128 v[180:183], v166 offset:4096
	ds_read_b128 v[204:207], v166 offset:5120
	ds_read_b128 v[208:211], v166 offset:6144
	ds_read_b128 v[212:215], v166 offset:7168
	global_load_lds_dwordx4 v[162:163], off
	v_lshl_add_u64 v[162:163], s[0:1], 0, v[140:141]
	s_add_i32 m0, s29, 0xe000
	s_nop 0
	global_load_lds_dwordx4 v[162:163], off
	s_waitcnt lgkmcnt(8)
	s_barrier
	s_waitcnt lgkmcnt(0)
	s_setprio 1
	s_waitcnt lgkmcnt(0)
	v_mfma_f32_16x16x32_bf16 v[126:129], v[142:145], v[158:161], 0
	v_mfma_f32_16x16x32_bf16 v[122:125], v[150:153], v[158:161], 0
	v_mfma_f32_16x16x32_bf16 v[110:113], v[142:145], v[172:175], 0
	v_mfma_f32_16x16x32_bf16 v[106:109], v[150:153], v[172:175], 0
	v_mfma_f32_16x16x32_bf16 v[94:97], v[142:145], v[180:183], 0
	v_mfma_f32_16x16x32_bf16 v[90:93], v[150:153], v[180:183], 0
	v_mfma_f32_16x16x32_bf16 v[78:81], v[142:145], v[208:211], 0
	v_mfma_f32_16x16x32_bf16 v[74:77], v[150:153], v[208:211], 0
	v_mfma_f32_16x16x32_bf16 v[126:129], v[146:149], v[168:171], v[126:129]
	v_mfma_f32_16x16x32_bf16 v[122:125], v[154:157], v[168:171], v[122:125]
	v_mfma_f32_16x16x32_bf16 v[110:113], v[146:149], v[176:179], v[110:113]
	v_mfma_f32_16x16x32_bf16 v[106:109], v[154:157], v[176:179], v[106:109]
	v_mfma_f32_16x16x32_bf16 v[94:97], v[146:149], v[204:207], v[94:97]
	v_mfma_f32_16x16x32_bf16 v[90:93], v[154:157], v[204:207], v[90:93]
	v_mfma_f32_16x16x32_bf16 v[78:81], v[146:149], v[212:215], v[78:81]
	v_mfma_f32_16x16x32_bf16 v[74:77], v[154:157], v[212:215], v[74:77]
	s_setprio 0
	s_barrier
	s_add_i32 s24, 0, 0x14000
	v_add_u32_e32 v162, s24, v165
	s_add_i32 s23, s23, s28
	ds_read_b128 v[216:219], v162
	ds_read_b128 v[220:223], v162 offset:1024
	ds_read_b128 v[224:227], v162 offset:2048
	ds_read_b128 v[228:231], v162 offset:3072
	v_lshl_add_u64 v[162:163], s[10:11], 0, v[132:133]
	s_mov_b32 m0, s23
	v_lshl_add_u64 v[184:185], s[10:11], 0, v[136:137]
	global_load_lds_dwordx4 v[162:163], off
	s_add_i32 m0, s23, 0x2000
	s_nop 0
	global_load_lds_dwordx4 v[184:185], off
	s_barrier
	s_waitcnt lgkmcnt(0)
	s_setprio 1
	s_waitcnt lgkmcnt(0)
	v_mfma_f32_16x16x32_bf16 v[118:121], v[216:219], v[158:161], 0
	v_mfma_f32_16x16x32_bf16 v[114:117], v[224:227], v[158:161], 0
	v_mfma_f32_16x16x32_bf16 v[102:105], v[216:219], v[172:175], 0
	v_mfma_f32_16x16x32_bf16 v[98:101], v[224:227], v[172:175], 0
	v_mfma_f32_16x16x32_bf16 v[86:89], v[216:219], v[180:183], 0
	v_mfma_f32_16x16x32_bf16 v[82:85], v[224:227], v[180:183], 0
	v_mfma_f32_16x16x32_bf16 v[70:73], v[216:219], v[208:211], 0
	v_mfma_f32_16x16x32_bf16 v[66:69], v[224:227], v[208:211], 0
	v_mfma_f32_16x16x32_bf16 v[118:121], v[220:223], v[168:171], v[118:121]
	v_mfma_f32_16x16x32_bf16 v[114:117], v[228:231], v[168:171], v[114:117]
	v_mfma_f32_16x16x32_bf16 v[102:105], v[220:223], v[176:179], v[102:105]
	v_mfma_f32_16x16x32_bf16 v[98:101], v[228:231], v[176:179], v[98:101]
	v_mfma_f32_16x16x32_bf16 v[86:89], v[220:223], v[204:207], v[86:89]
	v_mfma_f32_16x16x32_bf16 v[82:85], v[228:231], v[204:207], v[82:85]
	v_mfma_f32_16x16x32_bf16 v[70:73], v[220:223], v[212:215], v[70:73]
	v_mfma_f32_16x16x32_bf16 v[66:69], v[228:231], v[212:215], v[66:69]
	s_setprio 0
	s_mov_b32 m0, s29
	v_lshl_add_u64 v[232:233], s[4:5], 0, v[130:131]
	s_barrier
	ds_read_b128 v[158:161], v166 offset:16384
	ds_read_b128 v[168:171], v166 offset:17408
	ds_read_b128 v[172:175], v166 offset:18432
	ds_read_b128 v[176:179], v166 offset:19456
	ds_read_b128 v[180:183], v166 offset:20480
	ds_read_b128 v[204:207], v166 offset:21504
	ds_read_b128 v[208:211], v166 offset:22528
	ds_read_b128 v[212:215], v166 offset:23552
	global_load_lds_dwordx4 v[232:233], off
	v_lshl_add_u64 v[234:235], s[4:5], 0, v[134:135]
	s_mov_b32 m0, s30
	s_nop 0
	global_load_lds_dwordx4 v[234:235], off
	s_barrier
	s_waitcnt lgkmcnt(0)
	s_setprio 1
	s_waitcnt lgkmcnt(0)
	v_mfma_f32_16x16x32_bf16 v[62:65], v[142:145], v[158:161], 0
	v_mfma_f32_16x16x32_bf16 v[58:61], v[150:153], v[158:161], 0
	v_mfma_f32_16x16x32_bf16 v[46:49], v[142:145], v[172:175], 0
	v_mfma_f32_16x16x32_bf16 v[42:45], v[150:153], v[172:175], 0
	v_mfma_f32_16x16x32_bf16 v[30:33], v[142:145], v[180:183], 0
	v_mfma_f32_16x16x32_bf16 v[26:29], v[150:153], v[180:183], 0
	v_mfma_f32_16x16x32_bf16 v[14:17], v[142:145], v[208:211], 0
	v_mfma_f32_16x16x32_bf16 v[10:13], v[150:153], v[208:211], 0
	v_mfma_f32_16x16x32_bf16 v[62:65], v[146:149], v[168:171], v[62:65]
	v_mfma_f32_16x16x32_bf16 v[58:61], v[154:157], v[168:171], v[58:61]
	v_mfma_f32_16x16x32_bf16 v[46:49], v[146:149], v[176:179], v[46:49]
	v_mfma_f32_16x16x32_bf16 v[42:45], v[154:157], v[176:179], v[42:45]
	v_mfma_f32_16x16x32_bf16 v[30:33], v[146:149], v[204:207], v[30:33]
	v_mfma_f32_16x16x32_bf16 v[26:29], v[154:157], v[204:207], v[26:29]
	v_mfma_f32_16x16x32_bf16 v[14:17], v[146:149], v[212:215], v[14:17]
	v_mfma_f32_16x16x32_bf16 v[10:13], v[154:157], v[212:215], v[10:13]
	s_setprio 0
	s_barrier
	s_add_u32 s10, s10, s92
	s_addc_u32 s11, s11, 0
	s_add_i32 s23, s24, s28
	v_lshl_add_u64 v[236:237], s[10:11], 0, v[132:133]
	s_mov_b32 m0, s23
	v_lshl_add_u64 v[238:239], s[10:11], 0, v[136:137]
	global_load_lds_dwordx4 v[236:237], off
	s_add_i32 m0, s23, 0x2000
	s_nop 0
	global_load_lds_dwordx4 v[238:239], off
	s_waitcnt vmcnt(6)
	s_barrier
	s_setprio 1
	v_mfma_f32_16x16x32_bf16 v[54:57], v[216:219], v[158:161], 0
	v_mfma_f32_16x16x32_bf16 v[50:53], v[224:227], v[158:161], 0
	v_mfma_f32_16x16x32_bf16 v[38:41], v[216:219], v[172:175], 0
	v_mfma_f32_16x16x32_bf16 v[34:37], v[224:227], v[172:175], 0
	v_mfma_f32_16x16x32_bf16 v[22:25], v[216:219], v[180:183], 0
	v_mfma_f32_16x16x32_bf16 v[18:21], v[224:227], v[180:183], 0
	v_mfma_f32_16x16x32_bf16 v[6:9], v[216:219], v[208:211], 0
	v_mfma_f32_16x16x32_bf16 v[2:5], v[224:227], v[208:211], 0
	v_mfma_f32_16x16x32_bf16 v[54:57], v[220:223], v[168:171], v[54:57]
	v_mfma_f32_16x16x32_bf16 v[50:53], v[228:231], v[168:171], v[50:53]
	v_mfma_f32_16x16x32_bf16 v[38:41], v[220:223], v[176:179], v[38:41]
	v_mfma_f32_16x16x32_bf16 v[34:37], v[228:231], v[176:179], v[34:37]
	v_mfma_f32_16x16x32_bf16 v[22:25], v[220:223], v[204:207], v[22:25]
	v_mfma_f32_16x16x32_bf16 v[18:21], v[228:231], v[204:207], v[18:21]
	v_mfma_f32_16x16x32_bf16 v[6:9], v[220:223], v[212:215], v[6:9]
	v_mfma_f32_16x16x32_bf16 v[2:5], v[228:231], v[212:215], v[2:5]
	s_setprio 0
	s_add_i32 s10, 0, 0x18000
	v_add_u32_e32 v154, s10, v165
	s_barrier
	ds_read_b128 v[142:145], v154
	ds_read_b128 v[146:149], v154 offset:1024
	ds_read_b128 v[150:153], v154 offset:2048
	ds_read_b128 v[154:157], v154 offset:3072
	s_add_u32 s4, s4, s92
	s_addc_u32 s5, s5, 0
	s_mov_b32 m0, s31
	v_lshl_add_u64 v[216:217], s[4:5], 0, v[130:131]
	ds_read_b128 v[158:161], v166 offset:32768
	ds_read_b128 v[168:171], v166 offset:33792
	ds_read_b128 v[172:175], v166 offset:34816
	ds_read_b128 v[176:179], v166 offset:35840
	ds_read_b128 v[180:183], v166 offset:36864
	ds_read_b128 v[204:207], v166 offset:37888
	ds_read_b128 v[208:211], v166 offset:38912
	ds_read_b128 v[212:215], v166 offset:39936
	global_load_lds_dwordx4 v[216:217], off
	v_lshl_add_u64 v[216:217], s[4:5], 0, v[134:135]
	s_mov_b32 m0, s34
	s_nop 0
	global_load_lds_dwordx4 v[216:217], off
	s_waitcnt lgkmcnt(8)
	s_barrier
	s_waitcnt lgkmcnt(0)
	s_setprio 1
	s_waitcnt lgkmcnt(0)
	v_mfma_f32_16x16x32_bf16 v[126:129], v[142:145], v[158:161], v[126:129]
	v_mfma_f32_16x16x32_bf16 v[122:125], v[150:153], v[158:161], v[122:125]
	v_mfma_f32_16x16x32_bf16 v[110:113], v[142:145], v[172:175], v[110:113]
	v_mfma_f32_16x16x32_bf16 v[106:109], v[150:153], v[172:175], v[106:109]
	v_mfma_f32_16x16x32_bf16 v[94:97], v[142:145], v[180:183], v[94:97]
	v_mfma_f32_16x16x32_bf16 v[90:93], v[150:153], v[180:183], v[90:93]
	v_mfma_f32_16x16x32_bf16 v[78:81], v[142:145], v[208:211], v[78:81]
	v_mfma_f32_16x16x32_bf16 v[74:77], v[150:153], v[208:211], v[74:77]
	v_mfma_f32_16x16x32_bf16 v[126:129], v[146:149], v[168:171], v[126:129]
	v_mfma_f32_16x16x32_bf16 v[122:125], v[154:157], v[168:171], v[122:125]
	v_mfma_f32_16x16x32_bf16 v[110:113], v[146:149], v[176:179], v[110:113]
	v_mfma_f32_16x16x32_bf16 v[106:109], v[154:157], v[176:179], v[106:109]
	v_mfma_f32_16x16x32_bf16 v[94:97], v[146:149], v[204:207], v[94:97]
	v_mfma_f32_16x16x32_bf16 v[90:93], v[154:157], v[204:207], v[90:93]
	v_mfma_f32_16x16x32_bf16 v[78:81], v[146:149], v[212:215], v[78:81]
	v_mfma_f32_16x16x32_bf16 v[74:77], v[154:157], v[212:215], v[74:77]
	s_setprio 0
	s_barrier
	s_add_i32 s4, 0, 0x1c000
	s_add_i32 s5, s10, s28
	v_add_u32_e32 v167, s4, v165
	v_lshl_add_u64 v[162:163], v[162:163], 0, s[6:7]
	s_mov_b32 m0, s5
	ds_read_b128 v[216:219], v167
	ds_read_b128 v[220:223], v167 offset:1024
	ds_read_b128 v[224:227], v167 offset:2048
	ds_read_b128 v[228:231], v167 offset:3072
	global_load_lds_dwordx4 v[162:163], off
	v_lshl_add_u64 v[162:163], v[184:185], 0, s[6:7]
	s_add_i32 m0, s5, 0x2000
	s_nop 0
	global_load_lds_dwordx4 v[162:163], off
	s_barrier
	s_waitcnt lgkmcnt(0)
	s_setprio 1
	s_waitcnt lgkmcnt(0)
	v_mfma_f32_16x16x32_bf16 v[118:121], v[216:219], v[158:161], v[118:121]
	v_mfma_f32_16x16x32_bf16 v[114:117], v[224:227], v[158:161], v[114:117]
	v_mfma_f32_16x16x32_bf16 v[102:105], v[216:219], v[172:175], v[102:105]
	v_mfma_f32_16x16x32_bf16 v[98:101], v[224:227], v[172:175], v[98:101]
	v_mfma_f32_16x16x32_bf16 v[86:89], v[216:219], v[180:183], v[86:89]
	v_mfma_f32_16x16x32_bf16 v[82:85], v[224:227], v[180:183], v[82:85]
	v_mfma_f32_16x16x32_bf16 v[70:73], v[216:219], v[208:211], v[70:73]
	v_mfma_f32_16x16x32_bf16 v[66:69], v[224:227], v[208:211], v[66:69]
	v_mfma_f32_16x16x32_bf16 v[118:121], v[220:223], v[168:171], v[118:121]
	v_mfma_f32_16x16x32_bf16 v[114:117], v[228:231], v[168:171], v[114:117]
	v_mfma_f32_16x16x32_bf16 v[102:105], v[220:223], v[176:179], v[102:105]
	v_mfma_f32_16x16x32_bf16 v[98:101], v[228:231], v[176:179], v[98:101]
	v_mfma_f32_16x16x32_bf16 v[86:89], v[220:223], v[204:207], v[86:89]
	v_mfma_f32_16x16x32_bf16 v[82:85], v[228:231], v[204:207], v[82:85]
	v_mfma_f32_16x16x32_bf16 v[70:73], v[220:223], v[212:215], v[70:73]
	v_mfma_f32_16x16x32_bf16 v[66:69], v[228:231], v[212:215], v[66:69]
	s_setprio 0
	s_mov_b32 m0, s42
	v_lshl_add_u64 v[162:163], v[232:233], 0, s[6:7]
	s_barrier
	ds_read_b128 v[158:161], v166 offset:49152
	ds_read_b128 v[168:171], v166 offset:50176
	ds_read_b128 v[172:175], v166 offset:51200
	ds_read_b128 v[176:179], v166 offset:52224
	ds_read_b128 v[180:183], v166 offset:53248
	ds_read_b128 v[204:207], v166 offset:54272
	ds_read_b128 v[208:211], v166 offset:55296
	ds_read_b128 v[212:215], v166 offset:56320
	global_load_lds_dwordx4 v[162:163], off
	v_lshl_add_u64 v[162:163], v[234:235], 0, s[6:7]
	s_mov_b32 m0, s43
	s_nop 0
	global_load_lds_dwordx4 v[162:163], off
	s_barrier
	s_waitcnt lgkmcnt(0)
	s_setprio 1
	s_waitcnt lgkmcnt(0)
	v_mfma_f32_16x16x32_bf16 v[62:65], v[142:145], v[158:161], v[62:65]
	v_mfma_f32_16x16x32_bf16 v[58:61], v[150:153], v[158:161], v[58:61]
	v_mfma_f32_16x16x32_bf16 v[46:49], v[142:145], v[172:175], v[46:49]
	v_mfma_f32_16x16x32_bf16 v[42:45], v[150:153], v[172:175], v[42:45]
	v_mfma_f32_16x16x32_bf16 v[30:33], v[142:145], v[180:183], v[30:33]
	v_mfma_f32_16x16x32_bf16 v[26:29], v[150:153], v[180:183], v[26:29]
	v_mfma_f32_16x16x32_bf16 v[14:17], v[142:145], v[208:211], v[14:17]
	v_mfma_f32_16x16x32_bf16 v[10:13], v[150:153], v[208:211], v[10:13]
	v_mfma_f32_16x16x32_bf16 v[62:65], v[146:149], v[168:171], v[62:65]
	v_mfma_f32_16x16x32_bf16 v[58:61], v[154:157], v[168:171], v[58:61]
	v_mfma_f32_16x16x32_bf16 v[46:49], v[146:149], v[176:179], v[46:49]
	v_mfma_f32_16x16x32_bf16 v[42:45], v[154:157], v[176:179], v[42:45]
	v_mfma_f32_16x16x32_bf16 v[30:33], v[146:149], v[204:207], v[30:33]
	v_mfma_f32_16x16x32_bf16 v[26:29], v[154:157], v[204:207], v[26:29]
	v_mfma_f32_16x16x32_bf16 v[14:17], v[146:149], v[212:215], v[14:17]
	v_mfma_f32_16x16x32_bf16 v[10:13], v[154:157], v[212:215], v[10:13]
	s_setprio 0
	s_barrier
	s_add_i32 s4, s4, s28
	v_lshl_add_u64 v[142:143], v[236:237], 0, s[6:7]
	s_mov_b32 m0, s4
	s_nop 0
	global_load_lds_dwordx4 v[142:143], off
	v_lshl_add_u64 v[142:143], v[238:239], 0, s[6:7]
	s_add_i32 m0, s4, 0x2000
	s_nop 0
	global_load_lds_dwordx4 v[142:143], off
	s_waitcnt vmcnt(6)
	s_barrier
	s_setprio 1
	v_mfma_f32_16x16x32_bf16 v[54:57], v[216:219], v[158:161], v[54:57]
	v_mfma_f32_16x16x32_bf16 v[50:53], v[224:227], v[158:161], v[50:53]
	v_mfma_f32_16x16x32_bf16 v[38:41], v[216:219], v[172:175], v[38:41]
	v_mfma_f32_16x16x32_bf16 v[34:37], v[224:227], v[172:175], v[34:37]
	v_mfma_f32_16x16x32_bf16 v[22:25], v[216:219], v[180:183], v[22:25]
	v_mfma_f32_16x16x32_bf16 v[18:21], v[224:227], v[180:183], v[18:21]
	v_mfma_f32_16x16x32_bf16 v[6:9], v[216:219], v[208:211], v[6:9]
	v_mfma_f32_16x16x32_bf16 v[2:5], v[224:227], v[208:211], v[2:5]
	v_mfma_f32_16x16x32_bf16 v[54:57], v[220:223], v[168:171], v[54:57]
	v_mfma_f32_16x16x32_bf16 v[50:53], v[228:231], v[168:171], v[50:53]
	v_mfma_f32_16x16x32_bf16 v[38:41], v[220:223], v[176:179], v[38:41]
	v_mfma_f32_16x16x32_bf16 v[34:37], v[228:231], v[176:179], v[34:37]
	v_mfma_f32_16x16x32_bf16 v[22:25], v[220:223], v[204:207], v[22:25]
	v_mfma_f32_16x16x32_bf16 v[18:21], v[228:231], v[204:207], v[18:21]
	v_mfma_f32_16x16x32_bf16 v[6:9], v[220:223], v[212:215], v[6:9]
	v_mfma_f32_16x16x32_bf16 v[2:5], v[228:231], v[212:215], v[2:5]
	s_setprio 0
	s_add_u32 s0, s0, 0x100
	s_addc_u32 s1, s1, 0
	s_add_u32 s20, s20, 0x100
	s_addc_u32 s21, s21, 0
	s_cmp_ge_u32 s22, s35
	s_mov_b32 s4, s22
	s_barrier
	s_cbranch_scc1 .Lkexit_282

.Lkexit_282:
	v_mov_b32_e32 v143, v1
	v_mov_b32_e32 v144, v164
	s_lshl_b32 s5, s68, 8
	s_cmp_lg_u32 s68, s19
	v_lshl_add_u32 v142, v143, 4, v144
	s_mov_b64 s[0:1], -1
	s_cbranch_scc0 .LBB0_285
	s_add_i32 s4, s5, s40
	v_and_or_b32 v145, v142, 63, s4
	v_lshlrev_b32_e32 v162, 1, v142
	v_add_u32_e32 v145, s50, v145
	v_and_b32_e32 v146, 0xffffff80, v162
	v_add_u32_e32 v146, v145, v146
	v_ashrrev_i32_e32 v147, 31, v146
	v_readlane_b32 s0, v243, 61
	v_lshlrev_b64 v[146:147], 6, v[146:147]
	v_readlane_b32 s1, v243, 62
	v_lshl_add_u32 v167, v142, 2, s49
	s_nop 0
	v_lshl_add_u64 v[158:159], s[0:1], 0, v[146:147]
	global_load_dwordx4 v[146:149], v[158:159], off offset:48
	global_load_dwordx4 v[150:153], v[158:159], off offset:32
	global_load_dwordx4 v[154:157], v[158:159], off offset:16
	s_nop 0
	global_load_dwordx4 v[158:161], v[158:159], off
	v_add_u32_e32 v222, 0x80, v162
	v_and_b32_e32 v222, 0xffffff80, v222
	v_add_u32_e32 v222, v145, v222
	v_ashrrev_i32_e32 v223, 31, v222
	v_lshlrev_b64 v[222:223], 6, v[222:223]
	v_lshl_add_u64 v[220:221], s[0:1], 0, v[222:223]
	global_load_dwordx4 v[204:207], v[220:221], off offset:48
	global_load_dwordx4 v[208:211], v[220:221], off offset:32
	global_load_dwordx4 v[212:215], v[220:221], off offset:16
	global_load_dwordx4 v[216:219], v[220:221], off
	s_waitcnt vmcnt(4)
	v_add_f32_e32 v146, v146, v147
	v_add_f32_e32 v150, v150, v151
	v_add_f32_e32 v154, v154, v155
	v_add_f32_e32 v158, v158, v159
	v_add_f32_e32 v158, v160, v158
	v_add_f32_e32 v154, v156, v154
	v_add_f32_e32 v158, v161, v158
	v_add_f32_e32 v154, v157, v154
	v_add_f32_e32 v150, v152, v150
	v_add_f32_e32 v154, v158, v154
	v_add_f32_e32 v150, v153, v150
	v_add_f32_e32 v146, v148, v146
	v_add_f32_e32 v150, v154, v150
	v_add_f32_e32 v146, v149, v146
	v_add_f32_e32 v146, v150, v146
	v_fmamk_f32 v146, v146, 0x3a800000, v188
	v_rsq_f32_e32 v163, v146
	s_mov_b64 s[0:1], 0
	s_waitcnt vmcnt(0)
	v_add_f32_e32 v146, v204, v205
	v_add_f32_e32 v150, v208, v209
	v_add_f32_e32 v154, v212, v213
	v_add_f32_e32 v145, v216, v217
	v_add_f32_e32 v145, v218, v145
	v_add_f32_e32 v154, v214, v154
	v_add_f32_e32 v145, v219, v145
	v_add_f32_e32 v154, v215, v154
	v_add_f32_e32 v150, v210, v150
	v_add_f32_e32 v145, v145, v154
	v_add_f32_e32 v150, v211, v150
	v_add_f32_e32 v146, v206, v146
	v_add_f32_e32 v145, v145, v150
	v_add_f32_e32 v146, v207, v146
	v_add_f32_e32 v145, v145, v146
	v_fmamk_f32 v145, v145, 0x3a800000, v188
	v_rsq_f32_e32 v145, v145
	ds_write2st64_b32 v167, v163, v145 offset1:1
	s_waitcnt lgkmcnt(0)

.LBB0_346:
	s_add_u32 s0, s0, 0x80
	s_addc_u32 s1, s1, 0
	s_add_u32 s12, s4, 0x100
	s_addc_u32 s13, s5, 0
	s_mov_b32 s4, 0
	s_waitcnt lgkmcnt(0)
	s_waitcnt vmcnt(0)
	s_add_i32 s15, s4, 2
	s_add_u32 s10, s0, 0x80
	s_addc_u32 s5, s1, 0
	s_add_i32 s16, 0, 0x10000
	v_add_u32_e32 v142, s16, v205
	ds_read_b128 v[130:133], v142
	ds_read_b128 v[134:137], v142 offset:1024
	ds_read_b128 v[138:141], v142 offset:2048
	ds_read_b128 v[142:145], v142 offset:3072
	s_cmp_eq_u32 s79, s4
	s_cselect_b32 s4, s44, s10
	s_cselect_b32 s5, s45, s5
	s_cselect_b32 s11, s47, s13
	s_cselect_b32 s10, s46, s12
	v_lshl_add_u64 v[212:213], s[0:1], 0, v[154:155]
	s_add_i32 m0, s71, 0xc000
	ds_read_b128 v[158:161], v206
	ds_read_b128 v[162:165], v206 offset:1024
	ds_read_b128 v[166:169], v206 offset:2048
	ds_read_b128 v[170:173], v206 offset:3072
	ds_read_b128 v[174:177], v206 offset:4096
	ds_read_b128 v[178:181], v206 offset:5120
	ds_read_b128 v[182:185], v206 offset:6144
	ds_read_b128 v[208:211], v206 offset:7168
	global_load_lds_dwordx4 v[212:213], off
	v_lshl_add_u64 v[212:213], s[0:1], 0, v[156:157]
	s_add_i32 m0, s71, 0xe000
	s_nop 0
	global_load_lds_dwordx4 v[212:213], off
	s_waitcnt lgkmcnt(8)
	s_barrier
	s_waitcnt lgkmcnt(0)
	s_setprio 1
	s_waitcnt lgkmcnt(0)
	v_mfma_f32_16x16x32_bf16 v[126:129], v[130:133], v[158:161], 0
	v_mfma_f32_16x16x32_bf16 v[122:125], v[138:141], v[158:161], 0
	v_mfma_f32_16x16x32_bf16 v[110:113], v[130:133], v[166:169], 0
	v_mfma_f32_16x16x32_bf16 v[106:109], v[138:141], v[166:169], 0
	v_mfma_f32_16x16x32_bf16 v[94:97], v[130:133], v[174:177], 0
	v_mfma_f32_16x16x32_bf16 v[90:93], v[138:141], v[174:177], 0
	v_mfma_f32_16x16x32_bf16 v[78:81], v[130:133], v[182:185], 0
	v_mfma_f32_16x16x32_bf16 v[74:77], v[138:141], v[182:185], 0
	v_mfma_f32_16x16x32_bf16 v[126:129], v[134:137], v[162:165], v[126:129]
	v_mfma_f32_16x16x32_bf16 v[122:125], v[142:145], v[162:165], v[122:125]
	v_mfma_f32_16x16x32_bf16 v[110:113], v[134:137], v[170:173], v[110:113]
	v_mfma_f32_16x16x32_bf16 v[106:109], v[142:145], v[170:173], v[106:109]
	v_mfma_f32_16x16x32_bf16 v[94:97], v[134:137], v[178:181], v[94:97]
	v_mfma_f32_16x16x32_bf16 v[90:93], v[142:145], v[178:181], v[90:93]
	v_mfma_f32_16x16x32_bf16 v[78:81], v[134:137], v[208:211], v[78:81]
	v_mfma_f32_16x16x32_bf16 v[74:77], v[142:145], v[208:211], v[74:77]
	s_setprio 0
	s_barrier
	s_add_i32 s17, 0, 0x14000
	s_add_i32 s16, s16, s70
	v_add_u32_e32 v207, s17, v205
	v_lshl_add_u64 v[228:229], s[10:11], 0, v[148:149]
	s_mov_b32 m0, s16
	ds_read_b128 v[212:215], v207
	ds_read_b128 v[216:219], v207 offset:1024
	ds_read_b128 v[220:223], v207 offset:2048
	ds_read_b128 v[224:227], v207 offset:3072
	global_load_lds_dwordx4 v[228:229], off
	v_lshl_add_u64 v[230:231], s[10:11], 0, v[152:153]
	s_add_i32 m0, s16, 0x2000
	s_nop 0
	global_load_lds_dwordx4 v[230:231], off
	s_barrier
	s_waitcnt lgkmcnt(0)
	s_setprio 1
	s_waitcnt lgkmcnt(0)
	v_mfma_f32_16x16x32_bf16 v[118:121], v[212:215], v[158:161], 0
	v_mfma_f32_16x16x32_bf16 v[114:117], v[220:223], v[158:161], 0
	v_mfma_f32_16x16x32_bf16 v[102:105], v[212:215], v[166:169], 0
	v_mfma_f32_16x16x32_bf16 v[98:101], v[220:223], v[166:169], 0
	v_mfma_f32_16x16x32_bf16 v[86:89], v[212:215], v[174:177], 0
	v_mfma_f32_16x16x32_bf16 v[82:85], v[220:223], v[174:177], 0
	v_mfma_f32_16x16x32_bf16 v[70:73], v[212:215], v[182:185], 0
	v_mfma_f32_16x16x32_bf16 v[66:69], v[220:223], v[182:185], 0
	v_mfma_f32_16x16x32_bf16 v[118:121], v[216:219], v[162:165], v[118:121]
	v_mfma_f32_16x16x32_bf16 v[114:117], v[224:227], v[162:165], v[114:117]
	v_mfma_f32_16x16x32_bf16 v[102:105], v[216:219], v[170:173], v[102:105]
	v_mfma_f32_16x16x32_bf16 v[98:101], v[224:227], v[170:173], v[98:101]
	v_mfma_f32_16x16x32_bf16 v[86:89], v[216:219], v[178:181], v[86:89]
	v_mfma_f32_16x16x32_bf16 v[82:85], v[224:227], v[178:181], v[82:85]
	v_mfma_f32_16x16x32_bf16 v[70:73], v[216:219], v[208:211], v[70:73]
	v_mfma_f32_16x16x32_bf16 v[66:69], v[224:227], v[208:211], v[66:69]
	s_setprio 0
	s_mov_b32 m0, s71
	v_lshl_add_u64 v[232:233], s[4:5], 0, v[146:147]
	s_barrier
	ds_read_b128 v[158:161], v206 offset:16384
	ds_read_b128 v[162:165], v206 offset:17408
	ds_read_b128 v[166:169], v206 offset:18432
	ds_read_b128 v[170:173], v206 offset:19456
	ds_read_b128 v[174:177], v206 offset:20480
	ds_read_b128 v[178:181], v206 offset:21504
	ds_read_b128 v[182:185], v206 offset:22528
	ds_read_b128 v[208:211], v206 offset:23552
	global_load_lds_dwordx4 v[232:233], off
	v_lshl_add_u64 v[234:235], s[4:5], 0, v[150:151]
	s_mov_b32 m0, s72
	s_nop 0
	global_load_lds_dwordx4 v[234:235], off
	s_barrier
	s_waitcnt lgkmcnt(0)
	s_setprio 1
	s_waitcnt lgkmcnt(0)
	v_mfma_f32_16x16x32_bf16 v[62:65], v[130:133], v[158:161], 0
	v_mfma_f32_16x16x32_bf16 v[58:61], v[138:141], v[158:161], 0
	v_mfma_f32_16x16x32_bf16 v[46:49], v[130:133], v[166:169], 0
	v_mfma_f32_16x16x32_bf16 v[42:45], v[138:141], v[166:169], 0
	v_mfma_f32_16x16x32_bf16 v[30:33], v[130:133], v[174:177], 0
	v_mfma_f32_16x16x32_bf16 v[26:29], v[138:141], v[174:177], 0
	v_mfma_f32_16x16x32_bf16 v[14:17], v[130:133], v[182:185], 0
	v_mfma_f32_16x16x32_bf16 v[10:13], v[138:141], v[182:185], 0
	v_mfma_f32_16x16x32_bf16 v[62:65], v[134:137], v[162:165], v[62:65]
	v_mfma_f32_16x16x32_bf16 v[58:61], v[142:145], v[162:165], v[58:61]
	v_mfma_f32_16x16x32_bf16 v[46:49], v[134:137], v[170:173], v[46:49]
	v_mfma_f32_16x16x32_bf16 v[42:45], v[142:145], v[170:173], v[42:45]
	v_mfma_f32_16x16x32_bf16 v[30:33], v[134:137], v[178:181], v[30:33]
	v_mfma_f32_16x16x32_bf16 v[26:29], v[142:145], v[178:181], v[26:29]
	v_mfma_f32_16x16x32_bf16 v[14:17], v[134:137], v[208:211], v[14:17]
	v_mfma_f32_16x16x32_bf16 v[10:13], v[142:145], v[208:211], v[10:13]
	s_setprio 0
	s_barrier
	s_add_u32 s10, s10, s92
	s_addc_u32 s11, s11, 0
	s_add_i32 s16, s17, s70
	v_lshl_add_u64 v[236:237], s[10:11], 0, v[148:149]
	s_mov_b32 m0, s16
	v_lshl_add_u64 v[238:239], s[10:11], 0, v[152:153]
	global_load_lds_dwordx4 v[236:237], off
	s_add_i32 m0, s16, 0x2000
	s_nop 0
	global_load_lds_dwordx4 v[238:239], off
	s_waitcnt vmcnt(6)
	s_barrier
	s_setprio 1
	v_mfma_f32_16x16x32_bf16 v[54:57], v[212:215], v[158:161], 0
	v_mfma_f32_16x16x32_bf16 v[50:53], v[220:223], v[158:161], 0
	v_mfma_f32_16x16x32_bf16 v[38:41], v[212:215], v[166:169], 0
	v_mfma_f32_16x16x32_bf16 v[34:37], v[220:223], v[166:169], 0
	v_mfma_f32_16x16x32_bf16 v[22:25], v[212:215], v[174:177], 0
	v_mfma_f32_16x16x32_bf16 v[18:21], v[220:223], v[174:177], 0
	v_mfma_f32_16x16x32_bf16 v[6:9], v[212:215], v[182:185], 0
	v_mfma_f32_16x16x32_bf16 v[2:5], v[220:223], v[182:185], 0
	v_mfma_f32_16x16x32_bf16 v[54:57], v[216:219], v[162:165], v[54:57]
	v_mfma_f32_16x16x32_bf16 v[50:53], v[224:227], v[162:165], v[50:53]
	v_mfma_f32_16x16x32_bf16 v[38:41], v[216:219], v[170:173], v[38:41]
	v_mfma_f32_16x16x32_bf16 v[34:37], v[224:227], v[170:173], v[34:37]
	v_mfma_f32_16x16x32_bf16 v[22:25], v[216:219], v[178:181], v[22:25]
	v_mfma_f32_16x16x32_bf16 v[18:21], v[224:227], v[178:181], v[18:21]
	v_mfma_f32_16x16x32_bf16 v[6:9], v[216:219], v[208:211], v[6:9]
	v_mfma_f32_16x16x32_bf16 v[2:5], v[224:227], v[208:211], v[2:5]
	s_setprio 0
	s_add_i32 s10, 0, 0x18000
	v_add_u32_e32 v142, s10, v205
	s_barrier
	ds_read_b128 v[130:133], v142
	ds_read_b128 v[134:137], v142 offset:1024
	ds_read_b128 v[138:141], v142 offset:2048
	ds_read_b128 v[142:145], v142 offset:3072
	s_add_u32 s4, s4, s92
	s_addc_u32 s5, s5, 0
	s_mov_b32 m0, s73
	v_lshl_add_u64 v[212:213], s[4:5], 0, v[146:147]
	ds_read_b128 v[158:161], v206 offset:32768
	ds_read_b128 v[162:165], v206 offset:33792
	ds_read_b128 v[166:169], v206 offset:34816
	ds_read_b128 v[170:173], v206 offset:35840
	ds_read_b128 v[174:177], v206 offset:36864
	ds_read_b128 v[178:181], v206 offset:37888
	ds_read_b128 v[182:185], v206 offset:38912
	ds_read_b128 v[208:211], v206 offset:39936
	global_load_lds_dwordx4 v[212:213], off
	v_lshl_add_u64 v[212:213], s[4:5], 0, v[150:151]
	s_mov_b32 m0, s74
	s_nop 0
	global_load_lds_dwordx4 v[212:213], off
	s_waitcnt lgkmcnt(8)
	s_barrier
	s_waitcnt lgkmcnt(0)
	s_setprio 1
	s_waitcnt lgkmcnt(0)
	v_mfma_f32_16x16x32_bf16 v[126:129], v[130:133], v[158:161], v[126:129]
	v_mfma_f32_16x16x32_bf16 v[122:125], v[138:141], v[158:161], v[122:125]
	v_mfma_f32_16x16x32_bf16 v[110:113], v[130:133], v[166:169], v[110:113]
	v_mfma_f32_16x16x32_bf16 v[106:109], v[138:141], v[166:169], v[106:109]
	v_mfma_f32_16x16x32_bf16 v[94:97], v[130:133], v[174:177], v[94:97]
	v_mfma_f32_16x16x32_bf16 v[90:93], v[138:141], v[174:177], v[90:93]
	v_mfma_f32_16x16x32_bf16 v[78:81], v[130:133], v[182:185], v[78:81]
	v_mfma_f32_16x16x32_bf16 v[74:77], v[138:141], v[182:185], v[74:77]
	v_mfma_f32_16x16x32_bf16 v[126:129], v[134:137], v[162:165], v[126:129]
	v_mfma_f32_16x16x32_bf16 v[122:125], v[142:145], v[162:165], v[122:125]
	v_mfma_f32_16x16x32_bf16 v[110:113], v[134:137], v[170:173], v[110:113]
	v_mfma_f32_16x16x32_bf16 v[106:109], v[142:145], v[170:173], v[106:109]
	v_mfma_f32_16x16x32_bf16 v[94:97], v[134:137], v[178:181], v[94:97]
	v_mfma_f32_16x16x32_bf16 v[90:93], v[142:145], v[178:181], v[90:93]
	v_mfma_f32_16x16x32_bf16 v[78:81], v[134:137], v[208:211], v[78:81]
	v_mfma_f32_16x16x32_bf16 v[74:77], v[142:145], v[208:211], v[74:77]
	s_setprio 0
	s_barrier
	s_add_i32 s4, 0, 0x1c000
	s_add_i32 s5, s10, s70
	v_add_u32_e32 v207, s4, v205
	v_lshl_add_u64 v[228:229], v[228:229], 0, s[6:7]
	s_mov_b32 m0, s5
	ds_read_b128 v[212:215], v207
	ds_read_b128 v[216:219], v207 offset:1024
	ds_read_b128 v[220:223], v207 offset:2048
	ds_read_b128 v[224:227], v207 offset:3072
	global_load_lds_dwordx4 v[228:229], off
	v_lshl_add_u64 v[228:229], v[230:231], 0, s[6:7]
	s_add_i32 m0, s5, 0x2000
	s_nop 0
	global_load_lds_dwordx4 v[228:229], off
	s_barrier
	s_waitcnt lgkmcnt(0)
	s_setprio 1
	s_waitcnt lgkmcnt(0)
	v_mfma_f32_16x16x32_bf16 v[118:121], v[212:215], v[158:161], v[118:121]
	v_mfma_f32_16x16x32_bf16 v[114:117], v[220:223], v[158:161], v[114:117]
	v_mfma_f32_16x16x32_bf16 v[102:105], v[212:215], v[166:169], v[102:105]
	v_mfma_f32_16x16x32_bf16 v[98:101], v[220:223], v[166:169], v[98:101]
	v_mfma_f32_16x16x32_bf16 v[86:89], v[212:215], v[174:177], v[86:89]
	v_mfma_f32_16x16x32_bf16 v[82:85], v[220:223], v[174:177], v[82:85]
	v_mfma_f32_16x16x32_bf16 v[70:73], v[212:215], v[182:185], v[70:73]
	v_mfma_f32_16x16x32_bf16 v[66:69], v[220:223], v[182:185], v[66:69]
	v_mfma_f32_16x16x32_bf16 v[118:121], v[216:219], v[162:165], v[118:121]
	v_mfma_f32_16x16x32_bf16 v[114:117], v[224:227], v[162:165], v[114:117]
	v_mfma_f32_16x16x32_bf16 v[102:105], v[216:219], v[170:173], v[102:105]
	v_mfma_f32_16x16x32_bf16 v[98:101], v[224:227], v[170:173], v[98:101]
	v_mfma_f32_16x16x32_bf16 v[86:89], v[216:219], v[178:181], v[86:89]
	v_mfma_f32_16x16x32_bf16 v[82:85], v[224:227], v[178:181], v[82:85]
	v_mfma_f32_16x16x32_bf16 v[70:73], v[216:219], v[208:211], v[70:73]
	v_mfma_f32_16x16x32_bf16 v[66:69], v[224:227], v[208:211], v[66:69]
	s_setprio 0
	s_mov_b32 m0, s77
	v_lshl_add_u64 v[228:229], v[232:233], 0, s[6:7]
	s_barrier
	ds_read_b128 v[158:161], v206 offset:49152
	ds_read_b128 v[162:165], v206 offset:50176
	ds_read_b128 v[166:169], v206 offset:51200
	ds_read_b128 v[170:173], v206 offset:52224
	ds_read_b128 v[174:177], v206 offset:53248
	ds_read_b128 v[178:181], v206 offset:54272
	ds_read_b128 v[182:185], v206 offset:55296
	ds_read_b128 v[208:211], v206 offset:56320
	global_load_lds_dwordx4 v[228:229], off
	v_lshl_add_u64 v[228:229], v[234:235], 0, s[6:7]
	s_mov_b32 m0, s78
	s_nop 0
	global_load_lds_dwordx4 v[228:229], off
	s_barrier
	s_waitcnt lgkmcnt(0)
	s_setprio 1
	s_waitcnt lgkmcnt(0)
	v_mfma_f32_16x16x32_bf16 v[62:65], v[130:133], v[158:161], v[62:65]
	v_mfma_f32_16x16x32_bf16 v[58:61], v[138:141], v[158:161], v[58:61]
	v_mfma_f32_16x16x32_bf16 v[46:49], v[130:133], v[166:169], v[46:49]
	v_mfma_f32_16x16x32_bf16 v[42:45], v[138:141], v[166:169], v[42:45]
	v_mfma_f32_16x16x32_bf16 v[30:33], v[130:133], v[174:177], v[30:33]
	v_mfma_f32_16x16x32_bf16 v[26:29], v[138:141], v[174:177], v[26:29]
	v_mfma_f32_16x16x32_bf16 v[14:17], v[130:133], v[182:185], v[14:17]
	v_mfma_f32_16x16x32_bf16 v[10:13], v[138:141], v[182:185], v[10:13]
	v_mfma_f32_16x16x32_bf16 v[62:65], v[134:137], v[162:165], v[62:65]
	v_mfma_f32_16x16x32_bf16 v[58:61], v[142:145], v[162:165], v[58:61]
	v_mfma_f32_16x16x32_bf16 v[46:49], v[134:137], v[170:173], v[46:49]
	v_mfma_f32_16x16x32_bf16 v[42:45], v[142:145], v[170:173], v[42:45]
	v_mfma_f32_16x16x32_bf16 v[30:33], v[134:137], v[178:181], v[30:33]
	v_mfma_f32_16x16x32_bf16 v[26:29], v[142:145], v[178:181], v[26:29]
	v_mfma_f32_16x16x32_bf16 v[14:17], v[134:137], v[208:211], v[14:17]
	v_mfma_f32_16x16x32_bf16 v[10:13], v[142:145], v[208:211], v[10:13]
	s_setprio 0
	s_barrier
	s_add_i32 s4, s4, s70
	v_lshl_add_u64 v[130:131], v[236:237], 0, s[6:7]
	s_mov_b32 m0, s4
	s_nop 0
	global_load_lds_dwordx4 v[130:131], off
	v_lshl_add_u64 v[130:131], v[238:239], 0, s[6:7]
	s_add_i32 m0, s4, 0x2000
	s_nop 0
	global_load_lds_dwordx4 v[130:131], off
	s_waitcnt vmcnt(6)
	s_barrier
	s_setprio 1
	v_mfma_f32_16x16x32_bf16 v[54:57], v[212:215], v[158:161], v[54:57]
	v_mfma_f32_16x16x32_bf16 v[50:53], v[220:223], v[158:161], v[50:53]
	v_mfma_f32_16x16x32_bf16 v[38:41], v[212:215], v[166:169], v[38:41]
	v_mfma_f32_16x16x32_bf16 v[34:37], v[220:223], v[166:169], v[34:37]
	v_mfma_f32_16x16x32_bf16 v[22:25], v[212:215], v[174:177], v[22:25]
	v_mfma_f32_16x16x32_bf16 v[18:21], v[220:223], v[174:177], v[18:21]
	v_mfma_f32_16x16x32_bf16 v[6:9], v[212:215], v[182:185], v[6:9]
	v_mfma_f32_16x16x32_bf16 v[2:5], v[220:223], v[182:185], v[2:5]
	v_mfma_f32_16x16x32_bf16 v[54:57], v[216:219], v[162:165], v[54:57]
	v_mfma_f32_16x16x32_bf16 v[50:53], v[224:227], v[162:165], v[50:53]
	v_mfma_f32_16x16x32_bf16 v[38:41], v[216:219], v[170:173], v[38:41]
	v_mfma_f32_16x16x32_bf16 v[34:37], v[224:227], v[170:173], v[34:37]
	v_mfma_f32_16x16x32_bf16 v[22:25], v[216:219], v[178:181], v[22:25]
	v_mfma_f32_16x16x32_bf16 v[18:21], v[224:227], v[178:181], v[18:21]
	v_mfma_f32_16x16x32_bf16 v[6:9], v[216:219], v[208:211], v[6:9]
	v_mfma_f32_16x16x32_bf16 v[2:5], v[224:227], v[208:211], v[2:5]
	s_setprio 0
	s_add_u32 s0, s0, 0x100
	s_addc_u32 s1, s1, 0
	s_add_u32 s12, s12, 0x100
	s_addc_u32 s13, s13, 0
	s_cmp_ge_u32 s15, s75
	s_mov_b32 s4, s15
	s_barrier
	s_cbranch_scc1 .Lkexit_347

.Lkexit_347:
	v_mov_b32_e32 v130, v1
	v_mov_b32_e32 v131, v204
	s_lshl_b32 s5, s69, 8
	s_cmp_lg_u32 s69, s14
	v_lshl_add_u32 v140, v130, 4, v131
	s_mov_b64 s[0:1], -1
	s_cbranch_scc0 .LBB0_350
	s_add_i32 s4, s5, s76
	v_and_or_b32 v132, v140, 63, s4
	v_lshlrev_b32_e32 v162, 1, v140
	v_add_u32_e32 v141, s50, v132
	v_and_b32_e32 v132, 0xffffff80, v162
	v_add_u32_e32 v132, v141, v132
	v_ashrrev_i32_e32 v133, 31, v132
	v_readlane_b32 s0, v242, 3
	v_lshlrev_b64 v[132:133], 6, v[132:133]
	v_readlane_b32 s1, v242, 4
	v_lshl_add_u32 v164, v140, 2, s97
	s_nop 0
	v_lshl_add_u64 v[158:159], s[0:1], 0, v[132:133]
	global_load_dwordx4 v[132:135], v[158:159], off offset:48
	global_load_dwordx4 v[136:139], v[158:159], off offset:32
	global_load_dwordx4 v[142:145], v[158:159], off offset:16
	s_nop 0
	global_load_dwordx4 v[158:161], v[158:159], off
	v_add_u32_e32 v234, 0x80, v162
	v_and_b32_e32 v234, 0xffffff80, v234
	v_add_u32_e32 v234, v141, v234
	v_ashrrev_i32_e32 v235, 31, v234
	v_lshlrev_b64 v[234:235], 6, v[234:235]
	v_lshl_add_u64 v[232:233], s[0:1], 0, v[234:235]
	global_load_dwordx4 v[216:219], v[232:233], off offset:48
	global_load_dwordx4 v[220:223], v[232:233], off offset:32
	global_load_dwordx4 v[224:227], v[232:233], off offset:16
	global_load_dwordx4 v[228:231], v[232:233], off
	s_waitcnt vmcnt(4)
	v_add_f32_e32 v132, v132, v133
	v_add_f32_e32 v136, v136, v137
	v_add_f32_e32 v142, v142, v143
	v_add_f32_e32 v158, v158, v159
	v_add_f32_e32 v158, v160, v158
	v_add_f32_e32 v142, v144, v142
	v_add_f32_e32 v158, v161, v158
	v_add_f32_e32 v142, v145, v142
	v_add_f32_e32 v136, v138, v136
	v_add_f32_e32 v142, v158, v142
	v_add_f32_e32 v136, v139, v136
	v_add_f32_e32 v132, v134, v132
	v_add_f32_e32 v136, v142, v136
	v_add_f32_e32 v132, v135, v132
	v_add_f32_e32 v132, v136, v132
	v_fmamk_f32 v132, v132, 0x3a800000, v188
	v_rsq_f32_e32 v163, v132
	s_mov_b64 s[0:1], 0
	s_waitcnt vmcnt(0)
	v_add_f32_e32 v132, v216, v217
	v_add_f32_e32 v136, v220, v221
	v_add_f32_e32 v142, v224, v225
	v_add_f32_e32 v141, v228, v229
	v_add_f32_e32 v141, v230, v141
	v_add_f32_e32 v142, v226, v142
	v_add_f32_e32 v141, v231, v141
	v_add_f32_e32 v142, v227, v142
	v_add_f32_e32 v136, v222, v136
	v_add_f32_e32 v141, v141, v142
	v_add_f32_e32 v136, v223, v136
	v_add_f32_e32 v132, v218, v132
	v_add_f32_e32 v136, v141, v136
	v_add_f32_e32 v132, v219, v132
	v_add_f32_e32 v132, v136, v132
	v_fmamk_f32 v132, v132, 0x3a800000, v188
	v_rsq_f32_e32 v132, v132
	ds_write2st64_b32 v164, v163, v132 offset1:1
	s_waitcnt lgkmcnt(0)

.LBB0_663:
	s_add_u32 s0, s0, 0x80
	s_addc_u32 s1, s1, 0
	s_add_u32 s49, s4, 0x100
	s_addc_u32 s65, s5, 0
	s_mov_b32 s4, 0
	s_waitcnt lgkmcnt(0)
	s_waitcnt vmcnt(0)
	s_add_i32 s66, s4, 2
	s_add_u32 s18, s0, 0x80
	s_addc_u32 s5, s1, 0
	s_add_i32 s68, 0, 0x10000
	v_add_u32_e32 v150, s68, v153
	ds_read_b128 v[142:145], v150
	ds_read_b128 v[146:149], v150 offset:1024
	ds_read_b128 v[156:159], v150 offset:2048
	ds_read_b128 v[160:163], v150 offset:3072
	s_cmp_eq_u32 s43, s4
	s_cselect_b32 s4, s10, s18
	s_cselect_b32 s5, s11, s5
	s_cselect_b32 s19, s13, s65
	s_cselect_b32 s18, s12, s49
	v_lshl_add_u64 v[150:151], s[0:1], 0, v[138:139]
	s_add_i32 m0, s28, 0xc000
	ds_read_b128 v[164:167], v154
	ds_read_b128 v[168:171], v154 offset:1024
	ds_read_b128 v[172:175], v154 offset:2048
	ds_read_b128 v[176:179], v154 offset:3072
	ds_read_b128 v[180:183], v154 offset:4096
	ds_read_b128 v[204:207], v154 offset:5120
	ds_read_b128 v[208:211], v154 offset:6144
	ds_read_b128 v[212:215], v154 offset:7168
	global_load_lds_dwordx4 v[150:151], off
	v_lshl_add_u64 v[150:151], s[0:1], 0, v[140:141]
	s_add_i32 m0, s28, 0xe000
	s_nop 0
	global_load_lds_dwordx4 v[150:151], off
	s_waitcnt lgkmcnt(8)
	s_barrier
	s_waitcnt lgkmcnt(0)
	s_setprio 1
	s_waitcnt lgkmcnt(0)
	v_mfma_f32_16x16x32_bf16 v[126:129], v[142:145], v[164:167], 0
	v_mfma_f32_16x16x32_bf16 v[122:125], v[156:159], v[164:167], 0
	v_mfma_f32_16x16x32_bf16 v[110:113], v[142:145], v[172:175], 0
	v_mfma_f32_16x16x32_bf16 v[106:109], v[156:159], v[172:175], 0
	v_mfma_f32_16x16x32_bf16 v[94:97], v[142:145], v[180:183], 0
	v_mfma_f32_16x16x32_bf16 v[90:93], v[156:159], v[180:183], 0
	v_mfma_f32_16x16x32_bf16 v[78:81], v[142:145], v[208:211], 0
	v_mfma_f32_16x16x32_bf16 v[74:77], v[156:159], v[208:211], 0
	v_mfma_f32_16x16x32_bf16 v[126:129], v[146:149], v[168:171], v[126:129]
	v_mfma_f32_16x16x32_bf16 v[122:125], v[160:163], v[168:171], v[122:125]
	v_mfma_f32_16x16x32_bf16 v[110:113], v[146:149], v[176:179], v[110:113]
	v_mfma_f32_16x16x32_bf16 v[106:109], v[160:163], v[176:179], v[106:109]
	v_mfma_f32_16x16x32_bf16 v[94:97], v[146:149], v[204:207], v[94:97]
	v_mfma_f32_16x16x32_bf16 v[90:93], v[160:163], v[204:207], v[90:93]
	v_mfma_f32_16x16x32_bf16 v[78:81], v[146:149], v[212:215], v[78:81]
	v_mfma_f32_16x16x32_bf16 v[74:77], v[160:163], v[212:215], v[74:77]
	s_setprio 0
	s_barrier
	s_add_i32 s69, 0, 0x14000
	v_add_u32_e32 v150, s69, v153
	s_add_i32 s68, s68, s25
	ds_read_b128 v[216:219], v150
	ds_read_b128 v[220:223], v150 offset:1024
	ds_read_b128 v[224:227], v150 offset:2048
	ds_read_b128 v[228:231], v150 offset:3072
	v_lshl_add_u64 v[150:151], s[18:19], 0, v[132:133]
	s_mov_b32 m0, s68
	v_lshl_add_u64 v[184:185], s[18:19], 0, v[136:137]
	global_load_lds_dwordx4 v[150:151], off
	s_add_i32 m0, s68, 0x2000
	s_nop 0
	global_load_lds_dwordx4 v[184:185], off
	s_barrier
	s_waitcnt lgkmcnt(0)
	s_setprio 1
	s_waitcnt lgkmcnt(0)
	v_mfma_f32_16x16x32_bf16 v[118:121], v[216:219], v[164:167], 0
	v_mfma_f32_16x16x32_bf16 v[114:117], v[224:227], v[164:167], 0
	v_mfma_f32_16x16x32_bf16 v[102:105], v[216:219], v[172:175], 0
	v_mfma_f32_16x16x32_bf16 v[98:101], v[224:227], v[172:175], 0
	v_mfma_f32_16x16x32_bf16 v[86:89], v[216:219], v[180:183], 0
	v_mfma_f32_16x16x32_bf16 v[82:85], v[224:227], v[180:183], 0
	v_mfma_f32_16x16x32_bf16 v[70:73], v[216:219], v[208:211], 0
	v_mfma_f32_16x16x32_bf16 v[66:69], v[224:227], v[208:211], 0
	v_mfma_f32_16x16x32_bf16 v[118:121], v[220:223], v[168:171], v[118:121]
	v_mfma_f32_16x16x32_bf16 v[114:117], v[228:231], v[168:171], v[114:117]
	v_mfma_f32_16x16x32_bf16 v[102:105], v[220:223], v[176:179], v[102:105]
	v_mfma_f32_16x16x32_bf16 v[98:101], v[228:231], v[176:179], v[98:101]
	v_mfma_f32_16x16x32_bf16 v[86:89], v[220:223], v[204:207], v[86:89]
	v_mfma_f32_16x16x32_bf16 v[82:85], v[228:231], v[204:207], v[82:85]
	v_mfma_f32_16x16x32_bf16 v[70:73], v[220:223], v[212:215], v[70:73]
	v_mfma_f32_16x16x32_bf16 v[66:69], v[228:231], v[212:215], v[66:69]
	s_setprio 0
	s_mov_b32 m0, s28
	v_lshl_add_u64 v[232:233], s[4:5], 0, v[130:131]
	s_barrier
	ds_read_b128 v[164:167], v154 offset:16384
	ds_read_b128 v[168:171], v154 offset:17408
	ds_read_b128 v[172:175], v154 offset:18432
	ds_read_b128 v[176:179], v154 offset:19456
	ds_read_b128 v[180:183], v154 offset:20480
	ds_read_b128 v[204:207], v154 offset:21504
	ds_read_b128 v[208:211], v154 offset:22528
	ds_read_b128 v[212:215], v154 offset:23552
	global_load_lds_dwordx4 v[232:233], off
	v_lshl_add_u64 v[234:235], s[4:5], 0, v[134:135]
	s_mov_b32 m0, s29
	s_nop 0
	global_load_lds_dwordx4 v[234:235], off
	s_barrier
	s_waitcnt lgkmcnt(0)
	s_setprio 1
	s_waitcnt lgkmcnt(0)
	v_mfma_f32_16x16x32_bf16 v[62:65], v[142:145], v[164:167], 0
	v_mfma_f32_16x16x32_bf16 v[58:61], v[156:159], v[164:167], 0
	v_mfma_f32_16x16x32_bf16 v[46:49], v[142:145], v[172:175], 0
	v_mfma_f32_16x16x32_bf16 v[42:45], v[156:159], v[172:175], 0
	v_mfma_f32_16x16x32_bf16 v[30:33], v[142:145], v[180:183], 0
	v_mfma_f32_16x16x32_bf16 v[26:29], v[156:159], v[180:183], 0
	v_mfma_f32_16x16x32_bf16 v[14:17], v[142:145], v[208:211], 0
	v_mfma_f32_16x16x32_bf16 v[10:13], v[156:159], v[208:211], 0
	v_mfma_f32_16x16x32_bf16 v[62:65], v[146:149], v[168:171], v[62:65]
	v_mfma_f32_16x16x32_bf16 v[58:61], v[160:163], v[168:171], v[58:61]
	v_mfma_f32_16x16x32_bf16 v[46:49], v[146:149], v[176:179], v[46:49]
	v_mfma_f32_16x16x32_bf16 v[42:45], v[160:163], v[176:179], v[42:45]
	v_mfma_f32_16x16x32_bf16 v[30:33], v[146:149], v[204:207], v[30:33]
	v_mfma_f32_16x16x32_bf16 v[26:29], v[160:163], v[204:207], v[26:29]
	v_mfma_f32_16x16x32_bf16 v[14:17], v[146:149], v[212:215], v[14:17]
	v_mfma_f32_16x16x32_bf16 v[10:13], v[160:163], v[212:215], v[10:13]
	s_setprio 0
	s_barrier
	s_add_u32 s18, s18, s14
	s_addc_u32 s19, s19, 0
	s_add_i32 s68, s69, s25
	v_lshl_add_u64 v[236:237], s[18:19], 0, v[132:133]
	s_mov_b32 m0, s68
	v_lshl_add_u64 v[238:239], s[18:19], 0, v[136:137]
	global_load_lds_dwordx4 v[236:237], off
	s_add_i32 m0, s68, 0x2000
	s_nop 0
	global_load_lds_dwordx4 v[238:239], off
	s_waitcnt vmcnt(6)
	s_barrier
	s_setprio 1
	v_mfma_f32_16x16x32_bf16 v[54:57], v[216:219], v[164:167], 0
	v_mfma_f32_16x16x32_bf16 v[50:53], v[224:227], v[164:167], 0
	v_mfma_f32_16x16x32_bf16 v[38:41], v[216:219], v[172:175], 0
	v_mfma_f32_16x16x32_bf16 v[34:37], v[224:227], v[172:175], 0
	v_mfma_f32_16x16x32_bf16 v[22:25], v[216:219], v[180:183], 0
	v_mfma_f32_16x16x32_bf16 v[18:21], v[224:227], v[180:183], 0
	v_mfma_f32_16x16x32_bf16 v[6:9], v[216:219], v[208:211], 0
	v_mfma_f32_16x16x32_bf16 v[2:5], v[224:227], v[208:211], 0
	v_mfma_f32_16x16x32_bf16 v[54:57], v[220:223], v[168:171], v[54:57]
	v_mfma_f32_16x16x32_bf16 v[50:53], v[228:231], v[168:171], v[50:53]
	v_mfma_f32_16x16x32_bf16 v[38:41], v[220:223], v[176:179], v[38:41]
	v_mfma_f32_16x16x32_bf16 v[34:37], v[228:231], v[176:179], v[34:37]
	v_mfma_f32_16x16x32_bf16 v[22:25], v[220:223], v[204:207], v[22:25]
	v_mfma_f32_16x16x32_bf16 v[18:21], v[228:231], v[204:207], v[18:21]
	v_mfma_f32_16x16x32_bf16 v[6:9], v[220:223], v[212:215], v[6:9]
	v_mfma_f32_16x16x32_bf16 v[2:5], v[228:231], v[212:215], v[2:5]
	s_setprio 0
	s_add_i32 s18, 0, 0x18000
	v_add_u32_e32 v155, s18, v153
	s_barrier
	ds_read_b128 v[142:145], v155
	ds_read_b128 v[146:149], v155 offset:1024
	ds_read_b128 v[156:159], v155 offset:2048
	ds_read_b128 v[160:163], v155 offset:3072
	s_add_u32 s4, s4, s14
	s_addc_u32 s5, s5, 0
	s_mov_b32 m0, s31
	v_lshl_add_u64 v[216:217], s[4:5], 0, v[130:131]
	ds_read_b128 v[164:167], v154 offset:32768
	ds_read_b128 v[168:171], v154 offset:33792
	ds_read_b128 v[172:175], v154 offset:34816
	ds_read_b128 v[176:179], v154 offset:35840
	ds_read_b128 v[180:183], v154 offset:36864
	ds_read_b128 v[204:207], v154 offset:37888
	ds_read_b128 v[208:211], v154 offset:38912
	ds_read_b128 v[212:215], v154 offset:39936
	global_load_lds_dwordx4 v[216:217], off
	v_lshl_add_u64 v[216:217], s[4:5], 0, v[134:135]
	s_mov_b32 m0, s34
	s_nop 0
	global_load_lds_dwordx4 v[216:217], off
	s_waitcnt lgkmcnt(8)
	s_barrier
	s_waitcnt lgkmcnt(0)
	s_setprio 1
	s_waitcnt lgkmcnt(0)
	v_mfma_f32_16x16x32_bf16 v[126:129], v[142:145], v[164:167], v[126:129]
	v_mfma_f32_16x16x32_bf16 v[122:125], v[156:159], v[164:167], v[122:125]
	v_mfma_f32_16x16x32_bf16 v[110:113], v[142:145], v[172:175], v[110:113]
	v_mfma_f32_16x16x32_bf16 v[106:109], v[156:159], v[172:175], v[106:109]
	v_mfma_f32_16x16x32_bf16 v[94:97], v[142:145], v[180:183], v[94:97]
	v_mfma_f32_16x16x32_bf16 v[90:93], v[156:159], v[180:183], v[90:93]
	v_mfma_f32_16x16x32_bf16 v[78:81], v[142:145], v[208:211], v[78:81]
	v_mfma_f32_16x16x32_bf16 v[74:77], v[156:159], v[208:211], v[74:77]
	v_mfma_f32_16x16x32_bf16 v[126:129], v[146:149], v[168:171], v[126:129]
	v_mfma_f32_16x16x32_bf16 v[122:125], v[160:163], v[168:171], v[122:125]
	v_mfma_f32_16x16x32_bf16 v[110:113], v[146:149], v[176:179], v[110:113]
	v_mfma_f32_16x16x32_bf16 v[106:109], v[160:163], v[176:179], v[106:109]
	v_mfma_f32_16x16x32_bf16 v[94:97], v[146:149], v[204:207], v[94:97]
	v_mfma_f32_16x16x32_bf16 v[90:93], v[160:163], v[204:207], v[90:93]
	v_mfma_f32_16x16x32_bf16 v[78:81], v[146:149], v[212:215], v[78:81]
	v_mfma_f32_16x16x32_bf16 v[74:77], v[160:163], v[212:215], v[74:77]
	s_setprio 0
	s_barrier
	s_add_i32 s4, 0, 0x1c000
	s_add_i32 s5, s18, s25
	v_add_u32_e32 v155, s4, v153
	v_lshl_add_u64 v[150:151], v[150:151], 0, s[6:7]
	s_mov_b32 m0, s5
	ds_read_b128 v[216:219], v155
	ds_read_b128 v[220:223], v155 offset:1024
	ds_read_b128 v[224:227], v155 offset:2048
	ds_read_b128 v[228:231], v155 offset:3072
	global_load_lds_dwordx4 v[150:151], off
	v_lshl_add_u64 v[150:151], v[184:185], 0, s[6:7]
	s_add_i32 m0, s5, 0x2000
	s_nop 0
	global_load_lds_dwordx4 v[150:151], off
	s_barrier
	s_waitcnt lgkmcnt(0)
	s_setprio 1
	s_waitcnt lgkmcnt(0)
	v_mfma_f32_16x16x32_bf16 v[118:121], v[216:219], v[164:167], v[118:121]
	v_mfma_f32_16x16x32_bf16 v[114:117], v[224:227], v[164:167], v[114:117]
	v_mfma_f32_16x16x32_bf16 v[102:105], v[216:219], v[172:175], v[102:105]
	v_mfma_f32_16x16x32_bf16 v[98:101], v[224:227], v[172:175], v[98:101]
	v_mfma_f32_16x16x32_bf16 v[86:89], v[216:219], v[180:183], v[86:89]
	v_mfma_f32_16x16x32_bf16 v[82:85], v[224:227], v[180:183], v[82:85]
	v_mfma_f32_16x16x32_bf16 v[70:73], v[216:219], v[208:211], v[70:73]
	v_mfma_f32_16x16x32_bf16 v[66:69], v[224:227], v[208:211], v[66:69]
	v_mfma_f32_16x16x32_bf16 v[118:121], v[220:223], v[168:171], v[118:121]
	v_mfma_f32_16x16x32_bf16 v[114:117], v[228:231], v[168:171], v[114:117]
	v_mfma_f32_16x16x32_bf16 v[102:105], v[220:223], v[176:179], v[102:105]
	v_mfma_f32_16x16x32_bf16 v[98:101], v[228:231], v[176:179], v[98:101]
	v_mfma_f32_16x16x32_bf16 v[86:89], v[220:223], v[204:207], v[86:89]
	v_mfma_f32_16x16x32_bf16 v[82:85], v[228:231], v[204:207], v[82:85]
	v_mfma_f32_16x16x32_bf16 v[70:73], v[220:223], v[212:215], v[70:73]
	v_mfma_f32_16x16x32_bf16 v[66:69], v[228:231], v[212:215], v[66:69]
	s_setprio 0
	s_mov_b32 m0, s41
	v_lshl_add_u64 v[150:151], v[232:233], 0, s[6:7]
	s_barrier
	ds_read_b128 v[164:167], v154 offset:49152
	ds_read_b128 v[168:171], v154 offset:50176
	ds_read_b128 v[172:175], v154 offset:51200
	ds_read_b128 v[176:179], v154 offset:52224
	ds_read_b128 v[180:183], v154 offset:53248
	ds_read_b128 v[204:207], v154 offset:54272
	ds_read_b128 v[208:211], v154 offset:55296
	ds_read_b128 v[212:215], v154 offset:56320
	global_load_lds_dwordx4 v[150:151], off
	v_lshl_add_u64 v[150:151], v[234:235], 0, s[6:7]
	s_mov_b32 m0, s42
	s_nop 0
	global_load_lds_dwordx4 v[150:151], off
	s_barrier
	s_waitcnt lgkmcnt(0)
	s_setprio 1
	s_waitcnt lgkmcnt(0)
	v_mfma_f32_16x16x32_bf16 v[62:65], v[142:145], v[164:167], v[62:65]
	v_mfma_f32_16x16x32_bf16 v[58:61], v[156:159], v[164:167], v[58:61]
	v_mfma_f32_16x16x32_bf16 v[46:49], v[142:145], v[172:175], v[46:49]
	v_mfma_f32_16x16x32_bf16 v[42:45], v[156:159], v[172:175], v[42:45]
	v_mfma_f32_16x16x32_bf16 v[30:33], v[142:145], v[180:183], v[30:33]
	v_mfma_f32_16x16x32_bf16 v[26:29], v[156:159], v[180:183], v[26:29]
	v_mfma_f32_16x16x32_bf16 v[14:17], v[142:145], v[208:211], v[14:17]
	v_mfma_f32_16x16x32_bf16 v[10:13], v[156:159], v[208:211], v[10:13]
	v_mfma_f32_16x16x32_bf16 v[62:65], v[146:149], v[168:171], v[62:65]
	v_mfma_f32_16x16x32_bf16 v[58:61], v[160:163], v[168:171], v[58:61]
	v_mfma_f32_16x16x32_bf16 v[46:49], v[146:149], v[176:179], v[46:49]
	v_mfma_f32_16x16x32_bf16 v[42:45], v[160:163], v[176:179], v[42:45]
	v_mfma_f32_16x16x32_bf16 v[30:33], v[146:149], v[204:207], v[30:33]
	v_mfma_f32_16x16x32_bf16 v[26:29], v[160:163], v[204:207], v[26:29]
	v_mfma_f32_16x16x32_bf16 v[14:17], v[146:149], v[212:215], v[14:17]
	v_mfma_f32_16x16x32_bf16 v[10:13], v[160:163], v[212:215], v[10:13]
	s_setprio 0
	s_barrier
	s_add_i32 s4, s4, s25
	v_lshl_add_u64 v[142:143], v[236:237], 0, s[6:7]
	s_mov_b32 m0, s4
	s_nop 0
	global_load_lds_dwordx4 v[142:143], off
	v_lshl_add_u64 v[142:143], v[238:239], 0, s[6:7]
	s_add_i32 m0, s4, 0x2000
	s_nop 0
	global_load_lds_dwordx4 v[142:143], off
	s_waitcnt vmcnt(6)
	s_barrier
	s_setprio 1
	v_mfma_f32_16x16x32_bf16 v[54:57], v[216:219], v[164:167], v[54:57]
	v_mfma_f32_16x16x32_bf16 v[50:53], v[224:227], v[164:167], v[50:53]
	v_mfma_f32_16x16x32_bf16 v[38:41], v[216:219], v[172:175], v[38:41]
	v_mfma_f32_16x16x32_bf16 v[34:37], v[224:227], v[172:175], v[34:37]
	v_mfma_f32_16x16x32_bf16 v[22:25], v[216:219], v[180:183], v[22:25]
	v_mfma_f32_16x16x32_bf16 v[18:21], v[224:227], v[180:183], v[18:21]
	v_mfma_f32_16x16x32_bf16 v[6:9], v[216:219], v[208:211], v[6:9]
	v_mfma_f32_16x16x32_bf16 v[2:5], v[224:227], v[208:211], v[2:5]
	v_mfma_f32_16x16x32_bf16 v[54:57], v[220:223], v[168:171], v[54:57]
	v_mfma_f32_16x16x32_bf16 v[50:53], v[228:231], v[168:171], v[50:53]
	v_mfma_f32_16x16x32_bf16 v[38:41], v[220:223], v[176:179], v[38:41]
	v_mfma_f32_16x16x32_bf16 v[34:37], v[228:231], v[176:179], v[34:37]
	v_mfma_f32_16x16x32_bf16 v[22:25], v[220:223], v[204:207], v[22:25]
	v_mfma_f32_16x16x32_bf16 v[18:21], v[228:231], v[204:207], v[18:21]
	v_mfma_f32_16x16x32_bf16 v[6:9], v[220:223], v[212:215], v[6:9]
	v_mfma_f32_16x16x32_bf16 v[2:5], v[228:231], v[212:215], v[2:5]
	s_setprio 0
	s_add_u32 s0, s0, 0x100
	s_addc_u32 s1, s1, 0
	s_add_u32 s49, s49, 0x100
	s_addc_u32 s65, s65, 0
	s_cmp_ge_u32 s66, s35
	s_mov_b32 s4, s66
	s_barrier
	s_cbranch_scc1 .Lkexit_664

.Lkexit_664:
	v_mov_b32_e32 v150, v1
	v_mov_b32_e32 v151, v152
	s_cmp_lg_u32 s45, s48
	s_mov_b64 s[0:1], -1
	s_cbranch_scc0 .LBB0_667
	s_lshl_b32 s0, s45, 8
	v_lshl_add_u32 v155, v150, 4, v151
	s_add_i32 s4, s0, s40
	v_and_or_b32 v142, v155, 63, s4
	v_lshlrev_b32_e32 v165, 1, v155
	v_add_u32_e32 v164, s50, v142
	v_and_b32_e32 v142, 0xffffff80, v165
	v_add_u32_e32 v142, v164, v142
	v_ashrrev_i32_e32 v143, 31, v142
	v_readlane_b32 s0, v242, 3
	v_lshlrev_b64 v[142:143], 6, v[142:143]
	v_readlane_b32 s1, v242, 4
	v_lshl_add_u32 v155, v155, 2, s44
	s_nop 0
	v_lshl_add_u64 v[160:161], s[0:1], 0, v[142:143]
	global_load_dwordx4 v[142:145], v[160:161], off offset:48
	global_load_dwordx4 v[146:149], v[160:161], off offset:32
	global_load_dwordx4 v[156:159], v[160:161], off offset:16
	s_nop 0
	global_load_dwordx4 v[160:163], v[160:161], off
	v_add_u32_e32 v222, 0x80, v165
	v_and_b32_e32 v222, 0xffffff80, v222
	v_add_u32_e32 v222, v164, v222
	v_ashrrev_i32_e32 v223, 31, v222
	v_lshlrev_b64 v[222:223], 6, v[222:223]
	v_lshl_add_u64 v[220:221], s[0:1], 0, v[222:223]
	global_load_dwordx4 v[204:207], v[220:221], off offset:48
	global_load_dwordx4 v[208:211], v[220:221], off offset:32
	global_load_dwordx4 v[212:215], v[220:221], off offset:16
	global_load_dwordx4 v[216:219], v[220:221], off
	s_waitcnt vmcnt(4)
	v_add_f32_e32 v142, v142, v143
	v_add_f32_e32 v146, v146, v147
	v_add_f32_e32 v156, v156, v157
	v_add_f32_e32 v160, v160, v161
	v_add_f32_e32 v160, v162, v160
	v_add_f32_e32 v156, v158, v156
	v_add_f32_e32 v160, v163, v160
	v_add_f32_e32 v156, v159, v156
	v_add_f32_e32 v146, v148, v146
	v_add_f32_e32 v156, v160, v156
	v_add_f32_e32 v146, v149, v146
	v_add_f32_e32 v142, v144, v142
	v_add_f32_e32 v146, v156, v146
	v_add_f32_e32 v142, v145, v142
	v_add_f32_e32 v142, v146, v142
	v_fmamk_f32 v142, v142, 0x3a800000, v188
	v_rsq_f32_e32 v166, v142
	s_mov_b64 s[0:1], 0
	s_waitcnt vmcnt(0)
	v_add_f32_e32 v142, v204, v205
	v_add_f32_e32 v146, v208, v209
	v_add_f32_e32 v156, v212, v213
	v_add_f32_e32 v160, v216, v217
	v_add_f32_e32 v160, v218, v160
	v_add_f32_e32 v156, v214, v156
	v_add_f32_e32 v160, v219, v160
	v_add_f32_e32 v156, v215, v156
	v_add_f32_e32 v146, v210, v146
	v_add_f32_e32 v156, v160, v156
	v_add_f32_e32 v146, v211, v146
	v_add_f32_e32 v142, v206, v142
	v_add_f32_e32 v146, v156, v146
	v_add_f32_e32 v142, v207, v142
	v_add_f32_e32 v142, v146, v142
	v_fmamk_f32 v142, v142, 0x3a800000, v188
	v_rsq_f32_e32 v142, v142
	ds_write2st64_b32 v155, v166, v142 offset1:1
	s_waitcnt lgkmcnt(0)

.LBB0_697:
	s_add_u32 s0, s0, 0x80
	s_addc_u32 s1, s1, 0
	s_add_u32 s48, s4, 0x100
	s_addc_u32 s49, s5, 0
	s_mov_b32 s4, 0
	s_waitcnt lgkmcnt(0)
	s_waitcnt vmcnt(0)
	s_add_i32 s65, s4, 2
	s_add_u32 s18, s0, 0x80
	s_addc_u32 s5, s1, 0
	s_add_i32 s66, 0, 0x10000
	v_add_u32_e32 v146, s66, v149
	ds_read_b128 v[142:145], v146
	ds_read_b128 v[152:155], v146 offset:1024
	ds_read_b128 v[156:159], v146 offset:2048
	ds_read_b128 v[160:163], v146 offset:3072
	s_cmp_eq_u32 s34, s4
	s_cselect_b32 s4, s10, s18
	s_cselect_b32 s5, s11, s5
	s_cselect_b32 s19, s13, s49
	s_cselect_b32 s18, s12, s48
	v_lshl_add_u64 v[146:147], s[0:1], 0, v[138:139]
	s_add_i32 m0, s22, 0xc000
	ds_read_b128 v[164:167], v150
	ds_read_b128 v[168:171], v150 offset:1024
	ds_read_b128 v[172:175], v150 offset:2048
	ds_read_b128 v[176:179], v150 offset:3072
	ds_read_b128 v[180:183], v150 offset:4096
	ds_read_b128 v[204:207], v150 offset:5120
	ds_read_b128 v[208:211], v150 offset:6144
	ds_read_b128 v[212:215], v150 offset:7168
	global_load_lds_dwordx4 v[146:147], off
	v_lshl_add_u64 v[146:147], s[0:1], 0, v[140:141]
	s_add_i32 m0, s22, 0xe000
	s_nop 0
	global_load_lds_dwordx4 v[146:147], off
	s_waitcnt lgkmcnt(8)
	s_barrier
	s_waitcnt lgkmcnt(0)
	s_setprio 1
	s_waitcnt lgkmcnt(0)
	v_mfma_f32_16x16x32_bf16 v[126:129], v[142:145], v[164:167], 0
	v_mfma_f32_16x16x32_bf16 v[122:125], v[156:159], v[164:167], 0
	v_mfma_f32_16x16x32_bf16 v[110:113], v[142:145], v[172:175], 0
	v_mfma_f32_16x16x32_bf16 v[106:109], v[156:159], v[172:175], 0
	v_mfma_f32_16x16x32_bf16 v[94:97], v[142:145], v[180:183], 0
	v_mfma_f32_16x16x32_bf16 v[90:93], v[156:159], v[180:183], 0
	v_mfma_f32_16x16x32_bf16 v[78:81], v[142:145], v[208:211], 0
	v_mfma_f32_16x16x32_bf16 v[74:77], v[156:159], v[208:211], 0
	v_mfma_f32_16x16x32_bf16 v[126:129], v[152:155], v[168:171], v[126:129]
	v_mfma_f32_16x16x32_bf16 v[122:125], v[160:163], v[168:171], v[122:125]
	v_mfma_f32_16x16x32_bf16 v[110:113], v[152:155], v[176:179], v[110:113]
	v_mfma_f32_16x16x32_bf16 v[106:109], v[160:163], v[176:179], v[106:109]
	v_mfma_f32_16x16x32_bf16 v[94:97], v[152:155], v[204:207], v[94:97]
	v_mfma_f32_16x16x32_bf16 v[90:93], v[160:163], v[204:207], v[90:93]
	v_mfma_f32_16x16x32_bf16 v[78:81], v[152:155], v[212:215], v[78:81]
	v_mfma_f32_16x16x32_bf16 v[74:77], v[160:163], v[212:215], v[74:77]
	s_setprio 0
	s_barrier
	s_add_i32 s67, 0, 0x14000
	v_add_u32_e32 v146, s67, v149
	s_add_i32 s66, s66, s21
	ds_read_b128 v[216:219], v146
	ds_read_b128 v[220:223], v146 offset:1024
	ds_read_b128 v[224:227], v146 offset:2048
	ds_read_b128 v[228:231], v146 offset:3072
	v_lshl_add_u64 v[146:147], s[18:19], 0, v[132:133]
	s_mov_b32 m0, s66
	v_lshl_add_u64 v[184:185], s[18:19], 0, v[136:137]
	global_load_lds_dwordx4 v[146:147], off
	s_add_i32 m0, s66, 0x2000
	s_nop 0
	global_load_lds_dwordx4 v[184:185], off
	s_barrier
	s_waitcnt lgkmcnt(0)
	s_setprio 1
	s_waitcnt lgkmcnt(0)
	v_mfma_f32_16x16x32_bf16 v[118:121], v[216:219], v[164:167], 0
	v_mfma_f32_16x16x32_bf16 v[114:117], v[224:227], v[164:167], 0
	v_mfma_f32_16x16x32_bf16 v[102:105], v[216:219], v[172:175], 0
	v_mfma_f32_16x16x32_bf16 v[98:101], v[224:227], v[172:175], 0
	v_mfma_f32_16x16x32_bf16 v[86:89], v[216:219], v[180:183], 0
	v_mfma_f32_16x16x32_bf16 v[82:85], v[224:227], v[180:183], 0
	v_mfma_f32_16x16x32_bf16 v[70:73], v[216:219], v[208:211], 0
	v_mfma_f32_16x16x32_bf16 v[66:69], v[224:227], v[208:211], 0
	v_mfma_f32_16x16x32_bf16 v[118:121], v[220:223], v[168:171], v[118:121]
	v_mfma_f32_16x16x32_bf16 v[114:117], v[228:231], v[168:171], v[114:117]
	v_mfma_f32_16x16x32_bf16 v[102:105], v[220:223], v[176:179], v[102:105]
	v_mfma_f32_16x16x32_bf16 v[98:101], v[228:231], v[176:179], v[98:101]
	v_mfma_f32_16x16x32_bf16 v[86:89], v[220:223], v[204:207], v[86:89]
	v_mfma_f32_16x16x32_bf16 v[82:85], v[228:231], v[204:207], v[82:85]
	v_mfma_f32_16x16x32_bf16 v[70:73], v[220:223], v[212:215], v[70:73]
	v_mfma_f32_16x16x32_bf16 v[66:69], v[228:231], v[212:215], v[66:69]
	s_setprio 0
	s_mov_b32 m0, s22
	v_lshl_add_u64 v[232:233], s[4:5], 0, v[130:131]
	s_barrier
	ds_read_b128 v[164:167], v150 offset:16384
	ds_read_b128 v[168:171], v150 offset:17408
	ds_read_b128 v[172:175], v150 offset:18432
	ds_read_b128 v[176:179], v150 offset:19456
	ds_read_b128 v[180:183], v150 offset:20480
	ds_read_b128 v[204:207], v150 offset:21504
	ds_read_b128 v[208:211], v150 offset:22528
	ds_read_b128 v[212:215], v150 offset:23552
	global_load_lds_dwordx4 v[232:233], off
	v_lshl_add_u64 v[234:235], s[4:5], 0, v[134:135]
	s_mov_b32 m0, s23
	s_nop 0
	global_load_lds_dwordx4 v[234:235], off
	s_barrier
	s_waitcnt lgkmcnt(0)
	s_setprio 1
	s_waitcnt lgkmcnt(0)
	v_mfma_f32_16x16x32_bf16 v[62:65], v[142:145], v[164:167], 0
	v_mfma_f32_16x16x32_bf16 v[58:61], v[156:159], v[164:167], 0
	v_mfma_f32_16x16x32_bf16 v[46:49], v[142:145], v[172:175], 0
	v_mfma_f32_16x16x32_bf16 v[42:45], v[156:159], v[172:175], 0
	v_mfma_f32_16x16x32_bf16 v[30:33], v[142:145], v[180:183], 0
	v_mfma_f32_16x16x32_bf16 v[26:29], v[156:159], v[180:183], 0
	v_mfma_f32_16x16x32_bf16 v[14:17], v[142:145], v[208:211], 0
	v_mfma_f32_16x16x32_bf16 v[10:13], v[156:159], v[208:211], 0
	v_mfma_f32_16x16x32_bf16 v[62:65], v[152:155], v[168:171], v[62:65]
	v_mfma_f32_16x16x32_bf16 v[58:61], v[160:163], v[168:171], v[58:61]
	v_mfma_f32_16x16x32_bf16 v[46:49], v[152:155], v[176:179], v[46:49]
	v_mfma_f32_16x16x32_bf16 v[42:45], v[160:163], v[176:179], v[42:45]
	v_mfma_f32_16x16x32_bf16 v[30:33], v[152:155], v[204:207], v[30:33]
	v_mfma_f32_16x16x32_bf16 v[26:29], v[160:163], v[204:207], v[26:29]
	v_mfma_f32_16x16x32_bf16 v[14:17], v[152:155], v[212:215], v[14:17]
	v_mfma_f32_16x16x32_bf16 v[10:13], v[160:163], v[212:215], v[10:13]
	s_setprio 0
	s_barrier
	s_add_u32 s18, s18, s2
	s_addc_u32 s19, s19, 0
	s_add_i32 s66, s67, s21
	v_lshl_add_u64 v[236:237], s[18:19], 0, v[132:133]
	s_mov_b32 m0, s66
	v_lshl_add_u64 v[238:239], s[18:19], 0, v[136:137]
	global_load_lds_dwordx4 v[236:237], off
	s_add_i32 m0, s66, 0x2000
	s_nop 0
	global_load_lds_dwordx4 v[238:239], off
	s_waitcnt vmcnt(6)
	s_barrier
	s_setprio 1
	v_mfma_f32_16x16x32_bf16 v[54:57], v[216:219], v[164:167], 0
	v_mfma_f32_16x16x32_bf16 v[50:53], v[224:227], v[164:167], 0
	v_mfma_f32_16x16x32_bf16 v[38:41], v[216:219], v[172:175], 0
	v_mfma_f32_16x16x32_bf16 v[34:37], v[224:227], v[172:175], 0
	v_mfma_f32_16x16x32_bf16 v[22:25], v[216:219], v[180:183], 0
	v_mfma_f32_16x16x32_bf16 v[18:21], v[224:227], v[180:183], 0
	v_mfma_f32_16x16x32_bf16 v[6:9], v[216:219], v[208:211], 0
	v_mfma_f32_16x16x32_bf16 v[2:5], v[224:227], v[208:211], 0
	v_mfma_f32_16x16x32_bf16 v[54:57], v[220:223], v[168:171], v[54:57]
	v_mfma_f32_16x16x32_bf16 v[50:53], v[228:231], v[168:171], v[50:53]
	v_mfma_f32_16x16x32_bf16 v[38:41], v[220:223], v[176:179], v[38:41]
	v_mfma_f32_16x16x32_bf16 v[34:37], v[228:231], v[176:179], v[34:37]
	v_mfma_f32_16x16x32_bf16 v[22:25], v[220:223], v[204:207], v[22:25]
	v_mfma_f32_16x16x32_bf16 v[18:21], v[228:231], v[204:207], v[18:21]
	v_mfma_f32_16x16x32_bf16 v[6:9], v[220:223], v[212:215], v[6:9]
	v_mfma_f32_16x16x32_bf16 v[2:5], v[228:231], v[212:215], v[2:5]
	s_setprio 0
	s_add_i32 s18, 0, 0x18000
	v_add_u32_e32 v151, s18, v149
	s_barrier
	ds_read_b128 v[142:145], v151
	ds_read_b128 v[152:155], v151 offset:1024
	ds_read_b128 v[156:159], v151 offset:2048
	ds_read_b128 v[160:163], v151 offset:3072
	s_add_u32 s4, s4, s2
	s_addc_u32 s5, s5, 0
	s_mov_b32 m0, s24
	v_lshl_add_u64 v[216:217], s[4:5], 0, v[130:131]
	ds_read_b128 v[164:167], v150 offset:32768
	ds_read_b128 v[168:171], v150 offset:33792
	ds_read_b128 v[172:175], v150 offset:34816
	ds_read_b128 v[176:179], v150 offset:35840
	ds_read_b128 v[180:183], v150 offset:36864
	ds_read_b128 v[204:207], v150 offset:37888
	ds_read_b128 v[208:211], v150 offset:38912
	ds_read_b128 v[212:215], v150 offset:39936
	global_load_lds_dwordx4 v[216:217], off
	v_lshl_add_u64 v[216:217], s[4:5], 0, v[134:135]
	s_mov_b32 m0, s25
	s_nop 0
	global_load_lds_dwordx4 v[216:217], off
	s_waitcnt lgkmcnt(8)
	s_barrier
	s_waitcnt lgkmcnt(0)
	s_setprio 1
	s_waitcnt lgkmcnt(0)
	v_mfma_f32_16x16x32_bf16 v[126:129], v[142:145], v[164:167], v[126:129]
	v_mfma_f32_16x16x32_bf16 v[122:125], v[156:159], v[164:167], v[122:125]
	v_mfma_f32_16x16x32_bf16 v[110:113], v[142:145], v[172:175], v[110:113]
	v_mfma_f32_16x16x32_bf16 v[106:109], v[156:159], v[172:175], v[106:109]
	v_mfma_f32_16x16x32_bf16 v[94:97], v[142:145], v[180:183], v[94:97]
	v_mfma_f32_16x16x32_bf16 v[90:93], v[156:159], v[180:183], v[90:93]
	v_mfma_f32_16x16x32_bf16 v[78:81], v[142:145], v[208:211], v[78:81]
	v_mfma_f32_16x16x32_bf16 v[74:77], v[156:159], v[208:211], v[74:77]
	v_mfma_f32_16x16x32_bf16 v[126:129], v[152:155], v[168:171], v[126:129]
	v_mfma_f32_16x16x32_bf16 v[122:125], v[160:163], v[168:171], v[122:125]
	v_mfma_f32_16x16x32_bf16 v[110:113], v[152:155], v[176:179], v[110:113]
	v_mfma_f32_16x16x32_bf16 v[106:109], v[160:163], v[176:179], v[106:109]
	v_mfma_f32_16x16x32_bf16 v[94:97], v[152:155], v[204:207], v[94:97]
	v_mfma_f32_16x16x32_bf16 v[90:93], v[160:163], v[204:207], v[90:93]
	v_mfma_f32_16x16x32_bf16 v[78:81], v[152:155], v[212:215], v[78:81]
	v_mfma_f32_16x16x32_bf16 v[74:77], v[160:163], v[212:215], v[74:77]
	s_setprio 0
	s_barrier
	s_add_i32 s4, 0, 0x1c000
	s_add_i32 s5, s18, s21
	v_add_u32_e32 v151, s4, v149
	v_lshl_add_u64 v[146:147], v[146:147], 0, s[6:7]
	s_mov_b32 m0, s5
	ds_read_b128 v[216:219], v151
	ds_read_b128 v[220:223], v151 offset:1024
	ds_read_b128 v[224:227], v151 offset:2048
	ds_read_b128 v[228:231], v151 offset:3072
	global_load_lds_dwordx4 v[146:147], off
	v_lshl_add_u64 v[146:147], v[184:185], 0, s[6:7]
	s_add_i32 m0, s5, 0x2000
	s_nop 0
	global_load_lds_dwordx4 v[146:147], off
	s_barrier
	s_waitcnt lgkmcnt(0)
	s_setprio 1
	s_waitcnt lgkmcnt(0)
	v_mfma_f32_16x16x32_bf16 v[118:121], v[216:219], v[164:167], v[118:121]
	v_mfma_f32_16x16x32_bf16 v[114:117], v[224:227], v[164:167], v[114:117]
	v_mfma_f32_16x16x32_bf16 v[102:105], v[216:219], v[172:175], v[102:105]
	v_mfma_f32_16x16x32_bf16 v[98:101], v[224:227], v[172:175], v[98:101]
	v_mfma_f32_16x16x32_bf16 v[86:89], v[216:219], v[180:183], v[86:89]
	v_mfma_f32_16x16x32_bf16 v[82:85], v[224:227], v[180:183], v[82:85]
	v_mfma_f32_16x16x32_bf16 v[70:73], v[216:219], v[208:211], v[70:73]
	v_mfma_f32_16x16x32_bf16 v[66:69], v[224:227], v[208:211], v[66:69]
	v_mfma_f32_16x16x32_bf16 v[118:121], v[220:223], v[168:171], v[118:121]
	v_mfma_f32_16x16x32_bf16 v[114:117], v[228:231], v[168:171], v[114:117]
	v_mfma_f32_16x16x32_bf16 v[102:105], v[220:223], v[176:179], v[102:105]
	v_mfma_f32_16x16x32_bf16 v[98:101], v[228:231], v[176:179], v[98:101]
	v_mfma_f32_16x16x32_bf16 v[86:89], v[220:223], v[204:207], v[86:89]
	v_mfma_f32_16x16x32_bf16 v[82:85], v[228:231], v[204:207], v[82:85]
	v_mfma_f32_16x16x32_bf16 v[70:73], v[220:223], v[212:215], v[70:73]
	v_mfma_f32_16x16x32_bf16 v[66:69], v[228:231], v[212:215], v[66:69]
	s_setprio 0
	s_mov_b32 m0, s30
	v_lshl_add_u64 v[146:147], v[232:233], 0, s[6:7]
	s_barrier
	ds_read_b128 v[164:167], v150 offset:49152
	ds_read_b128 v[168:171], v150 offset:50176
	ds_read_b128 v[172:175], v150 offset:51200
	ds_read_b128 v[176:179], v150 offset:52224
	ds_read_b128 v[180:183], v150 offset:53248
	ds_read_b128 v[204:207], v150 offset:54272
	ds_read_b128 v[208:211], v150 offset:55296
	ds_read_b128 v[212:215], v150 offset:56320
	global_load_lds_dwordx4 v[146:147], off
	v_lshl_add_u64 v[146:147], v[234:235], 0, s[6:7]
	s_mov_b32 m0, s31
	s_nop 0
	global_load_lds_dwordx4 v[146:147], off
	s_barrier
	s_waitcnt lgkmcnt(0)
	s_setprio 1
	s_waitcnt lgkmcnt(0)
	v_mfma_f32_16x16x32_bf16 v[62:65], v[142:145], v[164:167], v[62:65]
	v_mfma_f32_16x16x32_bf16 v[58:61], v[156:159], v[164:167], v[58:61]
	v_mfma_f32_16x16x32_bf16 v[46:49], v[142:145], v[172:175], v[46:49]
	v_mfma_f32_16x16x32_bf16 v[42:45], v[156:159], v[172:175], v[42:45]
	v_mfma_f32_16x16x32_bf16 v[30:33], v[142:145], v[180:183], v[30:33]
	v_mfma_f32_16x16x32_bf16 v[26:29], v[156:159], v[180:183], v[26:29]
	v_mfma_f32_16x16x32_bf16 v[14:17], v[142:145], v[208:211], v[14:17]
	v_mfma_f32_16x16x32_bf16 v[10:13], v[156:159], v[208:211], v[10:13]
	v_mfma_f32_16x16x32_bf16 v[62:65], v[152:155], v[168:171], v[62:65]
	v_mfma_f32_16x16x32_bf16 v[58:61], v[160:163], v[168:171], v[58:61]
	v_mfma_f32_16x16x32_bf16 v[46:49], v[152:155], v[176:179], v[46:49]
	v_mfma_f32_16x16x32_bf16 v[42:45], v[160:163], v[176:179], v[42:45]
	v_mfma_f32_16x16x32_bf16 v[30:33], v[152:155], v[204:207], v[30:33]
	v_mfma_f32_16x16x32_bf16 v[26:29], v[160:163], v[204:207], v[26:29]
	v_mfma_f32_16x16x32_bf16 v[14:17], v[152:155], v[212:215], v[14:17]
	v_mfma_f32_16x16x32_bf16 v[10:13], v[160:163], v[212:215], v[10:13]
	s_setprio 0
	s_barrier
	s_add_i32 s4, s4, s21
	v_lshl_add_u64 v[142:143], v[236:237], 0, s[6:7]
	s_mov_b32 m0, s4
	s_nop 0
	global_load_lds_dwordx4 v[142:143], off
	v_lshl_add_u64 v[142:143], v[238:239], 0, s[6:7]
	s_add_i32 m0, s4, 0x2000
	s_nop 0
	global_load_lds_dwordx4 v[142:143], off
	s_waitcnt vmcnt(6)
	s_barrier
	s_setprio 1
	v_mfma_f32_16x16x32_bf16 v[54:57], v[216:219], v[164:167], v[54:57]
	v_mfma_f32_16x16x32_bf16 v[50:53], v[224:227], v[164:167], v[50:53]
	v_mfma_f32_16x16x32_bf16 v[38:41], v[216:219], v[172:175], v[38:41]
	v_mfma_f32_16x16x32_bf16 v[34:37], v[224:227], v[172:175], v[34:37]
	v_mfma_f32_16x16x32_bf16 v[22:25], v[216:219], v[180:183], v[22:25]
	v_mfma_f32_16x16x32_bf16 v[18:21], v[224:227], v[180:183], v[18:21]
	v_mfma_f32_16x16x32_bf16 v[6:9], v[216:219], v[208:211], v[6:9]
	v_mfma_f32_16x16x32_bf16 v[2:5], v[224:227], v[208:211], v[2:5]
	v_mfma_f32_16x16x32_bf16 v[54:57], v[220:223], v[168:171], v[54:57]
	v_mfma_f32_16x16x32_bf16 v[50:53], v[228:231], v[168:171], v[50:53]
	v_mfma_f32_16x16x32_bf16 v[38:41], v[220:223], v[176:179], v[38:41]
	v_mfma_f32_16x16x32_bf16 v[34:37], v[228:231], v[176:179], v[34:37]
	v_mfma_f32_16x16x32_bf16 v[22:25], v[220:223], v[204:207], v[22:25]
	v_mfma_f32_16x16x32_bf16 v[18:21], v[228:231], v[204:207], v[18:21]
	v_mfma_f32_16x16x32_bf16 v[6:9], v[220:223], v[212:215], v[6:9]
	v_mfma_f32_16x16x32_bf16 v[2:5], v[228:231], v[212:215], v[2:5]
	s_setprio 0
	s_add_u32 s0, s0, 0x100
	s_addc_u32 s1, s1, 0
	s_add_u32 s48, s48, 0x100
	s_addc_u32 s49, s49, 0
	s_cmp_ge_u32 s65, s27
	s_mov_b32 s4, s65
	s_barrier
	s_cbranch_scc1 .Lkexit_698

.Lkexit_698:
	v_mov_b32_e32 v144, v148
	v_mov_b32_e32 v145, v1
	s_lshl_b32 s0, s47, 8
	s_add_i32 s0, s0, s28
	v_add_u32_e32 v153, s0, v144
	v_lshlrev_b32_e32 v144, 2, v144
	s_lshl_b32 s0, s46, 8
	v_lshl_add_u32 v144, v145, 6, v144
	s_or_b32 s0, s0, s29
	v_xor_b32_e32 v152, 64, v144
	v_xor_b32_e32 v151, 0x80, v144
	v_add_u32_e32 v144, s50, v153
	v_lshl_add_u32 v142, v145, 3, s0
	v_cmp_eq_u32_e32 vcc, 0, v145
	v_ashrrev_i32_e32 v145, 31, v144
	v_readlane_b32 s0, v243, 48
	v_lshlrev_b64 v[146:147], 11, v[144:145]
	v_readlane_b32 s1, v243, 49
	v_ashrrev_i32_e32 v143, 31, v142
	s_lshl_b32 s18, s46, 2
	v_lshl_add_u64 v[146:147], s[0:1], 0, v[146:147]
	v_lshl_add_u64 v[146:147], v[142:143], 1, v[146:147]
	v_lshlrev_b32_e32 v159, 11, v148
	v_lshl_add_u32 v159, v142, 1, v159
	s_lshl_b32 s65, s47, 8
	s_add_i32 s65, s65, s28
	s_add_i32 s48, s65, s50
	s_lshl_b32 s48, s48, 11
	s_add_u32 s48, s0, s48
	s_addc_u32 s49, s1, 0
	global_load_dwordx4 v[154:157], v159, s[48:49]
	global_load_dwordx4 v[160:163], v159, s[48:49] offset:256
	s_add_i32 s48, s65, s83
	s_lshl_b32 s48, s48, 11
	s_add_u32 s48, s0, s48
	s_addc_u32 s49, s1, 0
	global_load_dwordx4 v[164:167], v159, s[48:49]
	global_load_dwordx4 v[168:171], v159, s[48:49] offset:256
	s_add_i32 s48, s65, s91
	s_lshl_b32 s48, s48, 11
	s_add_u32 s48, s0, s48
	s_addc_u32 s49, s1, 0
	global_load_dwordx4 v[172:175], v159, s[48:49]
	global_load_dwordx4 v[176:179], v159, s[48:49] offset:256
	s_add_i32 s48, s65, s51
	s_lshl_b32 s48, s48, 11
	s_add_u32 s48, s0, s48
	s_addc_u32 s49, s1, 0
	global_load_dwordx4 v[180:183], v159, s[48:49]
	global_load_dwordx4 v[204:207], v159, s[48:49] offset:256
	s_add_i32 s48, s65, s88
	s_lshl_b32 s48, s48, 11
	s_add_u32 s48, s0, s48
	s_addc_u32 s49, s1, 0
	global_load_dwordx4 v[208:211], v159, s[48:49]
	global_load_dwordx4 v[212:215], v159, s[48:49] offset:256
	s_add_i32 s48, s65, s60
	s_lshl_b32 s48, s48, 11
	s_add_u32 s48, s0, s48
	s_addc_u32 s49, s1, 0
	global_load_dwordx4 v[216:219], v159, s[48:49]
	global_load_dwordx4 v[220:223], v159, s[48:49] offset:256
	s_add_i32 s48, s65, s61
	s_lshl_b32 s48, s48, 11
	s_add_u32 s48, s0, s48
	s_addc_u32 s49, s1, 0
	global_load_dwordx4 v[224:227], v159, s[48:49]
	global_load_dwordx4 v[228:231], v159, s[48:49] offset:256
	s_add_i32 s48, s65, s62
	s_lshl_b32 s48, s48, 11
	s_add_u32 s48, s0, s48
	s_addc_u32 s49, s1, 0
	global_load_dwordx4 v[232:235], v159, s[48:49]
	global_load_dwordx4 v[236:239], v159, s[48:49] offset:256
	s_ashr_i32 s19, s18, 31
	s_waitcnt vmcnt(15)
	v_lshlrev_b32_e32 v158, 16, v154
	v_and_b32_e32 v154, 0xffff0000, v154
	v_add_f32_e32 v127, v127, v154
	v_lshlrev_b32_e32 v154, 16, v155
	v_add_f32_e32 v128, v128, v154
	v_and_b32_e32 v154, 0xffff0000, v155
	v_add_f32_e32 v129, v129, v154
	v_lshlrev_b32_e32 v154, 16, v156
	v_add_f32_e32 v154, v122, v154
	v_and_b32_e32 v122, 0xffff0000, v156
	v_add_f32_e32 v155, v123, v122
	v_lshlrev_b32_e32 v122, 16, v157
	v_add_f32_e32 v156, v124, v122
	v_and_b32_e32 v122, 0xffff0000, v157
	v_add_f32_e32 v126, v126, v158
	v_add_f32_e32 v125, v125, v122
	v_cvt_pk_bf16_f32 v122, v126, v127
	v_cvt_pk_bf16_f32 v123, v128, v129
	v_cvt_pk_bf16_f32 v124, v154, v155
	v_cvt_pk_bf16_f32 v125, v156, v125
	global_store_dwordx4 v[146:147], v[122:125], off
	v_lshlrev_b32_e32 v126, 16, v122
	v_lshlrev_b32_e32 v127, 16, v123
	v_and_b32_e32 v122, 0xffff0000, v122
	v_mul_f32_e32 v154, v122, v122
	v_fmac_f32_e32 v154, v126, v126
	v_and_b32_e32 v123, 0xffff0000, v123
	v_fmac_f32_e32 v154, v127, v127
	v_lshlrev_b32_e32 v128, 16, v124
	v_fmac_f32_e32 v154, v123, v123
	v_and_b32_e32 v124, 0xffff0000, v124
	v_fmac_f32_e32 v154, v128, v128
	v_lshlrev_b32_e32 v129, 16, v125
	v_fmac_f32_e32 v154, v124, v124
	v_and_b32_e32 v125, 0xffff0000, v125
	v_fmac_f32_e32 v154, v129, v129
	v_fmac_f32_e32 v154, v125, v125
	s_waitcnt vmcnt(15)
	v_lshlrev_b32_e32 v126, 16, v160
	v_and_b32_e32 v122, 0xffff0000, v160
	v_add_f32_e32 v119, v119, v122
	v_lshlrev_b32_e32 v122, 16, v161
	v_add_f32_e32 v120, v120, v122
	v_and_b32_e32 v122, 0xffff0000, v161
	v_add_f32_e32 v121, v121, v122
	v_lshlrev_b32_e32 v122, 16, v162
	v_add_f32_e32 v122, v114, v122
	v_and_b32_e32 v114, 0xffff0000, v162
	v_add_f32_e32 v123, v115, v114
	v_lshlrev_b32_e32 v114, 16, v163
	v_add_f32_e32 v124, v116, v114
	v_and_b32_e32 v114, 0xffff0000, v163
	v_add_f32_e32 v118, v118, v126
	v_add_f32_e32 v117, v117, v114
	v_cvt_pk_bf16_f32 v114, v118, v119
	v_cvt_pk_bf16_f32 v115, v120, v121
	v_cvt_pk_bf16_f32 v116, v122, v123
	v_cvt_pk_bf16_f32 v117, v124, v117
	global_store_dwordx4 v[146:147], v[114:117], off offset:256
	v_lshlrev_b32_e32 v118, 16, v114
	v_lshlrev_b32_e32 v119, 16, v115
	v_and_b32_e32 v114, 0xffff0000, v114
	v_mul_f32_e32 v114, v114, v114
	v_fmac_f32_e32 v114, v118, v118
	v_and_b32_e32 v115, 0xffff0000, v115
	v_fmac_f32_e32 v114, v119, v119
	v_lshlrev_b32_e32 v120, 16, v116
	v_fmac_f32_e32 v114, v115, v115
	v_and_b32_e32 v116, 0xffff0000, v116
	v_fmac_f32_e32 v114, v120, v120
	v_lshlrev_b32_e32 v121, 16, v117
	v_fmac_f32_e32 v114, v116, v116
	v_and_b32_e32 v117, 0xffff0000, v117
	v_fmac_f32_e32 v114, v121, v121
	v_fmac_f32_e32 v114, v117, v117
	v_add_f32_e32 v114, v154, v114
	ds_bpermute_b32 v115, v152, v114
	s_waitcnt lgkmcnt(0)
	v_add_f32_e32 v114, v114, v115
	ds_bpermute_b32 v115, v151, v114
	s_and_saveexec_b64 s[0:1], vcc
	s_cbranch_execz .LBB0_701
	v_readlane_b32 s4, v242, 3
	s_waitcnt lgkmcnt(0)
	v_add_f32_e32 v116, v114, v115
	v_lshlrev_b64 v[114:115], 6, v[144:145]
	v_readlane_b32 s5, v242, 4
	s_lshl_b32 s92, s26, 2
	s_nop 0
	v_lshl_add_u64 v[114:115], s[4:5], 0, v[114:115]
	v_lshl_add_u64 v[114:115], s[18:19], 2, v[114:115]
	v_lshl_add_u64 v[114:115], v[114:115], 0, s[92:93]
	global_store_dword v[114:115], v116, off

.LBB0_713:
	s_or_b64 exec, exec, s[0:1]
	v_add_u32_e32 v18, s62, v153
	s_waitcnt lgkmcnt(0)
	v_ashrrev_i32_e32 v19, 31, v18
	v_readlane_b32 s0, v243, 48
	v_lshlrev_b64 v[20:21], 11, v[18:19]
	v_readlane_b32 s1, v243, 49
	s_nop 1
	v_lshl_add_u64 v[20:21], s[0:1], 0, v[20:21]
	v_lshl_add_u64 v[20:21], v[142:143], 1, v[20:21]
	s_waitcnt vmcnt(22)
	v_lshlrev_b32_e32 v26, 16, v232
	v_and_b32_e32 v22, 0xffff0000, v232
	v_add_f32_e32 v15, v15, v22
	v_lshlrev_b32_e32 v22, 16, v233
	v_add_f32_e32 v16, v16, v22
	v_and_b32_e32 v22, 0xffff0000, v233
	v_add_f32_e32 v17, v17, v22
	v_lshlrev_b32_e32 v22, 16, v234
	v_add_f32_e32 v22, v10, v22
	v_and_b32_e32 v10, 0xffff0000, v234
	v_add_f32_e32 v23, v11, v10
	v_lshlrev_b32_e32 v10, 16, v235
	v_add_f32_e32 v24, v12, v10
	v_and_b32_e32 v10, 0xffff0000, v235
	v_add_f32_e32 v14, v14, v26
	v_add_f32_e32 v13, v13, v10
	v_cvt_pk_bf16_f32 v10, v14, v15
	v_cvt_pk_bf16_f32 v11, v16, v17
	v_cvt_pk_bf16_f32 v12, v22, v23
	v_cvt_pk_bf16_f32 v13, v24, v13
	global_store_dwordx4 v[20:21], v[10:13], off
	v_lshlrev_b32_e32 v14, 16, v10
	v_lshlrev_b32_e32 v15, 16, v11
	v_and_b32_e32 v10, 0xffff0000, v10
	v_mul_f32_e32 v22, v10, v10
	v_fmac_f32_e32 v22, v14, v14
	v_and_b32_e32 v11, 0xffff0000, v11
	v_fmac_f32_e32 v22, v15, v15
	v_lshlrev_b32_e32 v16, 16, v12
	v_fmac_f32_e32 v22, v11, v11
	v_and_b32_e32 v12, 0xffff0000, v12
	v_fmac_f32_e32 v22, v16, v16
	v_lshlrev_b32_e32 v17, 16, v13
	v_fmac_f32_e32 v22, v12, v12
	v_and_b32_e32 v13, 0xffff0000, v13
	v_fmac_f32_e32 v22, v17, v17
	v_fmac_f32_e32 v22, v13, v13
	s_waitcnt vmcnt(22)
	v_lshlrev_b32_e32 v14, 16, v236
	v_and_b32_e32 v10, 0xffff0000, v236
	v_add_f32_e32 v7, v7, v10
	v_lshlrev_b32_e32 v10, 16, v237
	v_add_f32_e32 v8, v8, v10
	v_and_b32_e32 v10, 0xffff0000, v237
	v_add_f32_e32 v9, v9, v10
	v_lshlrev_b32_e32 v10, 16, v238
	v_add_f32_e32 v10, v2, v10
	v_and_b32_e32 v2, 0xffff0000, v238
	v_add_f32_e32 v11, v3, v2
	v_lshlrev_b32_e32 v2, 16, v239
	v_add_f32_e32 v12, v4, v2
	v_and_b32_e32 v2, 0xffff0000, v239
	v_add_f32_e32 v6, v6, v14
	v_add_f32_e32 v5, v5, v2
	v_cvt_pk_bf16_f32 v2, v6, v7
	v_cvt_pk_bf16_f32 v3, v8, v9
	v_cvt_pk_bf16_f32 v4, v10, v11
	v_cvt_pk_bf16_f32 v5, v12, v5
	global_store_dwordx4 v[20:21], v[2:5], off offset:256
	v_lshlrev_b32_e32 v6, 16, v2
	v_lshlrev_b32_e32 v7, 16, v3
	v_and_b32_e32 v2, 0xffff0000, v2
	v_mul_f32_e32 v2, v2, v2
	v_fmac_f32_e32 v2, v6, v6
	v_and_b32_e32 v3, 0xffff0000, v3
	v_fmac_f32_e32 v2, v7, v7
	v_lshlrev_b32_e32 v8, 16, v4
	v_fmac_f32_e32 v2, v3, v3
	v_and_b32_e32 v4, 0xffff0000, v4
	v_fmac_f32_e32 v2, v8, v8
	v_lshlrev_b32_e32 v9, 16, v5
	v_fmac_f32_e32 v2, v4, v4
	v_and_b32_e32 v5, 0xffff0000, v5
	v_fmac_f32_e32 v2, v9, v9
	v_fmac_f32_e32 v2, v5, v5
	v_add_f32_e32 v2, v22, v2
	ds_bpermute_b32 v3, v152, v2
	s_waitcnt lgkmcnt(0)
	v_add_f32_e32 v2, v2, v3
	ds_bpermute_b32 v3, v151, v2
	s_and_saveexec_b64 s[0:1], vcc
	s_cbranch_execz .LBB0_686
	v_readlane_b32 s4, v242, 3
	s_waitcnt lgkmcnt(0)
	v_add_f32_e32 v4, v2, v3
	v_lshlrev_b64 v[2:3], 6, v[18:19]
	v_readlane_b32 s5, v242, 4
	s_lshl_b32 s92, s26, 2
	s_nop 0
	v_lshl_add_u64 v[2:3], s[4:5], 0, v[2:3]
	v_lshl_add_u64 v[2:3], s[18:19], 2, v[2:3]
	v_lshl_add_u64 v[2:3], v[2:3], 0, s[92:93]
	global_store_dword v[2:3], v4, off
	s_branch .LBB0_686
.Ltramp_975:
	s_branch .LBB0_975
.LBB0_715:
	s_waitcnt vmcnt(0)
	s_cmpk_gt_u32 s20, 0xff
	s_cbranch_scc1 .LBB0_717
	s_barrier

.LBB0_741:
	s_add_u32 s0, s0, 0x80
	s_addc_u32 s1, s1, 0
	s_add_u32 s65, s4, 0x100
	s_addc_u32 s66, s5, 0
	s_mov_b32 s4, 0
	s_add_i32 s70, s4, 2
	s_add_u32 s10, s0, 0x80
	s_addc_u32 s5, s1, 0
	s_add_i32 s71, 0, 0x10000
	v_add_u32_e32 v154, s71, v165
	ds_read_b128 v[142:145], v154
	ds_read_b128 v[146:149], v154 offset:1024
	ds_read_b128 v[150:153], v154 offset:2048
	ds_read_b128 v[154:157], v154 offset:3072
	s_cmp_eq_u32 s43, s4
	s_cselect_b32 s4, s22, s10
	s_cselect_b32 s5, s23, s5
	s_cselect_b32 s11, s13, s66
	s_cselect_b32 s10, s12, s65
	v_lshl_add_u64 v[162:163], s[0:1], 0, v[138:139]
	s_add_i32 m0, s29, 0xc000
	ds_read_b128 v[158:161], v166
	ds_read_b128 v[168:171], v166 offset:1024
	ds_read_b128 v[172:175], v166 offset:2048
	ds_read_b128 v[176:179], v166 offset:3072
	ds_read_b128 v[180:183], v166 offset:4096
	ds_read_b128 v[204:207], v166 offset:5120
	ds_read_b128 v[208:211], v166 offset:6144
	ds_read_b128 v[212:215], v166 offset:7168
	global_load_lds_dwordx4 v[162:163], off
	v_lshl_add_u64 v[162:163], s[0:1], 0, v[140:141]
	s_add_i32 m0, s29, 0xe000
	s_nop 0
	global_load_lds_dwordx4 v[162:163], off
	s_waitcnt lgkmcnt(8)
	s_barrier
	s_waitcnt lgkmcnt(0)
	s_setprio 1
	s_waitcnt lgkmcnt(0)
	v_mfma_f32_16x16x32_bf16 v[126:129], v[142:145], v[158:161], 0
	v_mfma_f32_16x16x32_bf16 v[122:125], v[150:153], v[158:161], 0
	v_mfma_f32_16x16x32_bf16 v[110:113], v[142:145], v[172:175], 0
	v_mfma_f32_16x16x32_bf16 v[106:109], v[150:153], v[172:175], 0
	v_mfma_f32_16x16x32_bf16 v[94:97], v[142:145], v[180:183], 0
	v_mfma_f32_16x16x32_bf16 v[90:93], v[150:153], v[180:183], 0
	v_mfma_f32_16x16x32_bf16 v[78:81], v[142:145], v[208:211], 0
	v_mfma_f32_16x16x32_bf16 v[74:77], v[150:153], v[208:211], 0
	v_mfma_f32_16x16x32_bf16 v[126:129], v[146:149], v[168:171], v[126:129]
	v_mfma_f32_16x16x32_bf16 v[122:125], v[154:157], v[168:171], v[122:125]
	v_mfma_f32_16x16x32_bf16 v[110:113], v[146:149], v[176:179], v[110:113]
	v_mfma_f32_16x16x32_bf16 v[106:109], v[154:157], v[176:179], v[106:109]
	v_mfma_f32_16x16x32_bf16 v[94:97], v[146:149], v[204:207], v[94:97]
	v_mfma_f32_16x16x32_bf16 v[90:93], v[154:157], v[204:207], v[90:93]
	v_mfma_f32_16x16x32_bf16 v[78:81], v[146:149], v[212:215], v[78:81]
	v_mfma_f32_16x16x32_bf16 v[74:77], v[154:157], v[212:215], v[74:77]
	s_setprio 0
	s_barrier
	s_add_i32 s72, 0, 0x14000
	v_add_u32_e32 v162, s72, v165
	s_add_i32 s71, s71, s28
	ds_read_b128 v[216:219], v162
	ds_read_b128 v[220:223], v162 offset:1024
	ds_read_b128 v[224:227], v162 offset:2048
	ds_read_b128 v[228:231], v162 offset:3072
	v_lshl_add_u64 v[162:163], s[10:11], 0, v[132:133]
	s_mov_b32 m0, s71
	v_lshl_add_u64 v[184:185], s[10:11], 0, v[136:137]
	global_load_lds_dwordx4 v[162:163], off
	s_add_i32 m0, s71, 0x2000
	s_nop 0
	global_load_lds_dwordx4 v[184:185], off
	s_barrier
	s_waitcnt lgkmcnt(0)
	s_setprio 1
	s_waitcnt lgkmcnt(0)
	v_mfma_f32_16x16x32_bf16 v[118:121], v[216:219], v[158:161], 0
	v_mfma_f32_16x16x32_bf16 v[114:117], v[224:227], v[158:161], 0
	v_mfma_f32_16x16x32_bf16 v[102:105], v[216:219], v[172:175], 0
	v_mfma_f32_16x16x32_bf16 v[98:101], v[224:227], v[172:175], 0
	v_mfma_f32_16x16x32_bf16 v[86:89], v[216:219], v[180:183], 0
	v_mfma_f32_16x16x32_bf16 v[82:85], v[224:227], v[180:183], 0
	v_mfma_f32_16x16x32_bf16 v[70:73], v[216:219], v[208:211], 0
	v_mfma_f32_16x16x32_bf16 v[66:69], v[224:227], v[208:211], 0
	v_mfma_f32_16x16x32_bf16 v[118:121], v[220:223], v[168:171], v[118:121]
	v_mfma_f32_16x16x32_bf16 v[114:117], v[228:231], v[168:171], v[114:117]
	v_mfma_f32_16x16x32_bf16 v[102:105], v[220:223], v[176:179], v[102:105]
	v_mfma_f32_16x16x32_bf16 v[98:101], v[228:231], v[176:179], v[98:101]
	v_mfma_f32_16x16x32_bf16 v[86:89], v[220:223], v[204:207], v[86:89]
	v_mfma_f32_16x16x32_bf16 v[82:85], v[228:231], v[204:207], v[82:85]
	v_mfma_f32_16x16x32_bf16 v[70:73], v[220:223], v[212:215], v[70:73]
	v_mfma_f32_16x16x32_bf16 v[66:69], v[228:231], v[212:215], v[66:69]
	s_setprio 0
	s_mov_b32 m0, s29
	v_lshl_add_u64 v[232:233], s[4:5], 0, v[130:131]
	s_barrier
	ds_read_b128 v[158:161], v166 offset:16384
	ds_read_b128 v[168:171], v166 offset:17408
	ds_read_b128 v[172:175], v166 offset:18432
	ds_read_b128 v[176:179], v166 offset:19456
	ds_read_b128 v[180:183], v166 offset:20480
	ds_read_b128 v[204:207], v166 offset:21504
	ds_read_b128 v[208:211], v166 offset:22528
	ds_read_b128 v[212:215], v166 offset:23552
	global_load_lds_dwordx4 v[232:233], off
	v_lshl_add_u64 v[234:235], s[4:5], 0, v[134:135]
	s_mov_b32 m0, s30
	s_nop 0
	global_load_lds_dwordx4 v[234:235], off
	s_barrier
	s_waitcnt lgkmcnt(0)
	s_setprio 1
	s_waitcnt lgkmcnt(0)
	v_mfma_f32_16x16x32_bf16 v[62:65], v[142:145], v[158:161], 0
	v_mfma_f32_16x16x32_bf16 v[58:61], v[150:153], v[158:161], 0
	v_mfma_f32_16x16x32_bf16 v[46:49], v[142:145], v[172:175], 0
	v_mfma_f32_16x16x32_bf16 v[42:45], v[150:153], v[172:175], 0
	v_mfma_f32_16x16x32_bf16 v[30:33], v[142:145], v[180:183], 0
	v_mfma_f32_16x16x32_bf16 v[26:29], v[150:153], v[180:183], 0
	v_mfma_f32_16x16x32_bf16 v[14:17], v[142:145], v[208:211], 0
	v_mfma_f32_16x16x32_bf16 v[10:13], v[150:153], v[208:211], 0
	v_mfma_f32_16x16x32_bf16 v[62:65], v[146:149], v[168:171], v[62:65]
	v_mfma_f32_16x16x32_bf16 v[58:61], v[154:157], v[168:171], v[58:61]
	v_mfma_f32_16x16x32_bf16 v[46:49], v[146:149], v[176:179], v[46:49]
	v_mfma_f32_16x16x32_bf16 v[42:45], v[154:157], v[176:179], v[42:45]
	v_mfma_f32_16x16x32_bf16 v[30:33], v[146:149], v[204:207], v[30:33]
	v_mfma_f32_16x16x32_bf16 v[26:29], v[154:157], v[204:207], v[26:29]
	v_mfma_f32_16x16x32_bf16 v[14:17], v[146:149], v[212:215], v[14:17]
	v_mfma_f32_16x16x32_bf16 v[10:13], v[154:157], v[212:215], v[10:13]
	s_setprio 0
	s_barrier
	s_add_u32 s10, s10, s2
	s_addc_u32 s11, s11, 0
	s_add_i32 s71, s72, s28
	v_lshl_add_u64 v[236:237], s[10:11], 0, v[132:133]
	s_mov_b32 m0, s71
	v_lshl_add_u64 v[238:239], s[10:11], 0, v[136:137]
	global_load_lds_dwordx4 v[236:237], off
	s_add_i32 m0, s71, 0x2000
	s_nop 0
	global_load_lds_dwordx4 v[238:239], off
	s_waitcnt vmcnt(6)
	s_barrier
	s_setprio 1
	v_mfma_f32_16x16x32_bf16 v[54:57], v[216:219], v[158:161], 0
	v_mfma_f32_16x16x32_bf16 v[50:53], v[224:227], v[158:161], 0
	v_mfma_f32_16x16x32_bf16 v[38:41], v[216:219], v[172:175], 0
	v_mfma_f32_16x16x32_bf16 v[34:37], v[224:227], v[172:175], 0
	v_mfma_f32_16x16x32_bf16 v[22:25], v[216:219], v[180:183], 0
	v_mfma_f32_16x16x32_bf16 v[18:21], v[224:227], v[180:183], 0
	v_mfma_f32_16x16x32_bf16 v[6:9], v[216:219], v[208:211], 0
	v_mfma_f32_16x16x32_bf16 v[2:5], v[224:227], v[208:211], 0
	v_mfma_f32_16x16x32_bf16 v[54:57], v[220:223], v[168:171], v[54:57]
	v_mfma_f32_16x16x32_bf16 v[50:53], v[228:231], v[168:171], v[50:53]
	v_mfma_f32_16x16x32_bf16 v[38:41], v[220:223], v[176:179], v[38:41]
	v_mfma_f32_16x16x32_bf16 v[34:37], v[228:231], v[176:179], v[34:37]
	v_mfma_f32_16x16x32_bf16 v[22:25], v[220:223], v[204:207], v[22:25]
	v_mfma_f32_16x16x32_bf16 v[18:21], v[228:231], v[204:207], v[18:21]
	v_mfma_f32_16x16x32_bf16 v[6:9], v[220:223], v[212:215], v[6:9]
	v_mfma_f32_16x16x32_bf16 v[2:5], v[228:231], v[212:215], v[2:5]
	s_setprio 0
	s_add_i32 s10, 0, 0x18000
	v_add_u32_e32 v154, s10, v165
	s_barrier
	ds_read_b128 v[142:145], v154
	ds_read_b128 v[146:149], v154 offset:1024
	ds_read_b128 v[150:153], v154 offset:2048
	ds_read_b128 v[154:157], v154 offset:3072
	s_add_u32 s4, s4, s2
	s_addc_u32 s5, s5, 0
	s_mov_b32 m0, s31
	v_lshl_add_u64 v[216:217], s[4:5], 0, v[130:131]
	ds_read_b128 v[158:161], v166 offset:32768
	ds_read_b128 v[168:171], v166 offset:33792
	ds_read_b128 v[172:175], v166 offset:34816
	ds_read_b128 v[176:179], v166 offset:35840
	ds_read_b128 v[180:183], v166 offset:36864
	ds_read_b128 v[204:207], v166 offset:37888
	ds_read_b128 v[208:211], v166 offset:38912
	ds_read_b128 v[212:215], v166 offset:39936
	global_load_lds_dwordx4 v[216:217], off
	v_lshl_add_u64 v[216:217], s[4:5], 0, v[134:135]
	s_mov_b32 m0, s34
	s_nop 0
	global_load_lds_dwordx4 v[216:217], off
	s_waitcnt lgkmcnt(8)
	s_barrier
	s_waitcnt lgkmcnt(0)
	s_setprio 1
	s_waitcnt lgkmcnt(0)
	v_mfma_f32_16x16x32_bf16 v[126:129], v[142:145], v[158:161], v[126:129]
	v_mfma_f32_16x16x32_bf16 v[122:125], v[150:153], v[158:161], v[122:125]
	v_mfma_f32_16x16x32_bf16 v[110:113], v[142:145], v[172:175], v[110:113]
	v_mfma_f32_16x16x32_bf16 v[106:109], v[150:153], v[172:175], v[106:109]
	v_mfma_f32_16x16x32_bf16 v[94:97], v[142:145], v[180:183], v[94:97]
	v_mfma_f32_16x16x32_bf16 v[90:93], v[150:153], v[180:183], v[90:93]
	v_mfma_f32_16x16x32_bf16 v[78:81], v[142:145], v[208:211], v[78:81]
	v_mfma_f32_16x16x32_bf16 v[74:77], v[150:153], v[208:211], v[74:77]
	v_mfma_f32_16x16x32_bf16 v[126:129], v[146:149], v[168:171], v[126:129]
	v_mfma_f32_16x16x32_bf16 v[122:125], v[154:157], v[168:171], v[122:125]
	v_mfma_f32_16x16x32_bf16 v[110:113], v[146:149], v[176:179], v[110:113]
	v_mfma_f32_16x16x32_bf16 v[106:109], v[154:157], v[176:179], v[106:109]
	v_mfma_f32_16x16x32_bf16 v[94:97], v[146:149], v[204:207], v[94:97]
	v_mfma_f32_16x16x32_bf16 v[90:93], v[154:157], v[204:207], v[90:93]
	v_mfma_f32_16x16x32_bf16 v[78:81], v[146:149], v[212:215], v[78:81]
	v_mfma_f32_16x16x32_bf16 v[74:77], v[154:157], v[212:215], v[74:77]
	s_setprio 0
	s_barrier
	s_add_i32 s4, 0, 0x1c000
	s_add_i32 s5, s10, s28
	v_add_u32_e32 v167, s4, v165
	v_lshl_add_u64 v[162:163], v[162:163], 0, s[6:7]
	s_mov_b32 m0, s5
	ds_read_b128 v[216:219], v167
	ds_read_b128 v[220:223], v167 offset:1024
	ds_read_b128 v[224:227], v167 offset:2048
	ds_read_b128 v[228:231], v167 offset:3072
	global_load_lds_dwordx4 v[162:163], off
	v_lshl_add_u64 v[162:163], v[184:185], 0, s[6:7]
	s_add_i32 m0, s5, 0x2000
	s_nop 0
	global_load_lds_dwordx4 v[162:163], off
	s_barrier
	s_waitcnt lgkmcnt(0)
	s_setprio 1
	s_waitcnt lgkmcnt(0)
	v_mfma_f32_16x16x32_bf16 v[118:121], v[216:219], v[158:161], v[118:121]
	v_mfma_f32_16x16x32_bf16 v[114:117], v[224:227], v[158:161], v[114:117]
	v_mfma_f32_16x16x32_bf16 v[102:105], v[216:219], v[172:175], v[102:105]
	v_mfma_f32_16x16x32_bf16 v[98:101], v[224:227], v[172:175], v[98:101]
	v_mfma_f32_16x16x32_bf16 v[86:89], v[216:219], v[180:183], v[86:89]
	v_mfma_f32_16x16x32_bf16 v[82:85], v[224:227], v[180:183], v[82:85]
	v_mfma_f32_16x16x32_bf16 v[70:73], v[216:219], v[208:211], v[70:73]
	v_mfma_f32_16x16x32_bf16 v[66:69], v[224:227], v[208:211], v[66:69]
	v_mfma_f32_16x16x32_bf16 v[118:121], v[220:223], v[168:171], v[118:121]
	v_mfma_f32_16x16x32_bf16 v[114:117], v[228:231], v[168:171], v[114:117]
	v_mfma_f32_16x16x32_bf16 v[102:105], v[220:223], v[176:179], v[102:105]
	v_mfma_f32_16x16x32_bf16 v[98:101], v[228:231], v[176:179], v[98:101]
	v_mfma_f32_16x16x32_bf16 v[86:89], v[220:223], v[204:207], v[86:89]
	v_mfma_f32_16x16x32_bf16 v[82:85], v[228:231], v[204:207], v[82:85]
	v_mfma_f32_16x16x32_bf16 v[70:73], v[220:223], v[212:215], v[70:73]
	v_mfma_f32_16x16x32_bf16 v[66:69], v[228:231], v[212:215], v[66:69]
	s_setprio 0
	s_mov_b32 m0, s41
	v_lshl_add_u64 v[162:163], v[232:233], 0, s[6:7]
	s_barrier
	ds_read_b128 v[158:161], v166 offset:49152
	ds_read_b128 v[168:171], v166 offset:50176
	ds_read_b128 v[172:175], v166 offset:51200
	ds_read_b128 v[176:179], v166 offset:52224
	ds_read_b128 v[180:183], v166 offset:53248
	ds_read_b128 v[204:207], v166 offset:54272
	ds_read_b128 v[208:211], v166 offset:55296
	ds_read_b128 v[212:215], v166 offset:56320
	global_load_lds_dwordx4 v[162:163], off
	v_lshl_add_u64 v[162:163], v[234:235], 0, s[6:7]
	s_mov_b32 m0, s42
	s_nop 0
	global_load_lds_dwordx4 v[162:163], off
	s_barrier
	s_waitcnt lgkmcnt(0)
	s_setprio 1
	s_waitcnt lgkmcnt(0)
	v_mfma_f32_16x16x32_bf16 v[62:65], v[142:145], v[158:161], v[62:65]
	v_mfma_f32_16x16x32_bf16 v[58:61], v[150:153], v[158:161], v[58:61]
	v_mfma_f32_16x16x32_bf16 v[46:49], v[142:145], v[172:175], v[46:49]
	v_mfma_f32_16x16x32_bf16 v[42:45], v[150:153], v[172:175], v[42:45]
	v_mfma_f32_16x16x32_bf16 v[30:33], v[142:145], v[180:183], v[30:33]
	v_mfma_f32_16x16x32_bf16 v[26:29], v[150:153], v[180:183], v[26:29]
	v_mfma_f32_16x16x32_bf16 v[14:17], v[142:145], v[208:211], v[14:17]
	v_mfma_f32_16x16x32_bf16 v[10:13], v[150:153], v[208:211], v[10:13]
	v_mfma_f32_16x16x32_bf16 v[62:65], v[146:149], v[168:171], v[62:65]
	v_mfma_f32_16x16x32_bf16 v[58:61], v[154:157], v[168:171], v[58:61]
	v_mfma_f32_16x16x32_bf16 v[46:49], v[146:149], v[176:179], v[46:49]
	v_mfma_f32_16x16x32_bf16 v[42:45], v[154:157], v[176:179], v[42:45]
	v_mfma_f32_16x16x32_bf16 v[30:33], v[146:149], v[204:207], v[30:33]
	v_mfma_f32_16x16x32_bf16 v[26:29], v[154:157], v[204:207], v[26:29]
	v_mfma_f32_16x16x32_bf16 v[14:17], v[146:149], v[212:215], v[14:17]
	v_mfma_f32_16x16x32_bf16 v[10:13], v[154:157], v[212:215], v[10:13]
	s_setprio 0
	s_barrier
	s_add_i32 s4, s4, s28
	v_lshl_add_u64 v[142:143], v[236:237], 0, s[6:7]
	s_mov_b32 m0, s4
	s_nop 0
	global_load_lds_dwordx4 v[142:143], off
	v_lshl_add_u64 v[142:143], v[238:239], 0, s[6:7]
	s_add_i32 m0, s4, 0x2000
	s_nop 0
	global_load_lds_dwordx4 v[142:143], off
	s_waitcnt vmcnt(6)
	s_barrier
	s_setprio 1
	v_mfma_f32_16x16x32_bf16 v[54:57], v[216:219], v[158:161], v[54:57]
	v_mfma_f32_16x16x32_bf16 v[50:53], v[224:227], v[158:161], v[50:53]
	v_mfma_f32_16x16x32_bf16 v[38:41], v[216:219], v[172:175], v[38:41]
	v_mfma_f32_16x16x32_bf16 v[34:37], v[224:227], v[172:175], v[34:37]
	v_mfma_f32_16x16x32_bf16 v[22:25], v[216:219], v[180:183], v[22:25]
	v_mfma_f32_16x16x32_bf16 v[18:21], v[224:227], v[180:183], v[18:21]
	v_mfma_f32_16x16x32_bf16 v[6:9], v[216:219], v[208:211], v[6:9]
	v_mfma_f32_16x16x32_bf16 v[2:5], v[224:227], v[208:211], v[2:5]
	v_mfma_f32_16x16x32_bf16 v[54:57], v[220:223], v[168:171], v[54:57]
	v_mfma_f32_16x16x32_bf16 v[50:53], v[228:231], v[168:171], v[50:53]
	v_mfma_f32_16x16x32_bf16 v[38:41], v[220:223], v[176:179], v[38:41]
	v_mfma_f32_16x16x32_bf16 v[34:37], v[228:231], v[176:179], v[34:37]
	v_mfma_f32_16x16x32_bf16 v[22:25], v[220:223], v[204:207], v[22:25]
	v_mfma_f32_16x16x32_bf16 v[18:21], v[228:231], v[204:207], v[18:21]
	v_mfma_f32_16x16x32_bf16 v[6:9], v[220:223], v[212:215], v[6:9]
	v_mfma_f32_16x16x32_bf16 v[2:5], v[228:231], v[212:215], v[2:5]
	s_setprio 0
	s_add_u32 s0, s0, 0x100
	s_addc_u32 s1, s1, 0
	s_add_u32 s65, s65, 0x100
	s_addc_u32 s66, s66, 0
	s_cmp_ge_u32 s70, s35
	s_mov_b32 s4, s70
	s_barrier
	s_cbranch_scc1 .Lkexit_742

.Lkexit_742:
	v_mov_b32_e32 v152, v164
	v_mov_b32_e32 v142, v1
	s_lshl_b32 s5, s3, 8
	s_cmp_lg_u32 s3, s25
	v_lshl_add_u32 v143, v142, 4, v152
	s_mov_b64 s[0:1], -1
	s_cbranch_scc0 .LBB0_745
	s_add_i32 s4, s5, s40
	v_and_or_b32 v144, v143, 63, s4
	v_lshlrev_b32_e32 v162, 1, v143
	v_add_u32_e32 v153, s50, v144
	v_and_b32_e32 v144, 0xffffff80, v162
	v_add_u32_e32 v144, v153, v144
	v_ashrrev_i32_e32 v145, 31, v144
	v_readlane_b32 s0, v242, 3
	v_lshlrev_b64 v[144:145], 6, v[144:145]
	v_readlane_b32 s1, v242, 4
	v_lshl_add_u32 v167, v143, 2, s49
	s_nop 0
	v_lshl_add_u64 v[158:159], s[0:1], 0, v[144:145]
	global_load_dwordx4 v[144:147], v[158:159], off offset:48
	global_load_dwordx4 v[148:151], v[158:159], off offset:32
	global_load_dwordx4 v[154:157], v[158:159], off offset:16
	s_nop 0
	global_load_dwordx4 v[158:161], v[158:159], off
	v_add_u32_e32 v222, 0x80, v162
	v_and_b32_e32 v222, 0xffffff80, v222
	v_add_u32_e32 v222, v153, v222
	v_ashrrev_i32_e32 v223, 31, v222
	v_lshlrev_b64 v[222:223], 6, v[222:223]
	v_lshl_add_u64 v[220:221], s[0:1], 0, v[222:223]
	global_load_dwordx4 v[204:207], v[220:221], off offset:48
	global_load_dwordx4 v[208:211], v[220:221], off offset:32
	global_load_dwordx4 v[212:215], v[220:221], off offset:16
	global_load_dwordx4 v[216:219], v[220:221], off
	s_waitcnt vmcnt(4)
	v_add_f32_e32 v144, v144, v145
	v_add_f32_e32 v148, v148, v149
	v_add_f32_e32 v154, v154, v155
	v_add_f32_e32 v158, v158, v159
	v_add_f32_e32 v158, v160, v158
	v_add_f32_e32 v154, v156, v154
	v_add_f32_e32 v158, v161, v158
	v_add_f32_e32 v154, v157, v154
	v_add_f32_e32 v148, v150, v148
	v_add_f32_e32 v154, v158, v154
	v_add_f32_e32 v148, v151, v148
	v_add_f32_e32 v144, v146, v144
	v_add_f32_e32 v148, v154, v148
	v_add_f32_e32 v144, v147, v144
	v_add_f32_e32 v144, v148, v144
	v_fmamk_f32 v144, v144, 0x3a800000, v188
	v_rsq_f32_e32 v163, v144
	s_mov_b64 s[0:1], 0
	s_waitcnt vmcnt(0)
	v_add_f32_e32 v144, v204, v205
	v_add_f32_e32 v148, v208, v209
	v_add_f32_e32 v154, v212, v213
	v_add_f32_e32 v153, v216, v217
	v_add_f32_e32 v153, v218, v153
	v_add_f32_e32 v154, v214, v154
	v_add_f32_e32 v153, v219, v153
	v_add_f32_e32 v154, v215, v154
	v_add_f32_e32 v148, v210, v148
	v_add_f32_e32 v153, v153, v154
	v_add_f32_e32 v148, v211, v148
	v_add_f32_e32 v144, v206, v144
	v_add_f32_e32 v148, v153, v148
	v_add_f32_e32 v144, v207, v144
	v_add_f32_e32 v144, v148, v144
	v_fmamk_f32 v144, v144, 0x3a800000, v188
	v_rsq_f32_e32 v144, v144
	ds_write2st64_b32 v167, v163, v144 offset1:1
	s_waitcnt lgkmcnt(0)

.LBB0_805:
	s_add_u32 s0, s0, 0x80
	s_addc_u32 s1, s1, 0
	s_add_u32 s12, s4, 0x100
	s_addc_u32 s13, s5, 0
	s_mov_b32 s4, 0
	s_waitcnt vmcnt(0)
	s_add_i32 s27, s4, 2
	s_add_u32 s10, s0, 0x80
	s_addc_u32 s5, s1, 0
	s_add_i32 s28, 0, 0x10000
	v_add_u32_e32 v154, s28, v171
	ds_read_b128 v[142:145], v154
	ds_read_b128 v[146:149], v154 offset:1024
	ds_read_b128 v[150:153], v154 offset:2048
	ds_read_b128 v[154:157], v154 offset:3072
	s_cmp_eq_u32 s48, s4
	s_cselect_b32 s4, s22, s10
	s_cselect_b32 s5, s23, s5
	s_cselect_b32 s11, s25, s13
	s_cselect_b32 s10, s24, s12
	v_lshl_add_u64 v[212:213], s[0:1], 0, v[138:139]
	s_add_i32 m0, s35, 0xc000
	ds_read_b128 v[158:161], v172
	ds_read_b128 v[162:165], v172 offset:1024
	ds_read_b128 v[166:169], v172 offset:2048
	ds_read_b128 v[174:177], v172 offset:3072
	ds_read_b128 v[178:181], v172 offset:4096
	ds_read_b128 v[182:185], v172 offset:5120
	ds_read_b128 v[204:207], v172 offset:6144
	ds_read_b128 v[208:211], v172 offset:7168
	global_load_lds_dwordx4 v[212:213], off
	v_lshl_add_u64 v[212:213], s[0:1], 0, v[140:141]
	s_add_i32 m0, s35, 0xe000
	s_nop 0
	global_load_lds_dwordx4 v[212:213], off
	s_waitcnt lgkmcnt(8)
	s_barrier
	s_waitcnt lgkmcnt(0)
	s_setprio 1
	s_waitcnt lgkmcnt(0)
	v_mfma_f32_16x16x32_bf16 v[126:129], v[142:145], v[158:161], 0
	v_mfma_f32_16x16x32_bf16 v[122:125], v[150:153], v[158:161], 0
	v_mfma_f32_16x16x32_bf16 v[110:113], v[142:145], v[166:169], 0
	v_mfma_f32_16x16x32_bf16 v[106:109], v[150:153], v[166:169], 0
	v_mfma_f32_16x16x32_bf16 v[94:97], v[142:145], v[178:181], 0
	v_mfma_f32_16x16x32_bf16 v[90:93], v[150:153], v[178:181], 0
	v_mfma_f32_16x16x32_bf16 v[78:81], v[142:145], v[204:207], 0
	v_mfma_f32_16x16x32_bf16 v[74:77], v[150:153], v[204:207], 0
	v_mfma_f32_16x16x32_bf16 v[126:129], v[146:149], v[162:165], v[126:129]
	v_mfma_f32_16x16x32_bf16 v[122:125], v[154:157], v[162:165], v[122:125]
	v_mfma_f32_16x16x32_bf16 v[110:113], v[146:149], v[174:177], v[110:113]
	v_mfma_f32_16x16x32_bf16 v[106:109], v[154:157], v[174:177], v[106:109]
	v_mfma_f32_16x16x32_bf16 v[94:97], v[146:149], v[182:185], v[94:97]
	v_mfma_f32_16x16x32_bf16 v[90:93], v[154:157], v[182:185], v[90:93]
	v_mfma_f32_16x16x32_bf16 v[78:81], v[146:149], v[208:211], v[78:81]
	v_mfma_f32_16x16x32_bf16 v[74:77], v[154:157], v[208:211], v[74:77]
	s_setprio 0
	s_barrier
	s_add_i32 s29, 0, 0x14000
	s_add_i32 s28, s28, s34
	v_add_u32_e32 v173, s29, v171
	v_lshl_add_u64 v[228:229], s[10:11], 0, v[132:133]
	s_mov_b32 m0, s28
	ds_read_b128 v[212:215], v173
	ds_read_b128 v[216:219], v173 offset:1024
	ds_read_b128 v[220:223], v173 offset:2048
	ds_read_b128 v[224:227], v173 offset:3072
	global_load_lds_dwordx4 v[228:229], off
	v_lshl_add_u64 v[230:231], s[10:11], 0, v[136:137]
	s_add_i32 m0, s28, 0x2000
	s_nop 0
	global_load_lds_dwordx4 v[230:231], off
	s_barrier
	s_waitcnt lgkmcnt(0)
	s_setprio 1
	s_waitcnt lgkmcnt(0)
	v_mfma_f32_16x16x32_bf16 v[118:121], v[212:215], v[158:161], 0
	v_mfma_f32_16x16x32_bf16 v[114:117], v[220:223], v[158:161], 0
	v_mfma_f32_16x16x32_bf16 v[102:105], v[212:215], v[166:169], 0
	v_mfma_f32_16x16x32_bf16 v[98:101], v[220:223], v[166:169], 0
	v_mfma_f32_16x16x32_bf16 v[86:89], v[212:215], v[178:181], 0
	v_mfma_f32_16x16x32_bf16 v[82:85], v[220:223], v[178:181], 0
	v_mfma_f32_16x16x32_bf16 v[70:73], v[212:215], v[204:207], 0
	v_mfma_f32_16x16x32_bf16 v[66:69], v[220:223], v[204:207], 0
	v_mfma_f32_16x16x32_bf16 v[118:121], v[216:219], v[162:165], v[118:121]
	v_mfma_f32_16x16x32_bf16 v[114:117], v[224:227], v[162:165], v[114:117]
	v_mfma_f32_16x16x32_bf16 v[102:105], v[216:219], v[174:177], v[102:105]
	v_mfma_f32_16x16x32_bf16 v[98:101], v[224:227], v[174:177], v[98:101]
	v_mfma_f32_16x16x32_bf16 v[86:89], v[216:219], v[182:185], v[86:89]
	v_mfma_f32_16x16x32_bf16 v[82:85], v[224:227], v[182:185], v[82:85]
	v_mfma_f32_16x16x32_bf16 v[70:73], v[216:219], v[208:211], v[70:73]
	v_mfma_f32_16x16x32_bf16 v[66:69], v[224:227], v[208:211], v[66:69]
	s_setprio 0
	s_mov_b32 m0, s35
	v_lshl_add_u64 v[232:233], s[4:5], 0, v[130:131]
	s_barrier
	ds_read_b128 v[158:161], v172 offset:16384
	ds_read_b128 v[162:165], v172 offset:17408
	ds_read_b128 v[166:169], v172 offset:18432
	ds_read_b128 v[174:177], v172 offset:19456
	ds_read_b128 v[178:181], v172 offset:20480
	ds_read_b128 v[182:185], v172 offset:21504
	ds_read_b128 v[204:207], v172 offset:22528
	ds_read_b128 v[208:211], v172 offset:23552
	global_load_lds_dwordx4 v[232:233], off
	v_lshl_add_u64 v[234:235], s[4:5], 0, v[134:135]
	s_mov_b32 m0, s40
	s_nop 0
	global_load_lds_dwordx4 v[234:235], off
	s_barrier
	s_waitcnt lgkmcnt(0)
	s_setprio 1
	s_waitcnt lgkmcnt(0)
	v_mfma_f32_16x16x32_bf16 v[62:65], v[142:145], v[158:161], 0
	v_mfma_f32_16x16x32_bf16 v[58:61], v[150:153], v[158:161], 0
	v_mfma_f32_16x16x32_bf16 v[46:49], v[142:145], v[166:169], 0
	v_mfma_f32_16x16x32_bf16 v[42:45], v[150:153], v[166:169], 0
	v_mfma_f32_16x16x32_bf16 v[30:33], v[142:145], v[178:181], 0
	v_mfma_f32_16x16x32_bf16 v[26:29], v[150:153], v[178:181], 0
	v_mfma_f32_16x16x32_bf16 v[14:17], v[142:145], v[204:207], 0
	v_mfma_f32_16x16x32_bf16 v[10:13], v[150:153], v[204:207], 0
	v_mfma_f32_16x16x32_bf16 v[62:65], v[146:149], v[162:165], v[62:65]
	v_mfma_f32_16x16x32_bf16 v[58:61], v[154:157], v[162:165], v[58:61]
	v_mfma_f32_16x16x32_bf16 v[46:49], v[146:149], v[174:177], v[46:49]
	v_mfma_f32_16x16x32_bf16 v[42:45], v[154:157], v[174:177], v[42:45]
	v_mfma_f32_16x16x32_bf16 v[30:33], v[146:149], v[182:185], v[30:33]
	v_mfma_f32_16x16x32_bf16 v[26:29], v[154:157], v[182:185], v[26:29]
	v_mfma_f32_16x16x32_bf16 v[14:17], v[146:149], v[208:211], v[14:17]
	v_mfma_f32_16x16x32_bf16 v[10:13], v[154:157], v[208:211], v[10:13]
	s_setprio 0
	s_barrier
	s_add_u32 s10, s10, s92
	s_addc_u32 s11, s11, 0
	s_add_i32 s28, s29, s34
	v_lshl_add_u64 v[236:237], s[10:11], 0, v[132:133]
	s_mov_b32 m0, s28
	v_lshl_add_u64 v[238:239], s[10:11], 0, v[136:137]
	global_load_lds_dwordx4 v[236:237], off
	s_add_i32 m0, s28, 0x2000
	s_nop 0
	global_load_lds_dwordx4 v[238:239], off
	s_waitcnt vmcnt(6)
	s_barrier
	s_setprio 1
	v_mfma_f32_16x16x32_bf16 v[54:57], v[212:215], v[158:161], 0
	v_mfma_f32_16x16x32_bf16 v[50:53], v[220:223], v[158:161], 0
	v_mfma_f32_16x16x32_bf16 v[38:41], v[212:215], v[166:169], 0
	v_mfma_f32_16x16x32_bf16 v[34:37], v[220:223], v[166:169], 0
	v_mfma_f32_16x16x32_bf16 v[22:25], v[212:215], v[178:181], 0
	v_mfma_f32_16x16x32_bf16 v[18:21], v[220:223], v[178:181], 0
	v_mfma_f32_16x16x32_bf16 v[6:9], v[212:215], v[204:207], 0
	v_mfma_f32_16x16x32_bf16 v[2:5], v[220:223], v[204:207], 0
	v_mfma_f32_16x16x32_bf16 v[54:57], v[216:219], v[162:165], v[54:57]
	v_mfma_f32_16x16x32_bf16 v[50:53], v[224:227], v[162:165], v[50:53]
	v_mfma_f32_16x16x32_bf16 v[38:41], v[216:219], v[174:177], v[38:41]
	v_mfma_f32_16x16x32_bf16 v[34:37], v[224:227], v[174:177], v[34:37]
	v_mfma_f32_16x16x32_bf16 v[22:25], v[216:219], v[182:185], v[22:25]
	v_mfma_f32_16x16x32_bf16 v[18:21], v[224:227], v[182:185], v[18:21]
	v_mfma_f32_16x16x32_bf16 v[6:9], v[216:219], v[208:211], v[6:9]
	v_mfma_f32_16x16x32_bf16 v[2:5], v[224:227], v[208:211], v[2:5]
	s_setprio 0
	s_add_i32 s10, 0, 0x18000
	v_add_u32_e32 v154, s10, v171
	s_barrier
	ds_read_b128 v[142:145], v154
	ds_read_b128 v[146:149], v154 offset:1024
	ds_read_b128 v[150:153], v154 offset:2048
	ds_read_b128 v[154:157], v154 offset:3072
	s_add_u32 s4, s4, s92
	s_addc_u32 s5, s5, 0
	s_mov_b32 m0, s41
	v_lshl_add_u64 v[212:213], s[4:5], 0, v[130:131]
	ds_read_b128 v[158:161], v172 offset:32768
	ds_read_b128 v[162:165], v172 offset:33792
	ds_read_b128 v[166:169], v172 offset:34816
	ds_read_b128 v[174:177], v172 offset:35840
	ds_read_b128 v[178:181], v172 offset:36864
	ds_read_b128 v[182:185], v172 offset:37888
	ds_read_b128 v[204:207], v172 offset:38912
	ds_read_b128 v[208:211], v172 offset:39936
	global_load_lds_dwordx4 v[212:213], off
	v_lshl_add_u64 v[212:213], s[4:5], 0, v[134:135]
	s_mov_b32 m0, s42
	s_nop 0
	global_load_lds_dwordx4 v[212:213], off
	s_waitcnt lgkmcnt(8)
	s_barrier
	s_waitcnt lgkmcnt(0)
	s_setprio 1
	s_waitcnt lgkmcnt(0)
	v_mfma_f32_16x16x32_bf16 v[126:129], v[142:145], v[158:161], v[126:129]
	v_mfma_f32_16x16x32_bf16 v[122:125], v[150:153], v[158:161], v[122:125]
	v_mfma_f32_16x16x32_bf16 v[110:113], v[142:145], v[166:169], v[110:113]
	v_mfma_f32_16x16x32_bf16 v[106:109], v[150:153], v[166:169], v[106:109]
	v_mfma_f32_16x16x32_bf16 v[94:97], v[142:145], v[178:181], v[94:97]
	v_mfma_f32_16x16x32_bf16 v[90:93], v[150:153], v[178:181], v[90:93]
	v_mfma_f32_16x16x32_bf16 v[78:81], v[142:145], v[204:207], v[78:81]
	v_mfma_f32_16x16x32_bf16 v[74:77], v[150:153], v[204:207], v[74:77]
	v_mfma_f32_16x16x32_bf16 v[126:129], v[146:149], v[162:165], v[126:129]
	v_mfma_f32_16x16x32_bf16 v[122:125], v[154:157], v[162:165], v[122:125]
	v_mfma_f32_16x16x32_bf16 v[110:113], v[146:149], v[174:177], v[110:113]
	v_mfma_f32_16x16x32_bf16 v[106:109], v[154:157], v[174:177], v[106:109]
	v_mfma_f32_16x16x32_bf16 v[94:97], v[146:149], v[182:185], v[94:97]
	v_mfma_f32_16x16x32_bf16 v[90:93], v[154:157], v[182:185], v[90:93]
	v_mfma_f32_16x16x32_bf16 v[78:81], v[146:149], v[208:211], v[78:81]
	v_mfma_f32_16x16x32_bf16 v[74:77], v[154:157], v[208:211], v[74:77]
	s_setprio 0
	s_barrier
	s_add_i32 s4, 0, 0x1c000
	s_add_i32 s5, s10, s34
	v_add_u32_e32 v173, s4, v171
	v_lshl_add_u64 v[228:229], v[228:229], 0, s[6:7]
	s_mov_b32 m0, s5
	ds_read_b128 v[212:215], v173
	ds_read_b128 v[216:219], v173 offset:1024
	ds_read_b128 v[220:223], v173 offset:2048
	ds_read_b128 v[224:227], v173 offset:3072
	global_load_lds_dwordx4 v[228:229], off
	v_lshl_add_u64 v[228:229], v[230:231], 0, s[6:7]
	s_add_i32 m0, s5, 0x2000
	s_nop 0
	global_load_lds_dwordx4 v[228:229], off
	s_barrier
	s_waitcnt lgkmcnt(0)
	s_setprio 1
	s_waitcnt lgkmcnt(0)
	v_mfma_f32_16x16x32_bf16 v[118:121], v[212:215], v[158:161], v[118:121]
	v_mfma_f32_16x16x32_bf16 v[114:117], v[220:223], v[158:161], v[114:117]
	v_mfma_f32_16x16x32_bf16 v[102:105], v[212:215], v[166:169], v[102:105]
	v_mfma_f32_16x16x32_bf16 v[98:101], v[220:223], v[166:169], v[98:101]
	v_mfma_f32_16x16x32_bf16 v[86:89], v[212:215], v[178:181], v[86:89]
	v_mfma_f32_16x16x32_bf16 v[82:85], v[220:223], v[178:181], v[82:85]
	v_mfma_f32_16x16x32_bf16 v[70:73], v[212:215], v[204:207], v[70:73]
	v_mfma_f32_16x16x32_bf16 v[66:69], v[220:223], v[204:207], v[66:69]
	v_mfma_f32_16x16x32_bf16 v[118:121], v[216:219], v[162:165], v[118:121]
	v_mfma_f32_16x16x32_bf16 v[114:117], v[224:227], v[162:165], v[114:117]
	v_mfma_f32_16x16x32_bf16 v[102:105], v[216:219], v[174:177], v[102:105]
	v_mfma_f32_16x16x32_bf16 v[98:101], v[224:227], v[174:177], v[98:101]
	v_mfma_f32_16x16x32_bf16 v[86:89], v[216:219], v[182:185], v[86:89]
	v_mfma_f32_16x16x32_bf16 v[82:85], v[224:227], v[182:185], v[82:85]
	v_mfma_f32_16x16x32_bf16 v[70:73], v[216:219], v[208:211], v[70:73]
	v_mfma_f32_16x16x32_bf16 v[66:69], v[224:227], v[208:211], v[66:69]
	s_setprio 0
	s_mov_b32 m0, s46
	v_lshl_add_u64 v[228:229], v[232:233], 0, s[6:7]
	s_barrier
	ds_read_b128 v[158:161], v172 offset:49152
	ds_read_b128 v[162:165], v172 offset:50176
	ds_read_b128 v[166:169], v172 offset:51200
	ds_read_b128 v[174:177], v172 offset:52224
	ds_read_b128 v[178:181], v172 offset:53248
	ds_read_b128 v[182:185], v172 offset:54272
	ds_read_b128 v[204:207], v172 offset:55296
	ds_read_b128 v[208:211], v172 offset:56320
	global_load_lds_dwordx4 v[228:229], off
	v_lshl_add_u64 v[228:229], v[234:235], 0, s[6:7]
	s_mov_b32 m0, s47
	s_nop 0
	global_load_lds_dwordx4 v[228:229], off
	s_barrier
	s_waitcnt lgkmcnt(0)
	s_setprio 1
	s_waitcnt lgkmcnt(0)
	v_mfma_f32_16x16x32_bf16 v[62:65], v[142:145], v[158:161], v[62:65]
	v_mfma_f32_16x16x32_bf16 v[58:61], v[150:153], v[158:161], v[58:61]
	v_mfma_f32_16x16x32_bf16 v[46:49], v[142:145], v[166:169], v[46:49]
	v_mfma_f32_16x16x32_bf16 v[42:45], v[150:153], v[166:169], v[42:45]
	v_mfma_f32_16x16x32_bf16 v[30:33], v[142:145], v[178:181], v[30:33]
	v_mfma_f32_16x16x32_bf16 v[26:29], v[150:153], v[178:181], v[26:29]
	v_mfma_f32_16x16x32_bf16 v[14:17], v[142:145], v[204:207], v[14:17]
	v_mfma_f32_16x16x32_bf16 v[10:13], v[150:153], v[204:207], v[10:13]
	v_mfma_f32_16x16x32_bf16 v[62:65], v[146:149], v[162:165], v[62:65]
	v_mfma_f32_16x16x32_bf16 v[58:61], v[154:157], v[162:165], v[58:61]
	v_mfma_f32_16x16x32_bf16 v[46:49], v[146:149], v[174:177], v[46:49]
	v_mfma_f32_16x16x32_bf16 v[42:45], v[154:157], v[174:177], v[42:45]
	v_mfma_f32_16x16x32_bf16 v[30:33], v[146:149], v[182:185], v[30:33]
	v_mfma_f32_16x16x32_bf16 v[26:29], v[154:157], v[182:185], v[26:29]
	v_mfma_f32_16x16x32_bf16 v[14:17], v[146:149], v[208:211], v[14:17]
	v_mfma_f32_16x16x32_bf16 v[10:13], v[154:157], v[208:211], v[10:13]
	s_setprio 0
	s_barrier
	s_add_i32 s4, s4, s34
	v_lshl_add_u64 v[142:143], v[236:237], 0, s[6:7]
	s_mov_b32 m0, s4
	s_nop 0
	global_load_lds_dwordx4 v[142:143], off
	v_lshl_add_u64 v[142:143], v[238:239], 0, s[6:7]
	s_add_i32 m0, s4, 0x2000
	s_nop 0
	global_load_lds_dwordx4 v[142:143], off
	s_waitcnt vmcnt(6)
	s_barrier
	s_setprio 1
	v_mfma_f32_16x16x32_bf16 v[54:57], v[212:215], v[158:161], v[54:57]
	v_mfma_f32_16x16x32_bf16 v[50:53], v[220:223], v[158:161], v[50:53]
	v_mfma_f32_16x16x32_bf16 v[38:41], v[212:215], v[166:169], v[38:41]
	v_mfma_f32_16x16x32_bf16 v[34:37], v[220:223], v[166:169], v[34:37]
	v_mfma_f32_16x16x32_bf16 v[22:25], v[212:215], v[178:181], v[22:25]
	v_mfma_f32_16x16x32_bf16 v[18:21], v[220:223], v[178:181], v[18:21]
	v_mfma_f32_16x16x32_bf16 v[6:9], v[212:215], v[204:207], v[6:9]
	v_mfma_f32_16x16x32_bf16 v[2:5], v[220:223], v[204:207], v[2:5]
	v_mfma_f32_16x16x32_bf16 v[54:57], v[216:219], v[162:165], v[54:57]
	v_mfma_f32_16x16x32_bf16 v[50:53], v[224:227], v[162:165], v[50:53]
	v_mfma_f32_16x16x32_bf16 v[38:41], v[216:219], v[174:177], v[38:41]
	v_mfma_f32_16x16x32_bf16 v[34:37], v[224:227], v[174:177], v[34:37]
	v_mfma_f32_16x16x32_bf16 v[22:25], v[216:219], v[182:185], v[22:25]
	v_mfma_f32_16x16x32_bf16 v[18:21], v[224:227], v[182:185], v[18:21]
	v_mfma_f32_16x16x32_bf16 v[6:9], v[216:219], v[208:211], v[6:9]
	v_mfma_f32_16x16x32_bf16 v[2:5], v[224:227], v[208:211], v[2:5]
	s_setprio 0
	s_add_u32 s0, s0, 0x100
	s_addc_u32 s1, s1, 0
	s_add_u32 s12, s12, 0x100
	s_addc_u32 s13, s13, 0
	s_cmp_ge_u32 s27, s43
	s_mov_b32 s4, s27
	s_barrier
	s_cbranch_scc1 .Lkexit_806

.Lkexit_806:
	v_mov_b32_e32 v152, v170
	v_mov_b32_e32 v150, v1
	s_lshl_b32 s5, s69, 8
	s_cmp_lg_u32 s69, s26
	v_lshl_add_u32 v151, v150, 4, v152
	s_mov_b64 s[0:1], -1
	s_cbranch_scc0 .LBB0_809
	s_add_i32 s4, s5, s44
	v_and_or_b32 v142, v151, 63, s4
	v_lshlrev_b32_e32 v162, 1, v151
	v_add_u32_e32 v153, s50, v142
	v_and_b32_e32 v142, 0xffffff80, v162
	v_add_u32_e32 v142, v153, v142
	v_ashrrev_i32_e32 v143, 31, v142
	v_readlane_b32 s0, v242, 3
	v_lshlrev_b64 v[142:143], 6, v[142:143]
	v_readlane_b32 s1, v242, 4
	v_lshl_add_u32 v164, v151, 2, s66
	s_nop 0
	v_lshl_add_u64 v[158:159], s[0:1], 0, v[142:143]
	global_load_dwordx4 v[142:145], v[158:159], off offset:48
	global_load_dwordx4 v[146:149], v[158:159], off offset:32
	global_load_dwordx4 v[154:157], v[158:159], off offset:16
	s_nop 0
	global_load_dwordx4 v[158:161], v[158:159], off
	v_add_u32_e32 v222, 0x80, v162
	v_and_b32_e32 v222, 0xffffff80, v222
	v_add_u32_e32 v222, v153, v222
	v_ashrrev_i32_e32 v223, 31, v222
	v_lshlrev_b64 v[222:223], 6, v[222:223]
	v_lshl_add_u64 v[220:221], s[0:1], 0, v[222:223]
	global_load_dwordx4 v[204:207], v[220:221], off offset:48
	global_load_dwordx4 v[208:211], v[220:221], off offset:32
	global_load_dwordx4 v[212:215], v[220:221], off offset:16
	global_load_dwordx4 v[216:219], v[220:221], off
	s_waitcnt vmcnt(4)
	v_add_f32_e32 v142, v142, v143
	v_add_f32_e32 v146, v146, v147
	v_add_f32_e32 v154, v154, v155
	v_add_f32_e32 v158, v158, v159
	v_add_f32_e32 v158, v160, v158
	v_add_f32_e32 v154, v156, v154
	v_add_f32_e32 v158, v161, v158
	v_add_f32_e32 v154, v157, v154
	v_add_f32_e32 v146, v148, v146
	v_add_f32_e32 v154, v158, v154
	v_add_f32_e32 v146, v149, v146
	v_add_f32_e32 v142, v144, v142
	v_add_f32_e32 v146, v154, v146
	v_add_f32_e32 v142, v145, v142
	v_add_f32_e32 v142, v146, v142
	v_fmamk_f32 v142, v142, 0x3a800000, v188
	v_rsq_f32_e32 v163, v142
	s_mov_b64 s[0:1], 0
	s_waitcnt vmcnt(0)
	v_add_f32_e32 v142, v204, v205
	v_add_f32_e32 v146, v208, v209
	v_add_f32_e32 v154, v212, v213
	v_add_f32_e32 v153, v216, v217
	v_add_f32_e32 v153, v218, v153
	v_add_f32_e32 v154, v214, v154
	v_add_f32_e32 v153, v219, v153
	v_add_f32_e32 v154, v215, v154
	v_add_f32_e32 v146, v210, v146
	v_add_f32_e32 v153, v153, v154
	v_add_f32_e32 v146, v211, v146
	v_add_f32_e32 v142, v206, v142
	v_add_f32_e32 v146, v153, v146
	v_add_f32_e32 v142, v207, v142
	v_add_f32_e32 v142, v146, v142
	v_fmamk_f32 v142, v142, 0x3a800000, v188
	v_rsq_f32_e32 v142, v142
	ds_write2st64_b32 v164, v163, v142 offset1:1
	s_waitcnt lgkmcnt(0)
